# NA prologue: removed the four serialising vmcnt(0) between the per-state Q loads (loads issued together with the LDS-DMA staging)
# speedup vs baseline: 1.0715x; 1.0147x over previous
.LBB0_90:
	s_andn2_b64 vcc, exec, s[2:3]
	s_cbranch_vccnz .LBB0_143
	v_ashrrev_i32_e32 v2, 31, v3
	v_lshrrev_b32_e32 v2, 26, v2
	v_add_u32_e32 v2, v3, v2
	v_ashrrev_i32_e32 v5, 6, v2
	v_bfe_i32 v2, v3, 27, 1
	v_lshlrev_b32_e32 v0, 4, v3
	v_lshrrev_b32_e32 v2, 22, v2
	v_add_u32_e32 v2, v0, v2
	v_and_b32_e32 v2, 0xfffffc00, v2
	v_sub_u32_e32 v2, v0, v2
	v_lshrrev_b32_e32 v4, 4, v2
	v_bitop3_b32 v4, v4, v2, 32 bitop3:0x6c
	v_ashrrev_i32_e32 v2, 31, v2
	v_lshrrev_b32_e32 v2, 26, v2
	v_lshlrev_b32_e32 v6, 3, v5
	v_add_u32_e32 v2, v4, v2
	v_and_b32_e32 v6, -16, v6
	v_ashrrev_i32_e32 v2, 6, v2
	v_add_u32_e32 v8, v2, v6
	v_mul_i32_i24_e32 v2, 64, v2
	v_sub_u32_e32 v2, v4, v2
	v_lshlrev_b32_e32 v6, 5, v5
	v_ashrrev_i16_sdwa v2, v206, sext(v2) dst_sel:DWORD dst_unused:UNUSED_PAD src0_sel:DWORD src1_sel:BYTE_0
	v_and_b32_e32 v10, 32, v6
	v_bfe_i32 v14, v2, 0, 16
	v_lshrrev_b32_e32 v15, 6, v8
	v_and_b32_e32 v2, 63, v8
	v_lshlrev_b32_e32 v20, 2, v2
	v_lshrrev_b32_e32 v2, 4, v2
	v_and_or_b32 v2, v20, 60, v2
	v_mad_u64_u32 v[6:7], s[34:35], v15, 62, v[2:3]
	v_add_lshl_u32 v4, v10, v14, 1
	v_add_u32_e32 v0, 0x2000, v0
	v_lshl_add_u32 v162, v6, 11, v4
	v_lshl_add_u32 v10, v8, 11, v4
	v_ashrrev_i32_e32 v4, 31, v0
	v_lshrrev_b32_e32 v4, 22, v4
	v_add_u32_e32 v4, v0, v4
	v_ashrrev_i32_e32 v16, 10, v4
	v_mul_i32_i24_e32 v4, 0x400, v16
	v_sub_u32_e32 v0, v0, v4
	v_lshrrev_b32_e32 v4, 4, v0
	v_bitop3_b32 v0, v4, v0, 32 bitop3:0x6c
	v_ashrrev_i32_e32 v6, 31, v0
	v_lshrrev_b32_e32 v6, 26, v6
	v_lshlrev_b32_e32 v4, 3, v16
	v_add_u32_e32 v6, v0, v6
	s_mul_i32 s2, s62, 0x10800
	v_and_b32_e32 v4, -16, v4
	v_ashrrev_i32_e32 v7, 6, v6
	s_mul_hi_i32 s1, s62, 0x10800
	s_add_u32 s22, s86, s2
	v_add_u32_e32 v8, v7, v4
	v_lshlrev_b32_e32 v4, 5, v16
	s_addc_u32 s23, s87, s1
	s_mul_i32 s2, s62, 0x5800
	v_and_b32_e32 v11, 32, v4
	v_and_b32_e32 v4, 0xc0, v6
	s_mul_hi_i32 s1, s62, 0x5800
	s_add_u32 s12, s88, s2
	v_sub_u32_e32 v0, v0, v4
	s_addc_u32 s1, s89, s1
	s_mul_i32 s3, s62, 0x1880000
	v_ashrrev_i16_sdwa v0, v206, sext(v0) dst_sel:DWORD dst_unused:UNUSED_PAD src0_sel:DWORD src1_sel:BYTE_0
	s_mul_hi_i32 s2, s62, 0x1880000
	s_add_u32 s3, s8, s3
	v_bfe_i32 v17, v0, 0, 16
	s_addc_u32 s2, s9, s2
	v_lshrrev_b32_e32 v18, 6, v8
	v_and_b32_e32 v4, 63, v8
	v_lshlrev_b32_e32 v19, 2, v4
	v_lshrrev_b32_e32 v4, 4, v4
	v_and_or_b32 v4, v19, 60, v4
	v_add_lshl_u32 v0, v11, v17, 1
	s_add_u32 s90, s3, 0x804000
	v_mad_u64_u32 v[6:7], s[34:35], v18, 62, v[4:5]
	v_lshl_add_u32 v166, v8, 11, v0
	v_bfe_u32 v8, v3, 3, 2
	s_addc_u32 s77, s2, 0
	s_ashr_i32 s13, s64, 6
	v_lshl_add_u32 v164, v6, 11, v0
	v_mul_u32_u24_e32 v0, 0x1600, v8
	s_lshl_b32 s78, s13, 10
	v_lshlrev_b32_e32 v0, 2, v0
	v_lshl_add_u64 v[6:7], s[22:23], 0, v[0:1]
	v_mov_b32_e32 v0, s1
	v_cmp_eq_u32_e32 vcc, 3, v8
	s_add_i32 s85, s78, 0
	s_mul_i32 s1, s50, 0xf8
	s_and_b32 s2, s13, 3
	s_ashr_i32 s3, s64, 8
	v_cndmask_b32_e32 v7, v7, v0, vcc
	v_mov_b32_e32 v0, s12
	s_add_i32 s88, s85, 0x21400
	s_add_i32 s12, s1, 0xffffff1a
	s_cmpk_lt_i32 s50, 0x43
	v_and_b32_e32 v19, 4, v3
	s_cselect_b32 s22, s1, s12
	v_cndmask_b32_e32 v6, v6, v0, vcc
	v_lshl_or_b32 v0, s0, 3, v19
	v_lshlrev_b32_e32 v20, 2, v3
	s_ashr_i32 s23, s22, 31
	v_and_b32_e32 v9, 63, v3
	v_or_b32_e32 v0, s2, v0
	v_and_b32_e32 v176, 12, v20
	s_lshl_b64 s[22:23], s[22:23], 11
	v_readlane_b32 s12, v252, 20
	v_lshl_or_b32 v8, v0, 4, v176
	v_cmp_lt_u32_e32 vcc, 31, v9
	v_mov_b32_e32 v0, 0x2c00
	v_readlane_b32 s13, v252, 21
	s_add_u32 s34, s12, s22
	v_cndmask_b32_e32 v0, 0, v0, vcc
	s_addc_u32 s35, s13, s23
	s_ashr_i32 s1, s0, 31
	v_lshl_add_u64 v[168:169], v[6:7], 0, v[0:1]
	v_ashrrev_i32_e32 v9, 31, v8
	s_lshl_b64 s[22:23], s[0:1], 19
	v_lshl_add_u64 v[6:7], v[8:9], 2, v[168:169]
	s_mov_b32 m0, s88
	s_add_u32 s48, s90, s22
	global_load_lds_dwordx4 v[6:7], off
	s_addc_u32 s49, s77, s23
	s_add_i32 m0, s85, 0x10000
	s_add_i32 s82, s85, 0x2000
	global_load_lds_dwordx4 v10, s[48:49]
	s_add_i32 m0, s85, 0x12000
	s_add_u32 s22, s48, 0x40000
	global_load_lds_dwordx4 v166, s[48:49]
	s_mov_b32 m0, s85
	s_addc_u32 s23, s49, 0
	global_load_lds_dwordx4 v162, s[34:35]
	s_mov_b32 m0, s82
	v_mov_b32_e32 v0, v10
	global_load_lds_dwordx4 v164, s[34:35]
	s_add_i32 m0, s85, 0x14000
	v_mov_b32_e32 v167, v1
	global_load_lds_dwordx4 v10, s[22:23]
	s_add_i32 m0, s85, 0x16000
	v_mov_b32_e32 v163, v1
	global_load_lds_dwordx4 v166, s[22:23]
	s_add_u32 s22, s34, 0x3e000
	s_addc_u32 s23, s35, 0
	s_add_i32 s89, s85, 0x4000
	s_mov_b32 m0, s89
	s_add_i32 s91, s85, 0x6000
	global_load_lds_dwordx4 v162, s[22:23]
	s_mov_b32 m0, s91
	v_mov_b32_e32 v165, v1
	global_load_lds_dwordx4 v164, s[22:23]
	v_lshl_add_u64 v[12:13], s[48:49], 0, v[0:1]
	v_lshl_add_u64 v[10:11], s[48:49], 0, v[166:167]
	v_lshl_add_u64 v[8:9], s[34:35], 0, v[162:163]
	s_cmp_lg_u32 s3, 1
	v_lshl_add_u64 v[6:7], s[34:35], 0, v[164:165]
	s_cbranch_scc1 .LBB0_93
	s_setprio 1
	s_barrier

.LBB0_104:
	s_add_u32 s2, s34, 0xfffc2080
	s_addc_u32 s3, s35, -1
	s_add_i32 s12, 0, 0x10000
	v_add_u32_e32 v110, s12, v179
	ds_read_b128 v[98:101], v110
	ds_read_b128 v[102:105], v110 offset:1024
	ds_read_b128 v[106:109], v110 offset:2048
	ds_read_b128 v[110:113], v110 offset:3072
	s_cmp_eq_u32 s53, 12
	s_cselect_b32 s49, s97, s3
	s_cselect_b32 s48, s96, s2
	s_cselect_b32 s3, s1, s52
	s_cselect_b32 s2, s23, s51
	v_lshl_add_u64 v[174:175], s[34:35], 0, v[170:171]
	s_add_i32 m0, s85, 0xc000
	ds_read_b128 v[114:117], v184
	ds_read_b128 v[118:121], v184 offset:1024
	ds_read_b128 v[122:125], v184 offset:2048
	ds_read_b128 v[126:129], v184 offset:3072
	ds_read_b128 v[186:189], v184 offset:4096
	ds_read_b128 v[190:193], v184 offset:5120
	ds_read_b128 v[194:197], v184 offset:6144
	ds_read_b128 v[198:201], v184 offset:7168
	global_load_lds_dwordx4 v[174:175], off
	v_lshl_add_u64 v[174:175], s[34:35], 0, v[172:173]
	s_add_i32 m0, s85, 0xe000
	s_nop 0
	global_load_lds_dwordx4 v[174:175], off
	s_waitcnt lgkmcnt(8)
	s_barrier
	s_waitcnt lgkmcnt(0)
	s_waitcnt lgkmcnt(0)
	v_mfma_f32_16x16x32_bf16 v[158:161], v[98:101], v[114:117], v[158:161]
	v_mfma_f32_16x16x32_bf16 v[154:157], v[106:109], v[114:117], v[154:157]
	v_mfma_f32_16x16x32_bf16 v[150:153], v[98:101], v[122:125], v[150:153]
	v_mfma_f32_16x16x32_bf16 v[146:149], v[106:109], v[122:125], v[146:149]
	v_mfma_f32_16x16x32_bf16 v[142:145], v[98:101], v[186:189], v[142:145]
	v_mfma_f32_16x16x32_bf16 v[138:141], v[106:109], v[186:189], v[138:141]
	v_mfma_f32_16x16x32_bf16 v[134:137], v[98:101], v[194:197], v[134:137]
	v_mfma_f32_16x16x32_bf16 v[130:133], v[106:109], v[194:197], v[130:133]
	v_mfma_f32_16x16x32_bf16 v[158:161], v[102:105], v[118:121], v[158:161]
	v_mfma_f32_16x16x32_bf16 v[154:157], v[110:113], v[118:121], v[154:157]
	v_mfma_f32_16x16x32_bf16 v[150:153], v[102:105], v[126:129], v[150:153]
	v_mfma_f32_16x16x32_bf16 v[146:149], v[110:113], v[126:129], v[146:149]
	v_mfma_f32_16x16x32_bf16 v[142:145], v[102:105], v[190:193], v[142:145]
	v_mfma_f32_16x16x32_bf16 v[138:141], v[110:113], v[190:193], v[138:141]
	v_mfma_f32_16x16x32_bf16 v[134:137], v[102:105], v[198:201], v[134:137]
	v_mfma_f32_16x16x32_bf16 v[130:133], v[110:113], v[198:201], v[130:133]
	s_barrier
	s_add_i32 s54, 0, 0x14000
	v_add_u32_e32 v174, s54, v179
	s_add_i32 s12, s12, s78
	ds_read_b128 v[226:229], v174
	ds_read_b128 v[230:233], v174 offset:1024
	ds_read_b128 v[234:237], v174 offset:2048
	ds_read_b128 v[242:245], v174 offset:3072
	v_lshl_add_u64 v[174:175], s[2:3], 0, v[0:1]
	s_mov_b32 m0, s12
	v_lshl_add_u64 v[246:247], s[2:3], 0, v[166:167]
	global_load_lds_dwordx4 v[174:175], off
	s_add_i32 m0, s12, 0x2000
	s_nop 0
	global_load_lds_dwordx4 v[246:247], off
	s_barrier
	s_waitcnt lgkmcnt(0)
	s_waitcnt lgkmcnt(0)
	v_mfma_f32_16x16x32_bf16 v[62:65], v[226:229], v[114:117], v[62:65]
	v_mfma_f32_16x16x32_bf16 v[58:61], v[234:237], v[114:117], v[58:61]
	v_mfma_f32_16x16x32_bf16 v[54:57], v[226:229], v[122:125], v[54:57]
	v_mfma_f32_16x16x32_bf16 v[50:53], v[234:237], v[122:125], v[50:53]
	v_mfma_f32_16x16x32_bf16 v[46:49], v[226:229], v[186:189], v[46:49]
	v_mfma_f32_16x16x32_bf16 v[42:45], v[234:237], v[186:189], v[42:45]
	v_mfma_f32_16x16x32_bf16 v[38:41], v[226:229], v[194:197], v[38:41]
	v_mfma_f32_16x16x32_bf16 v[34:37], v[234:237], v[194:197], v[34:37]
	v_mfma_f32_16x16x32_bf16 v[62:65], v[230:233], v[118:121], v[62:65]
	v_mfma_f32_16x16x32_bf16 v[58:61], v[242:245], v[118:121], v[58:61]
	v_mfma_f32_16x16x32_bf16 v[54:57], v[230:233], v[126:129], v[54:57]
	v_mfma_f32_16x16x32_bf16 v[50:53], v[242:245], v[126:129], v[50:53]
	v_mfma_f32_16x16x32_bf16 v[46:49], v[230:233], v[190:193], v[46:49]
	v_mfma_f32_16x16x32_bf16 v[42:45], v[242:245], v[190:193], v[42:45]
	v_mfma_f32_16x16x32_bf16 v[38:41], v[230:233], v[198:201], v[38:41]
	v_mfma_f32_16x16x32_bf16 v[34:37], v[242:245], v[198:201], v[34:37]
	s_mov_b32 m0, s85
	v_lshl_add_u64 v[248:249], s[48:49], 0, v[162:163]
	s_barrier
	ds_read_b128 v[114:117], v184 offset:16384
	ds_read_b128 v[118:121], v184 offset:17408
	ds_read_b128 v[122:125], v184 offset:18432
	ds_read_b128 v[126:129], v184 offset:19456
	ds_read_b128 v[186:189], v184 offset:20480
	ds_read_b128 v[190:193], v184 offset:21504
	ds_read_b128 v[194:197], v184 offset:22528
	ds_read_b128 v[198:201], v184 offset:23552
	global_load_lds_dwordx4 v[248:249], off
	v_lshl_add_u64 v[250:251], s[48:49], 0, v[164:165]
	s_mov_b32 m0, s82
	s_nop 0
	global_load_lds_dwordx4 v[250:251], off
	s_barrier
	s_waitcnt lgkmcnt(0)
	s_waitcnt lgkmcnt(0)
	v_mfma_f32_16x16x32_bf16 v[94:97], v[98:101], v[114:117], v[94:97]
	v_mfma_f32_16x16x32_bf16 v[90:93], v[106:109], v[114:117], v[90:93]
	v_mfma_f32_16x16x32_bf16 v[86:89], v[98:101], v[122:125], v[86:89]
	v_mfma_f32_16x16x32_bf16 v[82:85], v[106:109], v[122:125], v[82:85]
	v_mfma_f32_16x16x32_bf16 v[78:81], v[98:101], v[186:189], v[78:81]
	v_mfma_f32_16x16x32_bf16 v[74:77], v[106:109], v[186:189], v[74:77]
	v_mfma_f32_16x16x32_bf16 v[70:73], v[98:101], v[194:197], v[70:73]
	v_mfma_f32_16x16x32_bf16 v[66:69], v[106:109], v[194:197], v[66:69]
	v_mfma_f32_16x16x32_bf16 v[94:97], v[102:105], v[118:121], v[94:97]
	v_mfma_f32_16x16x32_bf16 v[90:93], v[110:113], v[118:121], v[90:93]
	v_mfma_f32_16x16x32_bf16 v[86:89], v[102:105], v[126:129], v[86:89]
	v_mfma_f32_16x16x32_bf16 v[82:85], v[110:113], v[126:129], v[82:85]
	v_mfma_f32_16x16x32_bf16 v[78:81], v[102:105], v[190:193], v[78:81]
	v_mfma_f32_16x16x32_bf16 v[74:77], v[110:113], v[190:193], v[74:77]
	v_mfma_f32_16x16x32_bf16 v[70:73], v[102:105], v[198:201], v[70:73]
	v_mfma_f32_16x16x32_bf16 v[66:69], v[110:113], v[198:201], v[66:69]
	s_barrier
	s_add_u32 s12, s2, 0x40000
	s_addc_u32 s13, s3, 0
	s_add_i32 s54, s54, s78
	v_lshl_add_u64 v[98:99], s[12:13], 0, v[0:1]
	s_mov_b32 m0, s54
	s_nop 0
	global_load_lds_dwordx4 v[98:99], off
	v_lshl_add_u64 v[98:99], s[12:13], 0, v[166:167]
	s_add_i32 m0, s54, 0x2000
	s_nop 0
	global_load_lds_dwordx4 v[98:99], off
	s_waitcnt vmcnt(6)
	s_barrier
	v_mfma_f32_16x16x32_bf16 v[30:33], v[226:229], v[114:117], v[30:33]
	v_mfma_f32_16x16x32_bf16 v[26:29], v[234:237], v[114:117], v[26:29]
	v_mfma_f32_16x16x32_bf16 v[22:25], v[226:229], v[122:125], v[22:25]
	v_mfma_f32_16x16x32_bf16 v[18:21], v[234:237], v[122:125], v[18:21]
	v_mfma_f32_16x16x32_bf16 v[14:17], v[226:229], v[186:189], v[14:17]
	v_mfma_f32_16x16x32_bf16 v[10:13], v[234:237], v[186:189], v[10:13]
	v_mfma_f32_16x16x32_bf16 v[6:9], v[226:229], v[194:197], v[6:9]
	v_mfma_f32_16x16x32_bf16 v[2:5], v[234:237], v[194:197], v[2:5]
	v_mfma_f32_16x16x32_bf16 v[30:33], v[230:233], v[118:121], v[30:33]
	v_mfma_f32_16x16x32_bf16 v[26:29], v[242:245], v[118:121], v[26:29]
	v_mfma_f32_16x16x32_bf16 v[22:25], v[230:233], v[126:129], v[22:25]
	v_mfma_f32_16x16x32_bf16 v[18:21], v[242:245], v[126:129], v[18:21]
	v_mfma_f32_16x16x32_bf16 v[14:17], v[230:233], v[190:193], v[14:17]
	v_mfma_f32_16x16x32_bf16 v[10:13], v[242:245], v[190:193], v[10:13]
	v_mfma_f32_16x16x32_bf16 v[6:9], v[230:233], v[198:201], v[6:9]
	v_mfma_f32_16x16x32_bf16 v[2:5], v[242:245], v[198:201], v[2:5]
	s_add_i32 s54, 0, 0x18000
	v_add_u32_e32 v110, s54, v179
	s_barrier
	ds_read_b128 v[98:101], v110
	ds_read_b128 v[102:105], v110 offset:1024
	ds_read_b128 v[106:109], v110 offset:2048
	ds_read_b128 v[110:113], v110 offset:3072
	s_add_u32 s12, s48, 0x3e000
	s_addc_u32 s13, s49, 0
	s_mov_b32 m0, s89
	v_lshl_add_u64 v[226:227], s[12:13], 0, v[162:163]
	ds_read_b128 v[114:117], v184 offset:32768
	ds_read_b128 v[118:121], v184 offset:33792
	ds_read_b128 v[122:125], v184 offset:34816
	ds_read_b128 v[126:129], v184 offset:35840
	ds_read_b128 v[186:189], v184 offset:36864
	ds_read_b128 v[190:193], v184 offset:37888
	ds_read_b128 v[194:197], v184 offset:38912
	ds_read_b128 v[198:201], v184 offset:39936
	global_load_lds_dwordx4 v[226:227], off
	v_lshl_add_u64 v[226:227], s[12:13], 0, v[164:165]
	s_mov_b32 m0, s91
	s_nop 0
	global_load_lds_dwordx4 v[226:227], off
	s_waitcnt lgkmcnt(8)
	s_barrier
	s_waitcnt lgkmcnt(0)
	s_waitcnt lgkmcnt(0)
	v_mfma_f32_16x16x32_bf16 v[158:161], v[98:101], v[114:117], v[158:161]
	v_mfma_f32_16x16x32_bf16 v[154:157], v[106:109], v[114:117], v[154:157]
	v_mfma_f32_16x16x32_bf16 v[150:153], v[98:101], v[122:125], v[150:153]
	v_mfma_f32_16x16x32_bf16 v[146:149], v[106:109], v[122:125], v[146:149]
	v_mfma_f32_16x16x32_bf16 v[142:145], v[98:101], v[186:189], v[142:145]
	v_mfma_f32_16x16x32_bf16 v[138:141], v[106:109], v[186:189], v[138:141]
	v_mfma_f32_16x16x32_bf16 v[134:137], v[98:101], v[194:197], v[134:137]
	v_mfma_f32_16x16x32_bf16 v[130:133], v[106:109], v[194:197], v[130:133]
	v_mfma_f32_16x16x32_bf16 v[158:161], v[102:105], v[118:121], v[158:161]
	v_mfma_f32_16x16x32_bf16 v[154:157], v[110:113], v[118:121], v[154:157]
	v_mfma_f32_16x16x32_bf16 v[150:153], v[102:105], v[126:129], v[150:153]
	v_mfma_f32_16x16x32_bf16 v[146:149], v[110:113], v[126:129], v[146:149]
	v_mfma_f32_16x16x32_bf16 v[142:145], v[102:105], v[190:193], v[142:145]
	v_mfma_f32_16x16x32_bf16 v[138:141], v[110:113], v[190:193], v[138:141]
	v_mfma_f32_16x16x32_bf16 v[134:137], v[102:105], v[198:201], v[134:137]
	v_mfma_f32_16x16x32_bf16 v[130:133], v[110:113], v[198:201], v[130:133]
	s_barrier
	s_add_i32 s12, 0, 0x1c000
	s_add_i32 s13, s54, s78
	v_add_u32_e32 v242, s12, v179
	v_lshl_add_u64 v[174:175], v[174:175], 0, s[20:21]
	s_mov_b32 m0, s13
	ds_read_b128 v[226:229], v242
	ds_read_b128 v[230:233], v242 offset:1024
	ds_read_b128 v[234:237], v242 offset:2048
	ds_read_b128 v[242:245], v242 offset:3072
	global_load_lds_dwordx4 v[174:175], off
	v_lshl_add_u64 v[174:175], v[246:247], 0, s[20:21]
	s_add_i32 m0, s13, 0x2000
	s_nop 0
	global_load_lds_dwordx4 v[174:175], off
	s_barrier
	s_waitcnt lgkmcnt(0)
	s_waitcnt lgkmcnt(0)
	v_mfma_f32_16x16x32_bf16 v[62:65], v[226:229], v[114:117], v[62:65]
	v_mfma_f32_16x16x32_bf16 v[58:61], v[234:237], v[114:117], v[58:61]
	v_mfma_f32_16x16x32_bf16 v[54:57], v[226:229], v[122:125], v[54:57]
	v_mfma_f32_16x16x32_bf16 v[50:53], v[234:237], v[122:125], v[50:53]
	v_mfma_f32_16x16x32_bf16 v[46:49], v[226:229], v[186:189], v[46:49]
	v_mfma_f32_16x16x32_bf16 v[42:45], v[234:237], v[186:189], v[42:45]
	v_mfma_f32_16x16x32_bf16 v[38:41], v[226:229], v[194:197], v[38:41]
	v_mfma_f32_16x16x32_bf16 v[34:37], v[234:237], v[194:197], v[34:37]
	v_mfma_f32_16x16x32_bf16 v[62:65], v[230:233], v[118:121], v[62:65]
	v_mfma_f32_16x16x32_bf16 v[58:61], v[242:245], v[118:121], v[58:61]
	v_mfma_f32_16x16x32_bf16 v[54:57], v[230:233], v[126:129], v[54:57]
	v_mfma_f32_16x16x32_bf16 v[50:53], v[242:245], v[126:129], v[50:53]
	v_mfma_f32_16x16x32_bf16 v[46:49], v[230:233], v[190:193], v[46:49]
	v_mfma_f32_16x16x32_bf16 v[42:45], v[242:245], v[190:193], v[42:45]
	v_mfma_f32_16x16x32_bf16 v[38:41], v[230:233], v[198:201], v[38:41]
	v_mfma_f32_16x16x32_bf16 v[34:37], v[242:245], v[198:201], v[34:37]
	s_mov_b32 m0, s79
	v_lshl_add_u64 v[174:175], v[248:249], 0, s[20:21]
	s_barrier
	ds_read_b128 v[114:117], v184 offset:49152
	ds_read_b128 v[118:121], v184 offset:50176
	ds_read_b128 v[122:125], v184 offset:51200
	ds_read_b128 v[126:129], v184 offset:52224
	ds_read_b128 v[186:189], v184 offset:53248
	ds_read_b128 v[190:193], v184 offset:54272
	ds_read_b128 v[194:197], v184 offset:55296
	ds_read_b128 v[198:201], v184 offset:56320
	global_load_lds_dwordx4 v[174:175], off
	v_lshl_add_u64 v[174:175], v[250:251], 0, s[20:21]
	s_mov_b32 m0, s87
	s_nop 0
	global_load_lds_dwordx4 v[174:175], off
	s_barrier
	s_waitcnt lgkmcnt(0)
	s_waitcnt lgkmcnt(0)
	v_mfma_f32_16x16x32_bf16 v[94:97], v[98:101], v[114:117], v[94:97]
	v_mfma_f32_16x16x32_bf16 v[90:93], v[106:109], v[114:117], v[90:93]
	v_mfma_f32_16x16x32_bf16 v[86:89], v[98:101], v[122:125], v[86:89]
	v_mfma_f32_16x16x32_bf16 v[82:85], v[106:109], v[122:125], v[82:85]
	v_mfma_f32_16x16x32_bf16 v[78:81], v[98:101], v[186:189], v[78:81]
	v_mfma_f32_16x16x32_bf16 v[74:77], v[106:109], v[186:189], v[74:77]
	v_mfma_f32_16x16x32_bf16 v[70:73], v[98:101], v[194:197], v[70:73]
	v_mfma_f32_16x16x32_bf16 v[66:69], v[106:109], v[194:197], v[66:69]
	v_mfma_f32_16x16x32_bf16 v[94:97], v[102:105], v[118:121], v[94:97]
	v_mfma_f32_16x16x32_bf16 v[90:93], v[110:113], v[118:121], v[90:93]
	v_mfma_f32_16x16x32_bf16 v[86:89], v[102:105], v[126:129], v[86:89]
	v_mfma_f32_16x16x32_bf16 v[82:85], v[110:113], v[126:129], v[82:85]
	v_mfma_f32_16x16x32_bf16 v[78:81], v[102:105], v[190:193], v[78:81]
	v_mfma_f32_16x16x32_bf16 v[74:77], v[110:113], v[190:193], v[74:77]
	v_mfma_f32_16x16x32_bf16 v[70:73], v[102:105], v[198:201], v[70:73]
	v_mfma_f32_16x16x32_bf16 v[66:69], v[110:113], v[198:201], v[66:69]
	s_barrier
	s_add_u32 s2, s2, 0x40080
	s_addc_u32 s3, s3, 0
	s_add_i32 s12, s12, s78
	v_lshl_add_u64 v[98:99], s[2:3], 0, v[0:1]
	s_mov_b32 m0, s12
	s_nop 0
	global_load_lds_dwordx4 v[98:99], off
	v_lshl_add_u64 v[98:99], s[2:3], 0, v[166:167]
	s_add_i32 m0, s12, 0x2000
	s_nop 0
	global_load_lds_dwordx4 v[98:99], off
	s_waitcnt vmcnt(6)
	s_barrier
	v_mfma_f32_16x16x32_bf16 v[30:33], v[226:229], v[114:117], v[30:33]
	v_mfma_f32_16x16x32_bf16 v[26:29], v[234:237], v[114:117], v[26:29]
	v_mfma_f32_16x16x32_bf16 v[22:25], v[226:229], v[122:125], v[22:25]
	v_mfma_f32_16x16x32_bf16 v[18:21], v[234:237], v[122:125], v[18:21]
	v_mfma_f32_16x16x32_bf16 v[14:17], v[226:229], v[186:189], v[14:17]
	v_mfma_f32_16x16x32_bf16 v[10:13], v[234:237], v[186:189], v[10:13]
	v_mfma_f32_16x16x32_bf16 v[6:9], v[226:229], v[194:197], v[6:9]
	v_mfma_f32_16x16x32_bf16 v[2:5], v[234:237], v[194:197], v[2:5]
	v_mfma_f32_16x16x32_bf16 v[30:33], v[230:233], v[118:121], v[30:33]
	v_mfma_f32_16x16x32_bf16 v[26:29], v[242:245], v[118:121], v[26:29]
	v_mfma_f32_16x16x32_bf16 v[22:25], v[230:233], v[126:129], v[22:25]
	v_mfma_f32_16x16x32_bf16 v[18:21], v[242:245], v[126:129], v[18:21]
	v_mfma_f32_16x16x32_bf16 v[14:17], v[230:233], v[190:193], v[14:17]
	v_mfma_f32_16x16x32_bf16 v[10:13], v[242:245], v[190:193], v[10:13]
	v_mfma_f32_16x16x32_bf16 v[6:9], v[230:233], v[198:201], v[6:9]
	v_mfma_f32_16x16x32_bf16 v[2:5], v[242:245], v[198:201], v[2:5]
	s_add_i32 s53, s53, 2
	s_add_u32 s34, s34, 0x100
	s_addc_u32 s35, s35, 0
	s_add_u32 s51, s51, 0x100
	s_addc_u32 s52, s52, 0
	s_cmp_gt_u32 s53, 13
	s_barrier
	s_cbranch_scc0 .LBB0_104
	s_add_i32 s1, s50, 0xffffffbd
	s_cmpk_gt_i32 s50, 0x42
	s_cselect_b32 s1, s1, s50
	s_mul_i32 s23, s1, 0xf8
	s_cselect_b32 s2, 0x4000, 0
	s_cselect_b32 s3, 0x100, s37
	s_add_i32 s23, s23, s84
	v_add_u32_e32 v188, s88, v178
	ds_read_b128 v[126:129], v188
	ds_read_b128 v[122:125], v188 offset:128
	ds_read_b128 v[114:117], v188 offset:256
	ds_read_b128 v[118:121], v188 offset:384
	ds_read_b128 v[110:113], v188 offset:512
	ds_read_b128 v[106:109], v188 offset:640
	ds_read_b128 v[98:101], v188 offset:768
	ds_read_b128 v[102:105], v188 offset:896
	v_readlane_b32 s12, v252, 28
	v_readlane_b32 s13, v252, 29
	v_lshl_or_b32 v174, s0, 7, v180
	v_lshl_add_u32 v186, v177, 2, s23
	v_add_u32_e32 v187, s2, v186
	v_mul_u32_u24_e32 v187, 0x1600, v187
	v_lshl_add_u32 v187, v174, 1, v187
	s_waitcnt lgkmcnt(0)
	v_fma_f32 v190, v158, v122, v118
	v_fma_f32 v191, v159, v123, v119
	v_fma_f32 v192, v160, v124, v120
	v_fma_f32 v193, v161, v125, v121
	v_fma_f32 v194, v154, v106, v102
	v_fma_f32 v195, v155, v107, v103
	v_fma_f32 v196, v156, v108, v104
	v_fma_f32 v197, v157, v109, v105
	v_add_u32_e32 v228, 0, v186
	v_fmac_f32_dpp v190, v134, v126 row_ror:1 row_mask:0xf bank_mask:0xf
	v_fmac_f32_dpp v191, v135, v127 row_ror:1 row_mask:0xf bank_mask:0xf
	v_fmac_f32_dpp v192, v136, v128 row_ror:1 row_mask:0xf bank_mask:0xf
	v_fmac_f32_dpp v193, v137, v129 row_ror:1 row_mask:0xf bank_mask:0xf
	v_fmac_f32_dpp v194, v130, v110 row_ror:1 row_mask:0xf bank_mask:0xf
	v_fmac_f32_dpp v195, v131, v111 row_ror:1 row_mask:0xf bank_mask:0xf
	v_fmac_f32_dpp v196, v132, v112 row_ror:1 row_mask:0xf bank_mask:0xf
	v_fmac_f32_dpp v197, v133, v113 row_ror:1 row_mask:0xf bank_mask:0xf
	v_fmac_f32_e32 v190, v150, v114
	v_fmac_f32_e32 v191, v151, v115
	v_fmac_f32_e32 v192, v152, v116
	v_fmac_f32_e32 v193, v153, v117
	v_fmac_f32_e32 v194, v146, v98
	v_fmac_f32_e32 v195, v147, v99
	v_fmac_f32_e32 v196, v148, v100
	v_fmac_f32_e32 v197, v149, v101
	v_cmp_gt_i32_e32 vcc, s3, v228
	v_mul_f32_e32 v198, 0xbfb8aa3b, v190
	v_mul_f32_e32 v199, 0xbfb8aa3b, v191
	v_mul_f32_e32 v200, 0xbfb8aa3b, v192
	v_mul_f32_e32 v201, 0xbfb8aa3b, v193
	v_exp_f32_e32 v198, v198
	v_exp_f32_e32 v199, v199
	v_exp_f32_e32 v200, v200
	v_exp_f32_e32 v201, v201
	v_add_f32_e32 v198, 1.0, v198
	v_add_f32_e32 v199, 1.0, v199
	v_add_f32_e32 v200, 1.0, v200
	v_add_f32_e32 v201, 1.0, v201
	v_rcp_f32_e32 v198, v198
	v_rcp_f32_e32 v199, v199
	v_rcp_f32_e32 v200, v200
	v_rcp_f32_e32 v201, v201
	v_mul_f32_e32 v190, v190, v198
	v_mul_f32_e32 v191, v191, v199
	v_mul_f32_e32 v192, v192, v200
	v_mul_f32_e32 v193, v193, v201
	v_mul_f32_e32 v190, v190, v194
	v_mul_f32_e32 v191, v191, v195
	v_mul_f32_e32 v192, v192, v196
	v_mul_f32_e32 v193, v193, v197
	v_cvt_pk_bf16_f32 v226, v190, v191
	v_cvt_pk_bf16_f32 v227, v192, v193
	s_and_b64 vcc, vcc, s[42:43]
	s_and_saveexec_b64 s[0:1], vcc
	global_store_dwordx2 v187, v[226:227], s[12:13]
	s_mov_b64 exec, s[0:1]
	v_fma_f32 v190, v150, v122, v118
	v_fma_f32 v191, v151, v123, v119
	v_fma_f32 v192, v152, v124, v120
	v_fma_f32 v193, v153, v125, v121
	v_fma_f32 v194, v146, v106, v102
	v_fma_f32 v195, v147, v107, v103
	v_fma_f32 v196, v148, v108, v104
	v_fma_f32 v197, v149, v109, v105
	v_add_u32_e32 v228, 1, v186
	v_add_u32_e32 v229, 0x1600, v187
	v_fmac_f32_e32 v190, v158, v126
	v_fmac_f32_e32 v191, v159, v127
	v_fmac_f32_e32 v192, v160, v128
	v_fmac_f32_e32 v193, v161, v129
	v_fmac_f32_e32 v194, v154, v110
	v_fmac_f32_e32 v195, v155, v111
	v_fmac_f32_e32 v196, v156, v112
	v_fmac_f32_e32 v197, v157, v113
	v_fmac_f32_e32 v190, v142, v114
	v_fmac_f32_e32 v191, v143, v115
	v_fmac_f32_e32 v192, v144, v116
	v_fmac_f32_e32 v193, v145, v117
	v_fmac_f32_e32 v194, v138, v98
	v_fmac_f32_e32 v195, v139, v99
	v_fmac_f32_e32 v196, v140, v100
	v_fmac_f32_e32 v197, v141, v101
	v_cmp_gt_i32_e32 vcc, s3, v228
	v_mul_f32_e32 v198, 0xbfb8aa3b, v190
	v_mul_f32_e32 v199, 0xbfb8aa3b, v191
	v_mul_f32_e32 v200, 0xbfb8aa3b, v192
	v_mul_f32_e32 v201, 0xbfb8aa3b, v193
	v_exp_f32_e32 v198, v198
	v_exp_f32_e32 v199, v199
	v_exp_f32_e32 v200, v200
	v_exp_f32_e32 v201, v201
	v_add_f32_e32 v198, 1.0, v198
	v_add_f32_e32 v199, 1.0, v199
	v_add_f32_e32 v200, 1.0, v200
	v_add_f32_e32 v201, 1.0, v201
	v_rcp_f32_e32 v198, v198
	v_rcp_f32_e32 v199, v199
	v_rcp_f32_e32 v200, v200
	v_rcp_f32_e32 v201, v201
	v_mul_f32_e32 v190, v190, v198
	v_mul_f32_e32 v191, v191, v199
	v_mul_f32_e32 v192, v192, v200
	v_mul_f32_e32 v193, v193, v201
	v_mul_f32_e32 v190, v190, v194
	v_mul_f32_e32 v191, v191, v195
	v_mul_f32_e32 v192, v192, v196
	v_mul_f32_e32 v193, v193, v197
	v_cvt_pk_bf16_f32 v226, v190, v191
	v_cvt_pk_bf16_f32 v227, v192, v193
	s_and_saveexec_b64 s[0:1], vcc
	global_store_dwordx2 v229, v[226:227], s[12:13]
	s_mov_b64 exec, s[0:1]
	v_fma_f32 v190, v142, v122, v118
	v_fma_f32 v191, v143, v123, v119
	v_fma_f32 v192, v144, v124, v120
	v_fma_f32 v193, v145, v125, v121
	v_fma_f32 v194, v138, v106, v102
	v_fma_f32 v195, v139, v107, v103
	v_fma_f32 v196, v140, v108, v104
	v_fma_f32 v197, v141, v109, v105
	v_add_u32_e32 v228, 2, v186
	v_add_u32_e32 v229, 0x2c00, v187
	v_fmac_f32_e32 v190, v150, v126
	v_fmac_f32_e32 v191, v151, v127
	v_fmac_f32_e32 v192, v152, v128
	v_fmac_f32_e32 v193, v153, v129
	v_fmac_f32_e32 v194, v146, v110
	v_fmac_f32_e32 v195, v147, v111
	v_fmac_f32_e32 v196, v148, v112
	v_fmac_f32_e32 v197, v149, v113
	v_fmac_f32_e32 v190, v134, v114
	v_fmac_f32_e32 v191, v135, v115
	v_fmac_f32_e32 v192, v136, v116
	v_fmac_f32_e32 v193, v137, v117
	v_fmac_f32_e32 v194, v130, v98
	v_fmac_f32_e32 v195, v131, v99
	v_fmac_f32_e32 v196, v132, v100
	v_fmac_f32_e32 v197, v133, v101
	v_cmp_gt_i32_e32 vcc, s3, v228
	v_mul_f32_e32 v198, 0xbfb8aa3b, v190
	v_mul_f32_e32 v199, 0xbfb8aa3b, v191
	v_mul_f32_e32 v200, 0xbfb8aa3b, v192
	v_mul_f32_e32 v201, 0xbfb8aa3b, v193
	v_exp_f32_e32 v198, v198
	v_exp_f32_e32 v199, v199
	v_exp_f32_e32 v200, v200
	v_exp_f32_e32 v201, v201
	v_add_f32_e32 v198, 1.0, v198
	v_add_f32_e32 v199, 1.0, v199
	v_add_f32_e32 v200, 1.0, v200
	v_add_f32_e32 v201, 1.0, v201
	v_rcp_f32_e32 v198, v198
	v_rcp_f32_e32 v199, v199
	v_rcp_f32_e32 v200, v200
	v_rcp_f32_e32 v201, v201
	v_mul_f32_e32 v190, v190, v198
	v_mul_f32_e32 v191, v191, v199
	v_mul_f32_e32 v192, v192, v200
	v_mul_f32_e32 v193, v193, v201
	v_mul_f32_e32 v190, v190, v194
	v_mul_f32_e32 v191, v191, v195
	v_mul_f32_e32 v192, v192, v196
	v_mul_f32_e32 v193, v193, v197
	v_cvt_pk_bf16_f32 v226, v190, v191
	v_cvt_pk_bf16_f32 v227, v192, v193
	s_and_saveexec_b64 s[0:1], vcc
	global_store_dwordx2 v229, v[226:227], s[12:13]
	s_mov_b64 exec, s[0:1]
	v_fma_f32 v190, v134, v122, v118
	v_fma_f32 v191, v135, v123, v119
	v_fma_f32 v192, v136, v124, v120
	v_fma_f32 v193, v137, v125, v121
	v_fma_f32 v194, v130, v106, v102
	v_fma_f32 v195, v131, v107, v103
	v_fma_f32 v196, v132, v108, v104
	v_fma_f32 v197, v133, v109, v105
	v_add_u32_e32 v228, 3, v186
	v_add_u32_e32 v229, 0x4200, v187
	v_fmac_f32_e32 v190, v142, v126
	v_fmac_f32_e32 v191, v143, v127
	v_fmac_f32_e32 v192, v144, v128
	v_fmac_f32_e32 v193, v145, v129
	v_fmac_f32_e32 v194, v138, v110
	v_fmac_f32_e32 v195, v139, v111
	v_fmac_f32_e32 v196, v140, v112
	v_fmac_f32_e32 v197, v141, v113
	v_fmac_f32_dpp v190, v158, v114 row_ror:15 row_mask:0xf bank_mask:0xf
	v_fmac_f32_dpp v191, v159, v115 row_ror:15 row_mask:0xf bank_mask:0xf
	v_fmac_f32_dpp v192, v160, v116 row_ror:15 row_mask:0xf bank_mask:0xf
	v_fmac_f32_dpp v193, v161, v117 row_ror:15 row_mask:0xf bank_mask:0xf
	v_fmac_f32_dpp v194, v154, v98 row_ror:15 row_mask:0xf bank_mask:0xf
	v_fmac_f32_dpp v195, v155, v99 row_ror:15 row_mask:0xf bank_mask:0xf
	v_fmac_f32_dpp v196, v156, v100 row_ror:15 row_mask:0xf bank_mask:0xf
	v_fmac_f32_dpp v197, v157, v101 row_ror:15 row_mask:0xf bank_mask:0xf
	v_cmp_gt_i32_e32 vcc, s3, v228
	v_mul_f32_e32 v198, 0xbfb8aa3b, v190
	v_mul_f32_e32 v199, 0xbfb8aa3b, v191
	v_mul_f32_e32 v200, 0xbfb8aa3b, v192
	v_mul_f32_e32 v201, 0xbfb8aa3b, v193
	v_exp_f32_e32 v198, v198
	v_exp_f32_e32 v199, v199
	v_exp_f32_e32 v200, v200
	v_exp_f32_e32 v201, v201
	v_add_f32_e32 v198, 1.0, v198
	v_add_f32_e32 v199, 1.0, v199
	v_add_f32_e32 v200, 1.0, v200
	v_add_f32_e32 v201, 1.0, v201
	v_rcp_f32_e32 v198, v198
	v_rcp_f32_e32 v199, v199
	v_rcp_f32_e32 v200, v200
	v_rcp_f32_e32 v201, v201
	v_mul_f32_e32 v190, v190, v198
	v_mul_f32_e32 v191, v191, v199
	v_mul_f32_e32 v192, v192, v200
	v_mul_f32_e32 v193, v193, v201
	v_mul_f32_e32 v190, v190, v194
	v_mul_f32_e32 v191, v191, v195
	v_mul_f32_e32 v192, v192, v196
	v_mul_f32_e32 v193, v193, v197
	v_cvt_pk_bf16_f32 v226, v190, v191
	v_cvt_pk_bf16_f32 v227, v192, v193
	s_and_b64 vcc, vcc, s[44:45]
	s_and_saveexec_b64 s[0:1], vcc
	global_store_dwordx2 v229, v[226:227], s[12:13]
	s_mov_b64 exec, s[0:1]
	ds_read_b128 v[130:133], v188 offset:64
	ds_read_b128 v[134:137], v188 offset:192
	ds_read_b128 v[138:141], v188 offset:320
	ds_read_b128 v[142:145], v188 offset:448
	ds_read_b128 v[146:149], v188 offset:576
	ds_read_b128 v[150:153], v188 offset:704
	ds_read_b128 v[154:157], v188 offset:832
	ds_read_b128 v[158:161], v188 offset:960
	v_fma_f32 v190, v94, v122, v118
	v_fma_f32 v191, v95, v123, v119
	v_fma_f32 v192, v96, v124, v120
	v_fma_f32 v193, v97, v125, v121
	v_fma_f32 v194, v90, v106, v102
	v_fma_f32 v195, v91, v107, v103
	v_fma_f32 v196, v92, v108, v104
	v_fma_f32 v197, v93, v109, v105
	v_add_u32_e32 v228, 0x7c, v186
	v_add_u32_e32 v229, 0xaa800, v187
	v_fmac_f32_dpp v190, v70, v126 row_ror:1 row_mask:0xf bank_mask:0xf
	v_fmac_f32_dpp v191, v71, v127 row_ror:1 row_mask:0xf bank_mask:0xf
	v_fmac_f32_dpp v192, v72, v128 row_ror:1 row_mask:0xf bank_mask:0xf
	v_fmac_f32_dpp v193, v73, v129 row_ror:1 row_mask:0xf bank_mask:0xf
	v_fmac_f32_dpp v194, v66, v110 row_ror:1 row_mask:0xf bank_mask:0xf
	v_fmac_f32_dpp v195, v67, v111 row_ror:1 row_mask:0xf bank_mask:0xf
	v_fmac_f32_dpp v196, v68, v112 row_ror:1 row_mask:0xf bank_mask:0xf
	v_fmac_f32_dpp v197, v69, v113 row_ror:1 row_mask:0xf bank_mask:0xf
	v_fmac_f32_e32 v190, v86, v114
	v_fmac_f32_e32 v191, v87, v115
	v_fmac_f32_e32 v192, v88, v116
	v_fmac_f32_e32 v193, v89, v117
	v_fmac_f32_e32 v194, v82, v98
	v_fmac_f32_e32 v195, v83, v99
	v_fmac_f32_e32 v196, v84, v100
	v_fmac_f32_e32 v197, v85, v101
	v_cmp_gt_i32_e32 vcc, s3, v228
	v_mul_f32_e32 v198, 0xbfb8aa3b, v190
	v_mul_f32_e32 v199, 0xbfb8aa3b, v191
	v_mul_f32_e32 v200, 0xbfb8aa3b, v192
	v_mul_f32_e32 v201, 0xbfb8aa3b, v193
	v_exp_f32_e32 v198, v198
	v_exp_f32_e32 v199, v199
	v_exp_f32_e32 v200, v200
	v_exp_f32_e32 v201, v201
	v_add_f32_e32 v198, 1.0, v198
	v_add_f32_e32 v199, 1.0, v199
	v_add_f32_e32 v200, 1.0, v200
	v_add_f32_e32 v201, 1.0, v201
	v_rcp_f32_e32 v198, v198
	v_rcp_f32_e32 v199, v199
	v_rcp_f32_e32 v200, v200
	v_rcp_f32_e32 v201, v201
	v_mul_f32_e32 v190, v190, v198
	v_mul_f32_e32 v191, v191, v199
	v_mul_f32_e32 v192, v192, v200
	v_mul_f32_e32 v193, v193, v201
	v_mul_f32_e32 v190, v190, v194
	v_mul_f32_e32 v191, v191, v195
	v_mul_f32_e32 v192, v192, v196
	v_mul_f32_e32 v193, v193, v197
	v_cvt_pk_bf16_f32 v226, v190, v191
	v_cvt_pk_bf16_f32 v227, v192, v193
	s_and_b64 vcc, vcc, s[42:43]
	s_and_saveexec_b64 s[0:1], vcc
	global_store_dwordx2 v229, v[226:227], s[12:13]
	s_mov_b64 exec, s[0:1]
	v_fma_f32 v190, v86, v122, v118
	v_fma_f32 v191, v87, v123, v119
	v_fma_f32 v192, v88, v124, v120
	v_fma_f32 v193, v89, v125, v121
	v_fma_f32 v194, v82, v106, v102
	v_fma_f32 v195, v83, v107, v103
	v_fma_f32 v196, v84, v108, v104
	v_fma_f32 v197, v85, v109, v105
	v_add_u32_e32 v228, 0x7d, v186
	v_add_u32_e32 v229, 0xabe00, v187
	v_fmac_f32_e32 v190, v94, v126
	v_fmac_f32_e32 v191, v95, v127
	v_fmac_f32_e32 v192, v96, v128
	v_fmac_f32_e32 v193, v97, v129
	v_fmac_f32_e32 v194, v90, v110
	v_fmac_f32_e32 v195, v91, v111
	v_fmac_f32_e32 v196, v92, v112
	v_fmac_f32_e32 v197, v93, v113
	v_fmac_f32_e32 v190, v78, v114
	v_fmac_f32_e32 v191, v79, v115
	v_fmac_f32_e32 v192, v80, v116
	v_fmac_f32_e32 v193, v81, v117
	v_fmac_f32_e32 v194, v74, v98
	v_fmac_f32_e32 v195, v75, v99
	v_fmac_f32_e32 v196, v76, v100
	v_fmac_f32_e32 v197, v77, v101
	v_cmp_gt_i32_e32 vcc, s3, v228
	v_mul_f32_e32 v198, 0xbfb8aa3b, v190
	v_mul_f32_e32 v199, 0xbfb8aa3b, v191
	v_mul_f32_e32 v200, 0xbfb8aa3b, v192
	v_mul_f32_e32 v201, 0xbfb8aa3b, v193
	v_exp_f32_e32 v198, v198
	v_exp_f32_e32 v199, v199
	v_exp_f32_e32 v200, v200
	v_exp_f32_e32 v201, v201
	v_add_f32_e32 v198, 1.0, v198
	v_add_f32_e32 v199, 1.0, v199
	v_add_f32_e32 v200, 1.0, v200
	v_add_f32_e32 v201, 1.0, v201
	v_rcp_f32_e32 v198, v198
	v_rcp_f32_e32 v199, v199
	v_rcp_f32_e32 v200, v200
	v_rcp_f32_e32 v201, v201
	v_mul_f32_e32 v190, v190, v198
	v_mul_f32_e32 v191, v191, v199
	v_mul_f32_e32 v192, v192, v200
	v_mul_f32_e32 v193, v193, v201
	v_mul_f32_e32 v190, v190, v194
	v_mul_f32_e32 v191, v191, v195
	v_mul_f32_e32 v192, v192, v196
	v_mul_f32_e32 v193, v193, v197
	v_cvt_pk_bf16_f32 v226, v190, v191
	v_cvt_pk_bf16_f32 v227, v192, v193
	s_and_saveexec_b64 s[0:1], vcc
	global_store_dwordx2 v229, v[226:227], s[12:13]
	s_mov_b64 exec, s[0:1]
	v_fma_f32 v190, v78, v122, v118
	v_fma_f32 v191, v79, v123, v119
	v_fma_f32 v192, v80, v124, v120
	v_fma_f32 v193, v81, v125, v121
	v_fma_f32 v194, v74, v106, v102
	v_fma_f32 v195, v75, v107, v103
	v_fma_f32 v196, v76, v108, v104
	v_fma_f32 v197, v77, v109, v105
	v_add_u32_e32 v228, 0x7e, v186
	v_add_u32_e32 v229, 0xad400, v187
	v_fmac_f32_e32 v190, v86, v126
	v_fmac_f32_e32 v191, v87, v127
	v_fmac_f32_e32 v192, v88, v128
	v_fmac_f32_e32 v193, v89, v129
	v_fmac_f32_e32 v194, v82, v110
	v_fmac_f32_e32 v195, v83, v111
	v_fmac_f32_e32 v196, v84, v112
	v_fmac_f32_e32 v197, v85, v113
	v_fmac_f32_e32 v190, v70, v114
	v_fmac_f32_e32 v191, v71, v115
	v_fmac_f32_e32 v192, v72, v116
	v_fmac_f32_e32 v193, v73, v117
	v_fmac_f32_e32 v194, v66, v98
	v_fmac_f32_e32 v195, v67, v99
	v_fmac_f32_e32 v196, v68, v100
	v_fmac_f32_e32 v197, v69, v101
	v_cmp_gt_i32_e32 vcc, s3, v228
	v_mul_f32_e32 v198, 0xbfb8aa3b, v190
	v_mul_f32_e32 v199, 0xbfb8aa3b, v191
	v_mul_f32_e32 v200, 0xbfb8aa3b, v192
	v_mul_f32_e32 v201, 0xbfb8aa3b, v193
	v_exp_f32_e32 v198, v198
	v_exp_f32_e32 v199, v199
	v_exp_f32_e32 v200, v200
	v_exp_f32_e32 v201, v201
	v_add_f32_e32 v198, 1.0, v198
	v_add_f32_e32 v199, 1.0, v199
	v_add_f32_e32 v200, 1.0, v200
	v_add_f32_e32 v201, 1.0, v201
	v_rcp_f32_e32 v198, v198
	v_rcp_f32_e32 v199, v199
	v_rcp_f32_e32 v200, v200
	v_rcp_f32_e32 v201, v201
	v_mul_f32_e32 v190, v190, v198
	v_mul_f32_e32 v191, v191, v199
	v_mul_f32_e32 v192, v192, v200
	v_mul_f32_e32 v193, v193, v201
	v_mul_f32_e32 v190, v190, v194
	v_mul_f32_e32 v191, v191, v195
	v_mul_f32_e32 v192, v192, v196
	v_mul_f32_e32 v193, v193, v197
	v_cvt_pk_bf16_f32 v226, v190, v191
	v_cvt_pk_bf16_f32 v227, v192, v193
	s_and_saveexec_b64 s[0:1], vcc
	global_store_dwordx2 v229, v[226:227], s[12:13]
	s_mov_b64 exec, s[0:1]
	v_fma_f32 v190, v70, v122, v118
	v_fma_f32 v191, v71, v123, v119
	v_fma_f32 v192, v72, v124, v120
	v_fma_f32 v193, v73, v125, v121
	v_fma_f32 v194, v66, v106, v102
	v_fma_f32 v195, v67, v107, v103
	v_fma_f32 v196, v68, v108, v104
	v_fma_f32 v197, v69, v109, v105
	v_add_u32_e32 v228, 0x7f, v186
	v_add_u32_e32 v229, 0xaea00, v187
	v_fmac_f32_e32 v190, v78, v126
	v_fmac_f32_e32 v191, v79, v127
	v_fmac_f32_e32 v192, v80, v128
	v_fmac_f32_e32 v193, v81, v129
	v_fmac_f32_e32 v194, v74, v110
	v_fmac_f32_e32 v195, v75, v111
	v_fmac_f32_e32 v196, v76, v112
	v_fmac_f32_e32 v197, v77, v113
	v_fmac_f32_dpp v190, v94, v114 row_ror:15 row_mask:0xf bank_mask:0xf
	v_fmac_f32_dpp v191, v95, v115 row_ror:15 row_mask:0xf bank_mask:0xf
	v_fmac_f32_dpp v192, v96, v116 row_ror:15 row_mask:0xf bank_mask:0xf
	v_fmac_f32_dpp v193, v97, v117 row_ror:15 row_mask:0xf bank_mask:0xf
	v_fmac_f32_dpp v194, v90, v98 row_ror:15 row_mask:0xf bank_mask:0xf
	v_fmac_f32_dpp v195, v91, v99 row_ror:15 row_mask:0xf bank_mask:0xf
	v_fmac_f32_dpp v196, v92, v100 row_ror:15 row_mask:0xf bank_mask:0xf
	v_fmac_f32_dpp v197, v93, v101 row_ror:15 row_mask:0xf bank_mask:0xf
	v_cmp_gt_i32_e32 vcc, s3, v228
	v_mul_f32_e32 v198, 0xbfb8aa3b, v190
	v_mul_f32_e32 v199, 0xbfb8aa3b, v191
	v_mul_f32_e32 v200, 0xbfb8aa3b, v192
	v_mul_f32_e32 v201, 0xbfb8aa3b, v193
	v_exp_f32_e32 v198, v198
	v_exp_f32_e32 v199, v199
	v_exp_f32_e32 v200, v200
	v_exp_f32_e32 v201, v201
	v_add_f32_e32 v198, 1.0, v198
	v_add_f32_e32 v199, 1.0, v199
	v_add_f32_e32 v200, 1.0, v200
	v_add_f32_e32 v201, 1.0, v201
	v_rcp_f32_e32 v198, v198
	v_rcp_f32_e32 v199, v199
	v_rcp_f32_e32 v200, v200
	v_rcp_f32_e32 v201, v201
	v_mul_f32_e32 v190, v190, v198
	v_mul_f32_e32 v191, v191, v199
	v_mul_f32_e32 v192, v192, v200
	v_mul_f32_e32 v193, v193, v201
	v_mul_f32_e32 v190, v190, v194
	v_mul_f32_e32 v191, v191, v195
	v_mul_f32_e32 v192, v192, v196
	v_mul_f32_e32 v193, v193, v197
	v_cvt_pk_bf16_f32 v226, v190, v191
	v_cvt_pk_bf16_f32 v227, v192, v193
	s_and_b64 vcc, vcc, s[44:45]
	s_and_saveexec_b64 s[0:1], vcc
	global_store_dwordx2 v229, v[226:227], s[12:13]
	s_mov_b64 exec, s[0:1]
	s_waitcnt lgkmcnt(0)
	v_fma_f32 v190, v62, v134, v142
	v_fma_f32 v191, v63, v135, v143
	v_fma_f32 v192, v64, v136, v144
	v_fma_f32 v193, v65, v137, v145
	v_fma_f32 v194, v58, v150, v158
	v_fma_f32 v195, v59, v151, v159
	v_fma_f32 v196, v60, v152, v160
	v_fma_f32 v197, v61, v153, v161
	v_add_u32_e32 v228, 0, v186
	v_fmac_f32_dpp v190, v38, v130 row_ror:1 row_mask:0xf bank_mask:0xf
	v_fmac_f32_dpp v191, v39, v131 row_ror:1 row_mask:0xf bank_mask:0xf
	v_fmac_f32_dpp v192, v40, v132 row_ror:1 row_mask:0xf bank_mask:0xf
	v_fmac_f32_dpp v193, v41, v133 row_ror:1 row_mask:0xf bank_mask:0xf
	v_fmac_f32_dpp v194, v34, v146 row_ror:1 row_mask:0xf bank_mask:0xf
	v_fmac_f32_dpp v195, v35, v147 row_ror:1 row_mask:0xf bank_mask:0xf
	v_fmac_f32_dpp v196, v36, v148 row_ror:1 row_mask:0xf bank_mask:0xf
	v_fmac_f32_dpp v197, v37, v149 row_ror:1 row_mask:0xf bank_mask:0xf
	v_fmac_f32_e32 v190, v54, v138
	v_fmac_f32_e32 v191, v55, v139
	v_fmac_f32_e32 v192, v56, v140
	v_fmac_f32_e32 v193, v57, v141
	v_fmac_f32_e32 v194, v50, v154
	v_fmac_f32_e32 v195, v51, v155
	v_fmac_f32_e32 v196, v52, v156
	v_fmac_f32_e32 v197, v53, v157
	v_cmp_gt_i32_e32 vcc, s3, v228
	v_mul_f32_e32 v198, 0xbfb8aa3b, v190
	v_mul_f32_e32 v199, 0xbfb8aa3b, v191
	v_mul_f32_e32 v200, 0xbfb8aa3b, v192
	v_mul_f32_e32 v201, 0xbfb8aa3b, v193
	v_exp_f32_e32 v198, v198
	v_exp_f32_e32 v199, v199
	v_exp_f32_e32 v200, v200
	v_exp_f32_e32 v201, v201
	v_add_f32_e32 v198, 1.0, v198
	v_add_f32_e32 v199, 1.0, v199
	v_add_f32_e32 v200, 1.0, v200
	v_add_f32_e32 v201, 1.0, v201
	v_rcp_f32_e32 v198, v198
	v_rcp_f32_e32 v199, v199
	v_rcp_f32_e32 v200, v200
	v_rcp_f32_e32 v201, v201
	v_mul_f32_e32 v190, v190, v198
	v_mul_f32_e32 v191, v191, v199
	v_mul_f32_e32 v192, v192, v200
	v_mul_f32_e32 v193, v193, v201
	v_mul_f32_e32 v190, v190, v194
	v_mul_f32_e32 v191, v191, v195
	v_mul_f32_e32 v192, v192, v196
	v_mul_f32_e32 v193, v193, v197
	v_cvt_pk_bf16_f32 v226, v190, v191
	v_cvt_pk_bf16_f32 v227, v192, v193
	s_and_b64 vcc, vcc, s[42:43]
	s_and_saveexec_b64 s[0:1], vcc
	global_store_dwordx2 v187, v[226:227], s[12:13] offset:128
	s_mov_b64 exec, s[0:1]
	v_fma_f32 v190, v54, v134, v142
	v_fma_f32 v191, v55, v135, v143
	v_fma_f32 v192, v56, v136, v144
	v_fma_f32 v193, v57, v137, v145
	v_fma_f32 v194, v50, v150, v158
	v_fma_f32 v195, v51, v151, v159
	v_fma_f32 v196, v52, v152, v160
	v_fma_f32 v197, v53, v153, v161
	v_add_u32_e32 v228, 1, v186
	v_add_u32_e32 v229, 0x1600, v187
	v_fmac_f32_e32 v190, v62, v130
	v_fmac_f32_e32 v191, v63, v131
	v_fmac_f32_e32 v192, v64, v132
	v_fmac_f32_e32 v193, v65, v133
	v_fmac_f32_e32 v194, v58, v146
	v_fmac_f32_e32 v195, v59, v147
	v_fmac_f32_e32 v196, v60, v148
	v_fmac_f32_e32 v197, v61, v149
	v_fmac_f32_e32 v190, v46, v138
	v_fmac_f32_e32 v191, v47, v139
	v_fmac_f32_e32 v192, v48, v140
	v_fmac_f32_e32 v193, v49, v141
	v_fmac_f32_e32 v194, v42, v154
	v_fmac_f32_e32 v195, v43, v155
	v_fmac_f32_e32 v196, v44, v156
	v_fmac_f32_e32 v197, v45, v157
	v_cmp_gt_i32_e32 vcc, s3, v228
	v_mul_f32_e32 v198, 0xbfb8aa3b, v190
	v_mul_f32_e32 v199, 0xbfb8aa3b, v191
	v_mul_f32_e32 v200, 0xbfb8aa3b, v192
	v_mul_f32_e32 v201, 0xbfb8aa3b, v193
	v_exp_f32_e32 v198, v198
	v_exp_f32_e32 v199, v199
	v_exp_f32_e32 v200, v200
	v_exp_f32_e32 v201, v201
	v_add_f32_e32 v198, 1.0, v198
	v_add_f32_e32 v199, 1.0, v199
	v_add_f32_e32 v200, 1.0, v200
	v_add_f32_e32 v201, 1.0, v201
	v_rcp_f32_e32 v198, v198
	v_rcp_f32_e32 v199, v199
	v_rcp_f32_e32 v200, v200
	v_rcp_f32_e32 v201, v201
	v_mul_f32_e32 v190, v190, v198
	v_mul_f32_e32 v191, v191, v199
	v_mul_f32_e32 v192, v192, v200
	v_mul_f32_e32 v193, v193, v201
	v_mul_f32_e32 v190, v190, v194
	v_mul_f32_e32 v191, v191, v195
	v_mul_f32_e32 v192, v192, v196
	v_mul_f32_e32 v193, v193, v197
	v_cvt_pk_bf16_f32 v226, v190, v191
	v_cvt_pk_bf16_f32 v227, v192, v193
	s_and_saveexec_b64 s[0:1], vcc
	global_store_dwordx2 v229, v[226:227], s[12:13] offset:128
	s_mov_b64 exec, s[0:1]
	v_fma_f32 v190, v46, v134, v142
	v_fma_f32 v191, v47, v135, v143
	v_fma_f32 v192, v48, v136, v144
	v_fma_f32 v193, v49, v137, v145
	v_fma_f32 v194, v42, v150, v158
	v_fma_f32 v195, v43, v151, v159
	v_fma_f32 v196, v44, v152, v160
	v_fma_f32 v197, v45, v153, v161
	v_add_u32_e32 v228, 2, v186
	v_add_u32_e32 v229, 0x2c00, v187
	v_fmac_f32_e32 v190, v54, v130
	v_fmac_f32_e32 v191, v55, v131
	v_fmac_f32_e32 v192, v56, v132
	v_fmac_f32_e32 v193, v57, v133
	v_fmac_f32_e32 v194, v50, v146
	v_fmac_f32_e32 v195, v51, v147
	v_fmac_f32_e32 v196, v52, v148
	v_fmac_f32_e32 v197, v53, v149
	v_fmac_f32_e32 v190, v38, v138
	v_fmac_f32_e32 v191, v39, v139
	v_fmac_f32_e32 v192, v40, v140
	v_fmac_f32_e32 v193, v41, v141
	v_fmac_f32_e32 v194, v34, v154
	v_fmac_f32_e32 v195, v35, v155
	v_fmac_f32_e32 v196, v36, v156
	v_fmac_f32_e32 v197, v37, v157
	v_cmp_gt_i32_e32 vcc, s3, v228
	v_mul_f32_e32 v198, 0xbfb8aa3b, v190
	v_mul_f32_e32 v199, 0xbfb8aa3b, v191
	v_mul_f32_e32 v200, 0xbfb8aa3b, v192
	v_mul_f32_e32 v201, 0xbfb8aa3b, v193
	v_exp_f32_e32 v198, v198
	v_exp_f32_e32 v199, v199
	v_exp_f32_e32 v200, v200
	v_exp_f32_e32 v201, v201
	v_add_f32_e32 v198, 1.0, v198
	v_add_f32_e32 v199, 1.0, v199
	v_add_f32_e32 v200, 1.0, v200
	v_add_f32_e32 v201, 1.0, v201
	v_rcp_f32_e32 v198, v198
	v_rcp_f32_e32 v199, v199
	v_rcp_f32_e32 v200, v200
	v_rcp_f32_e32 v201, v201
	v_mul_f32_e32 v190, v190, v198
	v_mul_f32_e32 v191, v191, v199
	v_mul_f32_e32 v192, v192, v200
	v_mul_f32_e32 v193, v193, v201
	v_mul_f32_e32 v190, v190, v194
	v_mul_f32_e32 v191, v191, v195
	v_mul_f32_e32 v192, v192, v196
	v_mul_f32_e32 v193, v193, v197
	v_cvt_pk_bf16_f32 v226, v190, v191
	v_cvt_pk_bf16_f32 v227, v192, v193
	s_and_saveexec_b64 s[0:1], vcc
	global_store_dwordx2 v229, v[226:227], s[12:13] offset:128
	s_mov_b64 exec, s[0:1]
	v_fma_f32 v190, v38, v134, v142
	v_fma_f32 v191, v39, v135, v143
	v_fma_f32 v192, v40, v136, v144
	v_fma_f32 v193, v41, v137, v145
	v_fma_f32 v194, v34, v150, v158
	v_fma_f32 v195, v35, v151, v159
	v_fma_f32 v196, v36, v152, v160
	v_fma_f32 v197, v37, v153, v161
	v_add_u32_e32 v228, 3, v186
	v_add_u32_e32 v229, 0x4200, v187
	v_fmac_f32_e32 v190, v46, v130
	v_fmac_f32_e32 v191, v47, v131
	v_fmac_f32_e32 v192, v48, v132
	v_fmac_f32_e32 v193, v49, v133
	v_fmac_f32_e32 v194, v42, v146
	v_fmac_f32_e32 v195, v43, v147
	v_fmac_f32_e32 v196, v44, v148
	v_fmac_f32_e32 v197, v45, v149
	v_fmac_f32_dpp v190, v62, v138 row_ror:15 row_mask:0xf bank_mask:0xf
	v_fmac_f32_dpp v191, v63, v139 row_ror:15 row_mask:0xf bank_mask:0xf
	v_fmac_f32_dpp v192, v64, v140 row_ror:15 row_mask:0xf bank_mask:0xf
	v_fmac_f32_dpp v193, v65, v141 row_ror:15 row_mask:0xf bank_mask:0xf
	v_fmac_f32_dpp v194, v58, v154 row_ror:15 row_mask:0xf bank_mask:0xf
	v_fmac_f32_dpp v195, v59, v155 row_ror:15 row_mask:0xf bank_mask:0xf
	v_fmac_f32_dpp v196, v60, v156 row_ror:15 row_mask:0xf bank_mask:0xf
	v_fmac_f32_dpp v197, v61, v157 row_ror:15 row_mask:0xf bank_mask:0xf
	v_cmp_gt_i32_e32 vcc, s3, v228
	v_mul_f32_e32 v198, 0xbfb8aa3b, v190
	v_mul_f32_e32 v199, 0xbfb8aa3b, v191
	v_mul_f32_e32 v200, 0xbfb8aa3b, v192
	v_mul_f32_e32 v201, 0xbfb8aa3b, v193
	v_exp_f32_e32 v198, v198
	v_exp_f32_e32 v199, v199
	v_exp_f32_e32 v200, v200
	v_exp_f32_e32 v201, v201
	v_add_f32_e32 v198, 1.0, v198
	v_add_f32_e32 v199, 1.0, v199
	v_add_f32_e32 v200, 1.0, v200
	v_add_f32_e32 v201, 1.0, v201
	v_rcp_f32_e32 v198, v198
	v_rcp_f32_e32 v199, v199
	v_rcp_f32_e32 v200, v200
	v_rcp_f32_e32 v201, v201
	v_mul_f32_e32 v190, v190, v198
	v_mul_f32_e32 v191, v191, v199
	v_mul_f32_e32 v192, v192, v200
	v_mul_f32_e32 v193, v193, v201
	v_mul_f32_e32 v190, v190, v194
	v_mul_f32_e32 v191, v191, v195
	v_mul_f32_e32 v192, v192, v196
	v_mul_f32_e32 v193, v193, v197
	v_cvt_pk_bf16_f32 v226, v190, v191
	v_cvt_pk_bf16_f32 v227, v192, v193
	s_and_b64 vcc, vcc, s[44:45]
	s_and_saveexec_b64 s[0:1], vcc
	global_store_dwordx2 v229, v[226:227], s[12:13] offset:128
	s_mov_b64 exec, s[0:1]
	v_fma_f32 v190, v30, v134, v142
	v_fma_f32 v191, v31, v135, v143
	v_fma_f32 v192, v32, v136, v144
	v_fma_f32 v193, v33, v137, v145
	v_fma_f32 v194, v26, v150, v158
	v_fma_f32 v195, v27, v151, v159
	v_fma_f32 v196, v28, v152, v160
	v_fma_f32 v197, v29, v153, v161
	v_add_u32_e32 v228, 0x7c, v186
	v_add_u32_e32 v229, 0xaa800, v187
	v_fmac_f32_dpp v190, v6, v130 row_ror:1 row_mask:0xf bank_mask:0xf
	v_fmac_f32_dpp v191, v7, v131 row_ror:1 row_mask:0xf bank_mask:0xf
	v_fmac_f32_dpp v192, v8, v132 row_ror:1 row_mask:0xf bank_mask:0xf
	v_fmac_f32_dpp v193, v9, v133 row_ror:1 row_mask:0xf bank_mask:0xf
	v_fmac_f32_dpp v194, v2, v146 row_ror:1 row_mask:0xf bank_mask:0xf
	v_fmac_f32_dpp v195, v3, v147 row_ror:1 row_mask:0xf bank_mask:0xf
	v_fmac_f32_dpp v196, v4, v148 row_ror:1 row_mask:0xf bank_mask:0xf
	v_fmac_f32_dpp v197, v5, v149 row_ror:1 row_mask:0xf bank_mask:0xf
	v_fmac_f32_e32 v190, v22, v138
	v_fmac_f32_e32 v191, v23, v139
	v_fmac_f32_e32 v192, v24, v140
	v_fmac_f32_e32 v193, v25, v141
	v_fmac_f32_e32 v194, v18, v154
	v_fmac_f32_e32 v195, v19, v155
	v_fmac_f32_e32 v196, v20, v156
	v_fmac_f32_e32 v197, v21, v157
	v_cmp_gt_i32_e32 vcc, s3, v228
	v_mul_f32_e32 v198, 0xbfb8aa3b, v190
	v_mul_f32_e32 v199, 0xbfb8aa3b, v191
	v_mul_f32_e32 v200, 0xbfb8aa3b, v192
	v_mul_f32_e32 v201, 0xbfb8aa3b, v193
	v_exp_f32_e32 v198, v198
	v_exp_f32_e32 v199, v199
	v_exp_f32_e32 v200, v200
	v_exp_f32_e32 v201, v201
	v_add_f32_e32 v198, 1.0, v198
	v_add_f32_e32 v199, 1.0, v199
	v_add_f32_e32 v200, 1.0, v200
	v_add_f32_e32 v201, 1.0, v201
	v_rcp_f32_e32 v198, v198
	v_rcp_f32_e32 v199, v199
	v_rcp_f32_e32 v200, v200
	v_rcp_f32_e32 v201, v201
	v_mul_f32_e32 v190, v190, v198
	v_mul_f32_e32 v191, v191, v199
	v_mul_f32_e32 v192, v192, v200
	v_mul_f32_e32 v193, v193, v201
	v_mul_f32_e32 v190, v190, v194
	v_mul_f32_e32 v191, v191, v195
	v_mul_f32_e32 v192, v192, v196
	v_mul_f32_e32 v193, v193, v197
	v_cvt_pk_bf16_f32 v226, v190, v191
	v_cvt_pk_bf16_f32 v227, v192, v193
	s_and_b64 vcc, vcc, s[42:43]
	s_and_saveexec_b64 s[0:1], vcc
	global_store_dwordx2 v229, v[226:227], s[12:13] offset:128
	s_mov_b64 exec, s[0:1]
	v_fma_f32 v190, v22, v134, v142
	v_fma_f32 v191, v23, v135, v143
	v_fma_f32 v192, v24, v136, v144
	v_fma_f32 v193, v25, v137, v145
	v_fma_f32 v194, v18, v150, v158
	v_fma_f32 v195, v19, v151, v159
	v_fma_f32 v196, v20, v152, v160
	v_fma_f32 v197, v21, v153, v161
	v_add_u32_e32 v228, 0x7d, v186
	v_add_u32_e32 v229, 0xabe00, v187
	v_fmac_f32_e32 v190, v30, v130
	v_fmac_f32_e32 v191, v31, v131
	v_fmac_f32_e32 v192, v32, v132
	v_fmac_f32_e32 v193, v33, v133
	v_fmac_f32_e32 v194, v26, v146
	v_fmac_f32_e32 v195, v27, v147
	v_fmac_f32_e32 v196, v28, v148
	v_fmac_f32_e32 v197, v29, v149
	v_fmac_f32_e32 v190, v14, v138
	v_fmac_f32_e32 v191, v15, v139
	v_fmac_f32_e32 v192, v16, v140
	v_fmac_f32_e32 v193, v17, v141
	v_fmac_f32_e32 v194, v10, v154
	v_fmac_f32_e32 v195, v11, v155
	v_fmac_f32_e32 v196, v12, v156
	v_fmac_f32_e32 v197, v13, v157
	v_cmp_gt_i32_e32 vcc, s3, v228
	v_mul_f32_e32 v198, 0xbfb8aa3b, v190
	v_mul_f32_e32 v199, 0xbfb8aa3b, v191
	v_mul_f32_e32 v200, 0xbfb8aa3b, v192
	v_mul_f32_e32 v201, 0xbfb8aa3b, v193
	v_exp_f32_e32 v198, v198
	v_exp_f32_e32 v199, v199
	v_exp_f32_e32 v200, v200
	v_exp_f32_e32 v201, v201
	v_add_f32_e32 v198, 1.0, v198
	v_add_f32_e32 v199, 1.0, v199
	v_add_f32_e32 v200, 1.0, v200
	v_add_f32_e32 v201, 1.0, v201
	v_rcp_f32_e32 v198, v198
	v_rcp_f32_e32 v199, v199
	v_rcp_f32_e32 v200, v200
	v_rcp_f32_e32 v201, v201
	v_mul_f32_e32 v190, v190, v198
	v_mul_f32_e32 v191, v191, v199
	v_mul_f32_e32 v192, v192, v200
	v_mul_f32_e32 v193, v193, v201
	v_mul_f32_e32 v190, v190, v194
	v_mul_f32_e32 v191, v191, v195
	v_mul_f32_e32 v192, v192, v196
	v_mul_f32_e32 v193, v193, v197
	v_cvt_pk_bf16_f32 v226, v190, v191
	v_cvt_pk_bf16_f32 v227, v192, v193
	s_and_saveexec_b64 s[0:1], vcc
	global_store_dwordx2 v229, v[226:227], s[12:13] offset:128
	s_mov_b64 exec, s[0:1]
	v_fma_f32 v190, v14, v134, v142
	v_fma_f32 v191, v15, v135, v143
	v_fma_f32 v192, v16, v136, v144
	v_fma_f32 v193, v17, v137, v145
	v_fma_f32 v194, v10, v150, v158
	v_fma_f32 v195, v11, v151, v159
	v_fma_f32 v196, v12, v152, v160
	v_fma_f32 v197, v13, v153, v161
	v_add_u32_e32 v228, 0x7e, v186
	v_add_u32_e32 v229, 0xad400, v187
	v_fmac_f32_e32 v190, v22, v130
	v_fmac_f32_e32 v191, v23, v131
	v_fmac_f32_e32 v192, v24, v132
	v_fmac_f32_e32 v193, v25, v133
	v_fmac_f32_e32 v194, v18, v146
	v_fmac_f32_e32 v195, v19, v147
	v_fmac_f32_e32 v196, v20, v148
	v_fmac_f32_e32 v197, v21, v149
	v_fmac_f32_e32 v190, v6, v138
	v_fmac_f32_e32 v191, v7, v139
	v_fmac_f32_e32 v192, v8, v140
	v_fmac_f32_e32 v193, v9, v141
	v_fmac_f32_e32 v194, v2, v154
	v_fmac_f32_e32 v195, v3, v155
	v_fmac_f32_e32 v196, v4, v156
	v_fmac_f32_e32 v197, v5, v157
	v_cmp_gt_i32_e32 vcc, s3, v228
	v_mul_f32_e32 v198, 0xbfb8aa3b, v190
	v_mul_f32_e32 v199, 0xbfb8aa3b, v191
	v_mul_f32_e32 v200, 0xbfb8aa3b, v192
	v_mul_f32_e32 v201, 0xbfb8aa3b, v193
	v_exp_f32_e32 v198, v198
	v_exp_f32_e32 v199, v199
	v_exp_f32_e32 v200, v200
	v_exp_f32_e32 v201, v201
	v_add_f32_e32 v198, 1.0, v198
	v_add_f32_e32 v199, 1.0, v199
	v_add_f32_e32 v200, 1.0, v200
	v_add_f32_e32 v201, 1.0, v201
	v_rcp_f32_e32 v198, v198
	v_rcp_f32_e32 v199, v199
	v_rcp_f32_e32 v200, v200
	v_rcp_f32_e32 v201, v201
	v_mul_f32_e32 v190, v190, v198
	v_mul_f32_e32 v191, v191, v199
	v_mul_f32_e32 v192, v192, v200
	v_mul_f32_e32 v193, v193, v201
	v_mul_f32_e32 v190, v190, v194
	v_mul_f32_e32 v191, v191, v195
	v_mul_f32_e32 v192, v192, v196
	v_mul_f32_e32 v193, v193, v197
	v_cvt_pk_bf16_f32 v226, v190, v191
	v_cvt_pk_bf16_f32 v227, v192, v193
	s_and_saveexec_b64 s[0:1], vcc
	global_store_dwordx2 v229, v[226:227], s[12:13] offset:128
	s_mov_b64 exec, s[0:1]
	v_fma_f32 v190, v6, v134, v142
	v_fma_f32 v191, v7, v135, v143
	v_fma_f32 v192, v8, v136, v144
	v_fma_f32 v193, v9, v137, v145
	v_fma_f32 v194, v2, v150, v158
	v_fma_f32 v195, v3, v151, v159
	v_fma_f32 v196, v4, v152, v160
	v_fma_f32 v197, v5, v153, v161
	v_add_u32_e32 v228, 0x7f, v186
	v_add_u32_e32 v229, 0xaea00, v187
	v_fmac_f32_e32 v190, v14, v130
	v_fmac_f32_e32 v191, v15, v131
	v_fmac_f32_e32 v192, v16, v132
	v_fmac_f32_e32 v193, v17, v133
	v_fmac_f32_e32 v194, v10, v146
	v_fmac_f32_e32 v195, v11, v147
	v_fmac_f32_e32 v196, v12, v148
	v_fmac_f32_e32 v197, v13, v149
	v_fmac_f32_dpp v190, v30, v138 row_ror:15 row_mask:0xf bank_mask:0xf
	v_fmac_f32_dpp v191, v31, v139 row_ror:15 row_mask:0xf bank_mask:0xf
	v_fmac_f32_dpp v192, v32, v140 row_ror:15 row_mask:0xf bank_mask:0xf
	v_fmac_f32_dpp v193, v33, v141 row_ror:15 row_mask:0xf bank_mask:0xf
	v_fmac_f32_dpp v194, v26, v154 row_ror:15 row_mask:0xf bank_mask:0xf
	v_fmac_f32_dpp v195, v27, v155 row_ror:15 row_mask:0xf bank_mask:0xf
	v_fmac_f32_dpp v196, v28, v156 row_ror:15 row_mask:0xf bank_mask:0xf
	v_fmac_f32_dpp v197, v29, v157 row_ror:15 row_mask:0xf bank_mask:0xf
	v_cmp_gt_i32_e32 vcc, s3, v228
	v_mul_f32_e32 v198, 0xbfb8aa3b, v190
	v_mul_f32_e32 v199, 0xbfb8aa3b, v191
	v_mul_f32_e32 v200, 0xbfb8aa3b, v192
	v_mul_f32_e32 v201, 0xbfb8aa3b, v193
	v_exp_f32_e32 v198, v198
	v_exp_f32_e32 v199, v199
	v_exp_f32_e32 v200, v200
	v_exp_f32_e32 v201, v201
	v_add_f32_e32 v198, 1.0, v198
	v_add_f32_e32 v199, 1.0, v199
	v_add_f32_e32 v200, 1.0, v200
	v_add_f32_e32 v201, 1.0, v201
	v_rcp_f32_e32 v198, v198
	v_rcp_f32_e32 v199, v199
	v_rcp_f32_e32 v200, v200
	v_rcp_f32_e32 v201, v201
	v_mul_f32_e32 v190, v190, v198
	v_mul_f32_e32 v191, v191, v199
	v_mul_f32_e32 v192, v192, v200
	v_mul_f32_e32 v193, v193, v201
	v_mul_f32_e32 v190, v190, v194
	v_mul_f32_e32 v191, v191, v195
	v_mul_f32_e32 v192, v192, v196
	v_mul_f32_e32 v193, v193, v197
	v_cvt_pk_bf16_f32 v226, v190, v191
	v_cvt_pk_bf16_f32 v227, v192, v193
	s_and_b64 vcc, vcc, s[44:45]
	s_and_saveexec_b64 s[0:1], vcc
	global_store_dwordx2 v229, v[226:227], s[12:13] offset:128
	s_mov_b64 exec, s[0:1]

.LBB0_140:
	s_setprio 0
	s_waitcnt vmcnt(0)
	v_readlane_b32 s44, v255, 8
	s_cmpk_gt_u32 s64, 0xff
	v_readlane_b32 s45, v255, 9
	s_cbranch_scc1 .LBB0_142
	s_barrier

.LBB0_149:
	v_ashrrev_i32_e32 v0, 2, v164
	v_mul_hi_i32 v2, v0, s22
	v_lshrrev_b32_e32 v4, 31, v2
	v_add_u32_e32 v159, v2, v4
	v_mul_lo_u32 v2, v159, 6
	s_waitcnt vmcnt(0)
	v_sub_u32_e32 v130, v0, v2
	s_mul_i32 s3, s62, 6
	v_add_u32_e32 v4, s3, v130
	v_ashrrev_i32_e32 v5, 31, v4
	v_lshlrev_b64 v[4:5], 2, v[4:5]
	v_mov_b32_e32 v3, v202
	v_lshl_add_u64 v[6:7], s[66:67], 0, v[4:5]
	global_load_dword v178, v[6:7], off
	v_and_b32_e32 v158, 15, v3
	v_bfe_u32 v8, v3, 4, 2
	v_lshlrev_b32_e32 v2, 7, v159
	v_lshl_add_u64 v[4:5], s[68:69], 0, v[4:5]
	v_lshlrev_b32_e32 v98, 6, v130
	global_load_dword v179, v[4:5], off
	v_ashrrev_i32_e32 v99, 31, v98
	v_mov_b64_e32 v[4:5], s[16:17]
	v_lshlrev_b64 v[134:135], 1, v[98:99]
	v_lshlrev_b32_e32 v102, 4, v8
	v_mov_b32_e32 v103, v1
	v_and_or_b32 v168, v165, s23, v158
	v_or_b32_e32 v167, v168, v2
	v_or_b32_e32 v166, 16, v167
	v_lshlrev_b32_e32 v0, 3, v8
	v_mad_i64_i32 v[6:7], s[14:15], v167, s57, v[4:5]
	v_mad_i64_i32 v[8:9], s[14:15], v166, s57, v[4:5]
	v_lshl_add_u64 v[100:101], v[6:7], 0, v[134:135]
	v_lshl_add_u64 v[104:105], v[8:9], 0, v[134:135]
	v_lshl_add_u64 v[6:7], v[100:101], 0, v[102:103]
	v_lshl_add_u64 v[8:9], v[104:105], 0, v[102:103]
	v_lshl_add_u64 v[100:101], v[100:101], 0, v[0:1]
	v_lshl_add_u64 v[106:107], v[100:101], 0, s[52:53]
	v_lshl_add_u64 v[132:133], s[24:25], 0, v[102:103]
	v_or_b32_e32 v171, 16, v168
	v_ashrrev_i32_e32 v131, 31, v130
	v_mov_b32_e32 v173, v1
	v_mov_b32_e32 v175, v1
	v_add_u32_e32 v164, s33, v164
	v_add_u32_e32 v165, s13, v165
	v_lshlrev_b32_e32 v10, 1, v3
	v_and_b32_e32 v10, 24, v10
	v_and_b32_e32 v3, 3, v3
	v_or3_b32 v3, v3, v10, v2
	v_or_b32_e32 v18, 64, v3
	v_mad_i64_i32 v[18:19], s[14:15], v18, s57, v[4:5]
	v_lshl_add_u64 v[18:19], v[18:19], 0, v[134:135]
	v_lshl_add_u64 v[34:35], v[18:19], 0, v[102:103]
	v_or_b32_e32 v18, 0x44, v3
	v_mad_i64_i32 v[18:19], s[14:15], v18, s57, v[4:5]
	v_lshl_add_u64 v[18:19], v[18:19], 0, v[134:135]
	v_lshl_add_u64 v[36:37], v[18:19], 0, v[102:103]
	v_or_b32_e32 v18, 0x60, v3
	v_mad_i64_i32 v[18:19], s[14:15], v18, s57, v[4:5]
	v_mad_i64_i32 v[10:11], s[14:15], v3, s57, v[4:5]
	v_or_b32_e32 v12, 4, v3
	v_or_b32_e32 v14, 32, v3
	v_or_b32_e32 v16, 36, v3
	v_lshl_add_u64 v[18:19], v[18:19], 0, v[134:135]
	v_or_b32_e32 v3, 0x64, v3
	v_mad_i64_i32 v[12:13], s[14:15], v12, s57, v[4:5]
	v_mad_i64_i32 v[14:15], s[14:15], v14, s57, v[4:5]
	v_mad_i64_i32 v[16:17], s[14:15], v16, s57, v[4:5]
	v_lshl_add_u64 v[94:95], v[18:19], 0, v[102:103]
	v_mad_i64_i32 v[4:5], s[14:15], v3, s57, v[4:5]
	v_or_b32_e32 v18, v98, v158
	v_ashrrev_i32_e32 v3, 31, v2
	v_lshl_add_u64 v[2:3], v[2:3], 1, s[18:19]
	v_mul_lo_u32 v18, v18, s35
	v_lshl_add_u64 v[2:3], v[2:3], 0, v[102:103]
	v_ashrrev_i32_e32 v19, 31, v18
	v_lshl_add_u64 v[110:111], v[18:19], 1, v[2:3]
	v_add_co_u32_e32 v112, vcc, s42, v110
	v_lshl_add_u64 v[12:13], v[12:13], 0, v[134:135]
	s_nop 0
	v_addc_co_u32_e32 v113, vcc, 0, v111, vcc
	v_add_co_u32_e32 v152, vcc, s43, v110
	v_lshl_add_u64 v[10:11], v[10:11], 0, v[134:135]
	v_lshl_add_u64 v[12:13], v[12:13], 0, v[102:103]
	v_lshl_add_u64 v[14:15], v[14:15], 0, v[134:135]
	v_lshl_add_u64 v[16:17], v[16:17], 0, v[134:135]
	v_addc_co_u32_e32 v153, vcc, 0, v111, vcc
	v_lshl_add_u64 v[10:11], v[10:11], 0, v[102:103]
	v_lshl_add_u64 v[14:15], v[14:15], 0, v[102:103]
	v_lshl_add_u64 v[16:17], v[16:17], 0, v[102:103]
	v_lshl_add_u64 v[4:5], v[4:5], 0, v[134:135]
	global_load_dwordx4 v[66:69], v[12:13], off offset:3648
	global_load_dwordx4 v[70:73], v[12:13], off offset:3584
	global_load_dwordx4 v[74:77], v[10:11], off offset:3648
	global_load_dwordx4 v[78:81], v[10:11], off offset:3584
	global_load_dwordx4 v[18:21], v[8:9], off offset:2880
	global_load_dwordx4 v[26:29], v[8:9], off offset:2816
	global_load_dwordx4 v[22:25], v[6:7], off offset:2880
	global_load_dwordx4 v[30:33], v[6:7], off offset:2816
	global_load_dwordx4 v[114:117], v[36:37], off offset:3648
	global_load_dwordx4 v[118:121], v[36:37], off offset:3584
	global_load_dwordx4 v[122:125], v[34:35], off offset:3648
	global_load_dwordx4 v[126:129], v[34:35], off offset:3584
	s_nop 0
	global_load_dwordx4 v[34:37], v[16:17], off offset:3648
	global_load_dwordx4 v[38:41], v[16:17], off offset:3584
	global_load_dwordx4 v[42:45], v[14:15], off offset:3648
	global_load_dwordx4 v[46:49], v[14:15], off offset:3584
	v_add_co_u32_e32 v154, vcc, s50, v110
	v_lshl_add_u64 v[4:5], v[4:5], 0, v[102:103]
	s_nop 0
	v_addc_co_u32_e32 v155, vcc, 0, v111, vcc
	global_load_dwordx4 v[50:53], v[112:113], off
	global_load_dwordx4 v[54:57], v[152:153], off
	global_load_dwordx4 v[58:61], v[154:155], off
	global_load_dwordx4 v[62:65], v[110:111], off
	global_load_dwordx4 v[82:85], v[4:5], off offset:3648
	global_load_dwordx4 v[86:89], v[4:5], off offset:3584
	global_load_dwordx4 v[90:93], v[94:95], off offset:3648
	s_nop 0
	global_load_dwordx4 v[94:97], v[94:95], off offset:3584
	s_nop 0
	global_load_dwordx4 v[2:5], v[112:113], off offset:64
	global_load_dwordx4 v[6:9], v[152:153], off offset:64
	global_load_dwordx4 v[10:13], v[154:155], off offset:64
	global_load_dwordx4 v[14:17], v[110:111], off offset:64
	v_add_co_u32_e32 v100, vcc, s51, v100
	v_lshl_add_u64 v[98:99], v[98:99], 2, s[38:39]
	s_nop 0
	v_addc_co_u32_e32 v101, vcc, 0, v101, vcc
	v_lshl_add_u64 v[156:157], v[98:99], 0, v[102:103]
	v_or_b32_e32 v108, 7, v0
	s_waitcnt vmcnt(0)
	v_mul_f32_e32 v169, 0x3fb8aa3b, v178
	v_mul_f32_e32 v170, 0x3fb8aa3b, v179
	global_load_dwordx2 v[150:151], v[100:101], off offset:1024
	global_load_dwordx2 v[148:149], v[106:107], off offset:32
	global_load_dwordx2 v[146:147], v[106:107], off offset:64
	global_load_dwordx2 v[144:145], v[106:107], off offset:96
	v_lshl_add_u64 v[100:101], v[104:105], 0, v[0:1]
	v_lshl_add_u64 v[104:105], v[100:101], 0, s[52:53]
	v_add_co_u32_e32 v100, vcc, s51, v100
	v_or_b32_e32 v106, 5, v0
	s_nop 0
	v_addc_co_u32_e32 v101, vcc, 0, v101, vcc
	global_load_dwordx2 v[142:143], v[100:101], off offset:1024
	global_load_dwordx2 v[140:141], v[104:105], off offset:32
	global_load_dwordx2 v[138:139], v[104:105], off offset:64
	global_load_dwordx2 v[136:137], v[104:105], off offset:96
	v_mfma_f32_16x16x32_bf16 v[98:101], v[78:81], v[30:33], 0
	v_or_b32_e32 v107, 6, v0
	v_mfma_f32_16x16x32_bf16 v[78:81], v[78:81], v[26:29], 0
	v_mfma_f32_16x16x32_bf16 v[98:101], v[74:77], v[22:25], v[98:101]
	v_mfma_f32_16x16x32_bf16 v[74:77], v[74:77], v[18:21], v[78:81]
	v_mfma_f32_16x16x32_bf16 v[78:81], v[70:73], v[30:33], 0
	v_mfma_f32_16x16x32_bf16 v[70:73], v[70:73], v[26:29], 0
	v_mfma_f32_16x16x32_bf16 v[78:81], v[66:69], v[22:25], v[78:81]
	v_mfma_f32_16x16x32_bf16 v[66:69], v[66:69], v[18:21], v[70:73]
	s_nop 5
	v_sub_u32_e32 v71, v168, v0
	v_cvt_f32_u32_e32 v72, v71
	v_cmp_lt_i32_e32 vcc, -1, v71
	v_or_b32_e32 v70, 4, v0
	v_mul_f32_e32 v72, v169, v72
	v_exp_f32_e32 v72, v72
	s_nop 0
	v_cndmask_b32_e32 v72, 0, v72, vcc
	v_cmp_gt_i32_e32 vcc, 1, v71
	v_sub_u32_e32 v71, 0, v71
	v_cvt_f32_u32_e32 v71, v71
	v_mul_f32_e32 v71, v170, v71
	v_exp_f32_e32 v71, v71
	s_nop 0
	v_cndmask_b32_e32 v71, 0, v71, vcc
	v_add_f32_e32 v71, v72, v71
	v_or_b32_e32 v72, 1, v0
	v_sub_u32_e32 v73, v168, v72
	v_mul_f32_e32 v71, v71, v98
	v_cvt_f32_u32_e32 v98, v73
	v_cmp_lt_i32_e32 vcc, -1, v73
	v_sub_u32_e32 v72, v171, v72
	v_mul_f32_e32 v98, v169, v98
	v_exp_f32_e32 v98, v98
	s_nop 0
	v_cndmask_b32_e32 v98, 0, v98, vcc
	v_cmp_gt_i32_e32 vcc, 1, v73
	v_sub_u32_e32 v73, 0, v73
	v_cvt_f32_u32_e32 v73, v73
	v_mul_f32_e32 v73, v170, v73
	v_exp_f32_e32 v73, v73
	s_nop 0
	v_cndmask_b32_e32 v73, 0, v73, vcc
	v_add_f32_e32 v73, v98, v73
	v_or_b32_e32 v98, 2, v0
	v_mul_f32_e32 v73, v73, v99
	v_sub_u32_e32 v99, v168, v98
	v_cvt_f32_u32_e32 v102, v99
	v_cmp_lt_i32_e32 vcc, -1, v99
	v_mul_f32_e32 v102, v169, v102
	v_exp_f32_e32 v102, v102
	s_nop 0
	v_cndmask_b32_e32 v102, 0, v102, vcc
	v_cmp_gt_i32_e32 vcc, 1, v99
	v_sub_u32_e32 v99, 0, v99
	v_cvt_f32_u32_e32 v99, v99
	v_mul_f32_e32 v99, v170, v99
	v_exp_f32_e32 v99, v99
	s_nop 0
	v_cndmask_b32_e32 v99, 0, v99, vcc
	v_add_f32_e32 v99, v102, v99
	v_mul_f32_e32 v99, v99, v100
	v_or_b32_e32 v100, 3, v0
	v_sub_u32_e32 v102, v168, v100
	v_cvt_f32_u32_e32 v103, v102
	v_cmp_lt_i32_e32 vcc, -1, v102
	v_mul_f32_e32 v103, v169, v103
	v_exp_f32_e32 v103, v103
	s_nop 0
	v_cndmask_b32_e32 v103, 0, v103, vcc
	v_cmp_gt_i32_e32 vcc, 1, v102
	v_sub_u32_e32 v102, 0, v102
	v_cvt_f32_u32_e32 v102, v102
	v_mul_f32_e32 v102, v170, v102
	v_exp_f32_e32 v102, v102
	s_nop 0
	v_cndmask_b32_e32 v102, 0, v102, vcc
	v_add_f32_e32 v102, v103, v102
	v_mul_f32_e32 v101, v102, v101
	v_sub_u32_e32 v102, v168, v70
	v_cvt_f32_u32_e32 v103, v102
	v_cmp_lt_i32_e32 vcc, -1, v102
	v_sub_u32_e32 v70, v171, v70
	v_mul_f32_e32 v103, v169, v103
	v_exp_f32_e32 v103, v103
	s_nop 0
	v_cndmask_b32_e32 v103, 0, v103, vcc
	v_cmp_gt_i32_e32 vcc, 1, v102
	v_sub_u32_e32 v102, 0, v102
	v_cvt_f32_u32_e32 v102, v102
	v_mul_f32_e32 v102, v170, v102
	v_exp_f32_e32 v102, v102
	s_nop 0
	v_cndmask_b32_e32 v102, 0, v102, vcc
	v_add_f32_e32 v102, v103, v102
	v_mul_f32_e32 v78, v102, v78
	v_sub_u32_e32 v102, v168, v106
	v_cvt_f32_u32_e32 v103, v102
	v_cmp_lt_i32_e32 vcc, -1, v102
	v_mul_f32_e32 v103, v169, v103
	v_exp_f32_e32 v103, v103
	s_nop 0
	v_cndmask_b32_e32 v103, 0, v103, vcc
	v_cmp_gt_i32_e32 vcc, 1, v102
	v_sub_u32_e32 v102, 0, v102
	v_cvt_f32_u32_e32 v102, v102
	v_mul_f32_e32 v102, v170, v102
	v_exp_f32_e32 v102, v102
	s_nop 0
	v_cndmask_b32_e32 v102, 0, v102, vcc
	v_add_f32_e32 v102, v103, v102
	v_mul_f32_e32 v79, v102, v79
	v_sub_u32_e32 v102, v168, v107
	v_cvt_f32_u32_e32 v103, v102
	v_cmp_lt_i32_e32 vcc, -1, v102
	v_cvt_pk_bf16_f32 v104, v78, v79
	v_mul_f32_e32 v103, v169, v103
	v_exp_f32_e32 v103, v103
	s_nop 0
	v_cndmask_b32_e32 v103, 0, v103, vcc
	v_cmp_gt_i32_e32 vcc, 1, v102
	v_sub_u32_e32 v102, 0, v102
	v_cvt_f32_u32_e32 v102, v102
	v_mul_f32_e32 v102, v170, v102
	v_exp_f32_e32 v102, v102
	s_nop 0
	v_cndmask_b32_e32 v102, 0, v102, vcc
	v_add_f32_e32 v102, v103, v102
	v_mul_f32_e32 v80, v102, v80
	v_sub_u32_e32 v102, v168, v108
	v_cvt_f32_u32_e32 v103, v102
	v_cmp_lt_i32_e32 vcc, -1, v102
	v_mul_f32_e32 v103, v169, v103
	v_exp_f32_e32 v103, v103
	s_nop 0
	v_cndmask_b32_e32 v103, 0, v103, vcc
	v_cmp_gt_i32_e32 vcc, 1, v102
	v_sub_u32_e32 v102, 0, v102
	v_cvt_f32_u32_e32 v102, v102
	v_mul_f32_e32 v102, v170, v102
	v_exp_f32_e32 v102, v102
	s_nop 0
	v_cndmask_b32_e32 v102, 0, v102, vcc
	v_add_f32_e32 v102, v103, v102
	v_mul_f32_e32 v81, v102, v81
	v_cvt_pk_bf16_f32 v102, v71, v73
	v_sub_u32_e32 v71, v171, v0
	v_cvt_f32_u32_e32 v73, v71
	v_cmp_lt_i32_e32 vcc, -1, v71
	v_cvt_pk_bf16_f32 v103, v99, v101
	v_cvt_pk_bf16_f32 v105, v80, v81
	v_mul_f32_e32 v73, v169, v73
	v_exp_f32_e32 v73, v73
	v_mfma_f32_16x16x32_bf16 v[78:81], v[54:57], v[102:105], 0
	v_cndmask_b32_e32 v73, 0, v73, vcc
	v_cmp_gt_i32_e32 vcc, 1, v71
	v_sub_u32_e32 v71, 0, v71
	v_cvt_f32_u32_e32 v71, v71
	v_mul_f32_e32 v71, v170, v71
	v_exp_f32_e32 v71, v71
	s_nop 0
	v_cndmask_b32_e32 v71, 0, v71, vcc
	v_add_f32_e32 v71, v73, v71
	v_cvt_f32_u32_e32 v73, v72
	v_cmp_lt_i32_e32 vcc, -1, v72
	v_mul_f32_e32 v71, v71, v74
	v_mul_f32_e32 v73, v169, v73
	v_exp_f32_e32 v73, v73
	s_nop 0
	v_cndmask_b32_e32 v73, 0, v73, vcc
	v_cmp_gt_i32_e32 vcc, 1, v72
	v_sub_u32_e32 v72, 0, v72
	v_cvt_f32_u32_e32 v72, v72
	v_mul_f32_e32 v72, v170, v72
	v_exp_f32_e32 v72, v72
	s_nop 0
	v_cndmask_b32_e32 v72, 0, v72, vcc
	v_add_f32_e32 v72, v73, v72
	v_sub_u32_e32 v73, v171, v98
	v_cvt_f32_u32_e32 v74, v73
	v_cmp_lt_i32_e32 vcc, -1, v73
	v_mul_f32_e32 v72, v72, v75
	v_mul_f32_e32 v74, v169, v74
	v_exp_f32_e32 v74, v74
	s_nop 0
	v_cndmask_b32_e32 v74, 0, v74, vcc
	v_cmp_gt_i32_e32 vcc, 1, v73
	v_sub_u32_e32 v73, 0, v73
	v_cvt_f32_u32_e32 v73, v73
	v_mul_f32_e32 v73, v170, v73
	v_exp_f32_e32 v73, v73
	s_nop 0
	v_cndmask_b32_e32 v73, 0, v73, vcc
	v_add_f32_e32 v73, v74, v73
	v_sub_u32_e32 v74, v171, v100
	v_cvt_f32_u32_e32 v75, v74
	v_cmp_lt_i32_e32 vcc, -1, v74
	v_mul_f32_e32 v73, v73, v76
	v_mul_f32_e32 v75, v169, v75
	v_exp_f32_e32 v75, v75
	s_nop 0
	v_cndmask_b32_e32 v75, 0, v75, vcc
	v_cmp_gt_i32_e32 vcc, 1, v74
	v_sub_u32_e32 v74, 0, v74
	v_cvt_f32_u32_e32 v74, v74
	v_mul_f32_e32 v74, v170, v74
	v_exp_f32_e32 v74, v74
	s_nop 0
	v_cndmask_b32_e32 v74, 0, v74, vcc
	v_add_f32_e32 v74, v75, v74
	v_cvt_f32_u32_e32 v75, v70
	v_cmp_lt_i32_e32 vcc, -1, v70
	v_mul_f32_e32 v74, v74, v77
	v_mul_f32_e32 v75, v169, v75
	v_exp_f32_e32 v75, v75
	s_nop 0
	v_cndmask_b32_e32 v75, 0, v75, vcc
	v_cmp_gt_i32_e32 vcc, 1, v70
	v_sub_u32_e32 v70, 0, v70
	v_cvt_f32_u32_e32 v70, v70
	v_mul_f32_e32 v70, v170, v70
	v_exp_f32_e32 v70, v70
	s_nop 0
	v_cndmask_b32_e32 v70, 0, v70, vcc
	v_add_f32_e32 v70, v75, v70
	v_mul_f32_e32 v66, v70, v66
	v_sub_u32_e32 v70, v171, v106
	v_cvt_f32_u32_e32 v75, v70
	v_cmp_lt_i32_e32 vcc, -1, v70
	v_cvt_pk_bf16_f32 v106, v71, v72
	v_mul_f32_e32 v75, v169, v75
	v_exp_f32_e32 v75, v75
	s_nop 0
	v_cndmask_b32_e32 v75, 0, v75, vcc
	v_cmp_gt_i32_e32 vcc, 1, v70
	v_sub_u32_e32 v70, 0, v70
	v_cvt_f32_u32_e32 v70, v70
	v_mul_f32_e32 v70, v170, v70
	v_exp_f32_e32 v70, v70
	s_nop 0
	v_cndmask_b32_e32 v70, 0, v70, vcc
	v_add_f32_e32 v70, v75, v70
	v_mul_f32_e32 v67, v70, v67
	v_sub_u32_e32 v70, v171, v107
	v_cvt_f32_u32_e32 v75, v70
	v_cmp_lt_i32_e32 vcc, -1, v70
	v_cvt_pk_bf16_f32 v107, v73, v74
	v_mul_f32_e32 v75, v169, v75
	v_exp_f32_e32 v75, v75
	s_nop 0
	v_cndmask_b32_e32 v75, 0, v75, vcc
	v_cmp_gt_i32_e32 vcc, 1, v70
	v_sub_u32_e32 v70, 0, v70
	v_cvt_f32_u32_e32 v70, v70
	v_mul_f32_e32 v70, v170, v70
	v_exp_f32_e32 v70, v70
	s_nop 0
	v_cndmask_b32_e32 v70, 0, v70, vcc
	v_add_f32_e32 v70, v75, v70
	v_mul_f32_e32 v68, v70, v68
	v_sub_u32_e32 v70, v171, v108
	v_cvt_f32_u32_e32 v75, v70
	v_cmp_lt_i32_e32 vcc, -1, v70
	v_cvt_pk_bf16_f32 v108, v66, v67
	v_mul_f32_e32 v75, v169, v75
	v_exp_f32_e32 v75, v75
	s_nop 0
	v_cndmask_b32_e32 v75, 0, v75, vcc
	v_cmp_gt_i32_e32 vcc, 1, v70
	v_sub_u32_e32 v70, 0, v70
	v_cvt_f32_u32_e32 v70, v70
	v_mul_f32_e32 v70, v170, v70
	v_exp_f32_e32 v70, v70
	s_nop 0
	v_cndmask_b32_e32 v70, 0, v70, vcc
	v_add_f32_e32 v70, v75, v70
	v_mul_f32_e32 v69, v70, v69
	v_cvt_pk_bf16_f32 v109, v68, v69
	v_mfma_f32_16x16x32_bf16 v[66:69], v[62:65], v[102:105], 0
	v_mfma_f32_16x16x32_bf16 v[62:65], v[62:65], v[106:109], 0
	v_mfma_f32_16x16x32_bf16 v[70:73], v[58:61], v[102:105], 0
	v_mfma_f32_16x16x32_bf16 v[74:77], v[58:61], v[106:109], 0
	v_mfma_f32_16x16x32_bf16 v[98:101], v[54:57], v[106:109], 0
	v_or_b32_e32 v55, 32, v0
	v_or_b32_e32 v54, 36, v0
	v_mfma_f32_16x16x32_bf16 v[102:105], v[50:53], v[102:105], 0
	v_mfma_f32_16x16x32_bf16 v[106:109], v[50:53], v[106:109], 0
	v_mfma_f32_16x16x32_bf16 v[50:53], v[46:49], v[30:33], 0
	v_mfma_f32_16x16x32_bf16 v[46:49], v[46:49], v[26:29], 0
	v_mfma_f32_16x16x32_bf16 v[50:53], v[42:45], v[22:25], v[50:53]
	v_mfma_f32_16x16x32_bf16 v[42:45], v[42:45], v[18:21], v[46:49]
	v_mfma_f32_16x16x32_bf16 v[46:49], v[38:41], v[30:33], 0
	v_mfma_f32_16x16x32_bf16 v[38:41], v[38:41], v[26:29], 0
	v_mfma_f32_16x16x32_bf16 v[46:49], v[34:37], v[22:25], v[46:49]
	v_mfma_f32_16x16x32_bf16 v[34:37], v[34:37], v[18:21], v[38:41]
	s_nop 5
	v_sub_u32_e32 v38, v168, v55
	v_cvt_f32_u32_e32 v39, v38
	v_cmp_lt_i32_e32 vcc, -1, v38
	v_mul_f32_e32 v39, v169, v39
	v_exp_f32_e32 v39, v39
	s_nop 0
	v_cndmask_b32_e32 v39, 0, v39, vcc
	v_cmp_gt_i32_e32 vcc, 1, v38
	v_sub_u32_e32 v38, 0, v38
	v_cvt_f32_u32_e32 v38, v38
	v_mul_f32_e32 v38, v170, v38
	v_exp_f32_e32 v38, v38
	s_nop 0
	v_cndmask_b32_e32 v38, 0, v38, vcc
	v_add_f32_e32 v38, v39, v38
	v_mul_f32_e32 v38, v38, v50
	v_or_b32_e32 v50, 33, v0
	v_sub_u32_e32 v39, v168, v50
	v_cvt_f32_u32_e32 v40, v39
	v_cmp_lt_i32_e32 vcc, -1, v39
	v_mul_f32_e32 v40, v169, v40
	v_exp_f32_e32 v40, v40
	s_nop 0
	v_cndmask_b32_e32 v40, 0, v40, vcc
	v_cmp_gt_i32_e32 vcc, 1, v39
	v_sub_u32_e32 v39, 0, v39
	v_cvt_f32_u32_e32 v39, v39
	v_mul_f32_e32 v39, v170, v39
	v_exp_f32_e32 v39, v39
	s_nop 0
	v_cndmask_b32_e32 v39, 0, v39, vcc
	v_add_f32_e32 v39, v40, v39
	v_mul_f32_e32 v39, v39, v51
	v_or_b32_e32 v51, 34, v0
	v_sub_u32_e32 v40, v168, v51
	v_cvt_f32_u32_e32 v41, v40
	v_cmp_lt_i32_e32 vcc, -1, v40
	v_cvt_pk_bf16_f32 v38, v38, v39
	v_mul_f32_e32 v41, v169, v41
	v_exp_f32_e32 v41, v41
	s_nop 0
	v_cndmask_b32_e32 v41, 0, v41, vcc
	v_cmp_gt_i32_e32 vcc, 1, v40
	v_sub_u32_e32 v40, 0, v40
	v_cvt_f32_u32_e32 v40, v40
	v_mul_f32_e32 v40, v170, v40
	v_exp_f32_e32 v40, v40
	s_nop 0
	v_cndmask_b32_e32 v40, 0, v40, vcc
	v_add_f32_e32 v40, v41, v40
	v_mul_f32_e32 v40, v40, v52
	v_or_b32_e32 v52, 35, v0
	v_sub_u32_e32 v41, v168, v52
	v_cvt_f32_u32_e32 v56, v41
	v_cmp_lt_i32_e32 vcc, -1, v41
	v_mul_f32_e32 v56, v169, v56
	v_exp_f32_e32 v56, v56
	s_nop 0
	v_cndmask_b32_e32 v56, 0, v56, vcc
	v_cmp_gt_i32_e32 vcc, 1, v41
	v_sub_u32_e32 v41, 0, v41
	v_cvt_f32_u32_e32 v41, v41
	v_mul_f32_e32 v41, v170, v41
	v_exp_f32_e32 v41, v41
	s_nop 0
	v_cndmask_b32_e32 v41, 0, v41, vcc
	v_add_f32_e32 v41, v56, v41
	v_mul_f32_e32 v41, v41, v53
	v_sub_u32_e32 v53, v168, v54
	v_cvt_f32_u32_e32 v56, v53
	v_cmp_lt_i32_e32 vcc, -1, v53
	v_cvt_pk_bf16_f32 v39, v40, v41
	v_mul_f32_e32 v56, v169, v56
	v_exp_f32_e32 v56, v56
	s_nop 0
	v_cndmask_b32_e32 v56, 0, v56, vcc
	v_cmp_gt_i32_e32 vcc, 1, v53
	v_sub_u32_e32 v53, 0, v53
	v_cvt_f32_u32_e32 v53, v53
	v_mul_f32_e32 v53, v170, v53
	v_exp_f32_e32 v53, v53
	s_nop 0
	v_cndmask_b32_e32 v53, 0, v53, vcc
	v_add_f32_e32 v53, v56, v53
	v_mul_f32_e32 v46, v53, v46
	v_or_b32_e32 v53, 37, v0
	v_sub_u32_e32 v56, v168, v53
	v_cvt_f32_u32_e32 v57, v56
	v_cmp_lt_i32_e32 vcc, -1, v56
	v_mul_f32_e32 v57, v169, v57
	v_exp_f32_e32 v57, v57
	s_nop 0
	v_cndmask_b32_e32 v57, 0, v57, vcc
	v_cmp_gt_i32_e32 vcc, 1, v56
	v_sub_u32_e32 v56, 0, v56
	v_cvt_f32_u32_e32 v56, v56
	v_mul_f32_e32 v56, v170, v56
	v_exp_f32_e32 v56, v56
	s_nop 0
	v_cndmask_b32_e32 v56, 0, v56, vcc
	v_add_f32_e32 v56, v57, v56
	v_mul_f32_e32 v47, v56, v47
	v_or_b32_e32 v56, 38, v0
	v_sub_u32_e32 v57, v168, v56
	v_cvt_f32_u32_e32 v58, v57
	v_cmp_lt_i32_e32 vcc, -1, v57
	v_cvt_pk_bf16_f32 v40, v46, v47
	v_sub_u32_e32 v46, v171, v55
	v_mul_f32_e32 v58, v169, v58
	v_exp_f32_e32 v58, v58
	v_cvt_f32_u32_e32 v47, v46
	v_cndmask_b32_e32 v58, 0, v58, vcc
	v_cmp_gt_i32_e32 vcc, 1, v57
	v_sub_u32_e32 v57, 0, v57
	v_cvt_f32_u32_e32 v57, v57
	v_mul_f32_e32 v47, v169, v47
	v_exp_f32_e32 v47, v47
	v_mul_f32_e32 v57, v170, v57
	v_exp_f32_e32 v57, v57
	s_nop 0
	v_cndmask_b32_e32 v57, 0, v57, vcc
	v_add_f32_e32 v57, v58, v57
	v_mul_f32_e32 v48, v57, v48
	v_or_b32_e32 v57, 39, v0
	v_sub_u32_e32 v58, v168, v57
	v_cvt_f32_u32_e32 v59, v58
	v_cmp_lt_i32_e32 vcc, -1, v58
	v_mul_f32_e32 v59, v169, v59
	v_exp_f32_e32 v59, v59
	s_nop 0
	v_cndmask_b32_e32 v59, 0, v59, vcc
	v_cmp_gt_i32_e32 vcc, 1, v58
	v_sub_u32_e32 v58, 0, v58
	v_cvt_f32_u32_e32 v58, v58
	v_mul_f32_e32 v58, v170, v58
	v_exp_f32_e32 v58, v58
	s_nop 0
	v_cndmask_b32_e32 v58, 0, v58, vcc
	v_cmp_lt_i32_e32 vcc, -1, v46
	v_add_f32_e32 v58, v59, v58
	v_mul_f32_e32 v49, v58, v49
	v_cndmask_b32_e32 v47, 0, v47, vcc
	v_cmp_gt_i32_e32 vcc, 1, v46
	v_sub_u32_e32 v46, 0, v46
	v_cvt_f32_u32_e32 v46, v46
	v_cvt_pk_bf16_f32 v41, v48, v49
	v_mul_f32_e32 v46, v170, v46
	v_exp_f32_e32 v46, v46
	v_mfma_f32_16x16x32_bf16 v[58:61], v[10:13], v[38:41], v[70:73]
	v_cndmask_b32_e32 v46, 0, v46, vcc
	v_add_f32_e32 v46, v47, v46
	v_mul_f32_e32 v42, v46, v42
	v_sub_u32_e32 v46, v171, v50
	v_cvt_f32_u32_e32 v47, v46
	v_cmp_lt_i32_e32 vcc, -1, v46
	v_mul_f32_e32 v47, v169, v47
	v_exp_f32_e32 v47, v47
	s_nop 0
	v_cndmask_b32_e32 v47, 0, v47, vcc
	v_cmp_gt_i32_e32 vcc, 1, v46
	v_sub_u32_e32 v46, 0, v46
	v_cvt_f32_u32_e32 v46, v46
	v_mul_f32_e32 v46, v170, v46
	v_exp_f32_e32 v46, v46
	s_nop 0
	v_cndmask_b32_e32 v46, 0, v46, vcc
	v_add_f32_e32 v46, v47, v46
	v_mul_f32_e32 v43, v46, v43
	v_sub_u32_e32 v46, v171, v51
	v_cvt_f32_u32_e32 v47, v46
	v_cmp_lt_i32_e32 vcc, -1, v46
	v_mul_f32_e32 v47, v169, v47
	v_exp_f32_e32 v47, v47
	s_nop 0
	v_cndmask_b32_e32 v47, 0, v47, vcc
	v_cmp_gt_i32_e32 vcc, 1, v46
	v_sub_u32_e32 v46, 0, v46
	v_cvt_f32_u32_e32 v46, v46
	v_mul_f32_e32 v46, v170, v46
	v_exp_f32_e32 v46, v46
	s_nop 0
	v_cndmask_b32_e32 v46, 0, v46, vcc
	v_add_f32_e32 v46, v47, v46
	v_mul_f32_e32 v44, v46, v44
	v_sub_u32_e32 v46, v171, v52
	v_cvt_f32_u32_e32 v47, v46
	v_cmp_lt_i32_e32 vcc, -1, v46
	v_mul_f32_e32 v47, v169, v47
	v_exp_f32_e32 v47, v47
	s_nop 0
	v_cndmask_b32_e32 v47, 0, v47, vcc
	v_cmp_gt_i32_e32 vcc, 1, v46
	v_sub_u32_e32 v46, 0, v46
	v_cvt_f32_u32_e32 v46, v46
	v_mul_f32_e32 v46, v170, v46
	v_exp_f32_e32 v46, v46
	s_nop 0
	v_cndmask_b32_e32 v46, 0, v46, vcc
	v_add_f32_e32 v46, v47, v46
	v_mul_f32_e32 v45, v46, v45
	v_sub_u32_e32 v46, v171, v54
	v_cvt_f32_u32_e32 v47, v46
	v_cmp_lt_i32_e32 vcc, -1, v46
	v_mul_f32_e32 v47, v169, v47
	v_exp_f32_e32 v47, v47
	s_nop 0
	v_cndmask_b32_e32 v47, 0, v47, vcc
	v_cmp_gt_i32_e32 vcc, 1, v46
	v_sub_u32_e32 v46, 0, v46
	v_cvt_f32_u32_e32 v46, v46
	v_mul_f32_e32 v46, v170, v46
	v_exp_f32_e32 v46, v46
	s_nop 0
	v_cndmask_b32_e32 v46, 0, v46, vcc
	v_add_f32_e32 v46, v47, v46
	v_mul_f32_e32 v46, v46, v34
	v_sub_u32_e32 v34, v171, v53
	v_cvt_f32_u32_e32 v47, v34
	v_cmp_lt_i32_e32 vcc, -1, v34
	v_mfma_f32_16x16x32_bf16 v[50:53], v[14:17], v[38:41], v[66:69]
	v_mul_f32_e32 v47, v169, v47
	v_exp_f32_e32 v47, v47
	v_mfma_f32_16x16x32_bf16 v[66:69], v[6:9], v[38:41], v[78:81]
	v_cndmask_b32_e32 v47, 0, v47, vcc
	v_cmp_gt_i32_e32 vcc, 1, v34
	v_sub_u32_e32 v34, 0, v34
	v_cvt_f32_u32_e32 v34, v34
	v_mul_f32_e32 v34, v170, v34
	v_exp_f32_e32 v34, v34
	s_nop 0
	v_cndmask_b32_e32 v34, 0, v34, vcc
	v_add_f32_e32 v34, v47, v34
	v_mul_f32_e32 v47, v34, v35
	v_sub_u32_e32 v34, v171, v56
	v_cvt_f32_u32_e32 v35, v34
	v_cmp_lt_i32_e32 vcc, -1, v34
	v_mul_f32_e32 v35, v169, v35
	v_exp_f32_e32 v35, v35
	s_nop 0
	v_cndmask_b32_e32 v35, 0, v35, vcc
	v_cmp_gt_i32_e32 vcc, 1, v34
	v_sub_u32_e32 v34, 0, v34
	v_cvt_f32_u32_e32 v34, v34
	v_mul_f32_e32 v34, v170, v34
	v_exp_f32_e32 v34, v34
	s_nop 0
	v_cndmask_b32_e32 v34, 0, v34, vcc
	v_add_f32_e32 v34, v35, v34
	v_mul_f32_e32 v48, v34, v36
	v_sub_u32_e32 v34, v171, v57
	v_cvt_f32_u32_e32 v35, v34
	v_cmp_lt_i32_e32 vcc, -1, v34
	v_cvt_pk_bf16_f32 v36, v46, v47
	v_mul_f32_e32 v35, v169, v35
	v_exp_f32_e32 v35, v35
	s_nop 0
	v_cndmask_b32_e32 v35, 0, v35, vcc
	v_cmp_gt_i32_e32 vcc, 1, v34
	v_sub_u32_e32 v34, 0, v34
	v_cvt_f32_u32_e32 v34, v34
	v_mul_f32_e32 v34, v170, v34
	v_exp_f32_e32 v34, v34
	s_nop 0
	v_cndmask_b32_e32 v34, 0, v34, vcc
	v_add_f32_e32 v34, v35, v34
	v_mul_f32_e32 v37, v34, v37
	v_cvt_pk_bf16_f32 v34, v42, v43
	v_cvt_pk_bf16_f32 v35, v44, v45
	v_cvt_pk_bf16_f32 v37, v48, v37
	s_nop 1
	v_mfma_f32_16x16x32_bf16 v[54:57], v[14:17], v[34:37], v[62:65]
	v_mfma_f32_16x16x32_bf16 v[62:65], v[10:13], v[34:37], v[74:77]
	v_mfma_f32_16x16x32_bf16 v[70:73], v[6:9], v[34:37], v[98:101]
	v_mfma_f32_16x16x32_bf16 v[74:77], v[2:5], v[38:41], v[102:105]
	v_mfma_f32_16x16x32_bf16 v[78:81], v[2:5], v[34:37], v[106:109]
	global_load_dwordx4 v[34:37], v[112:113], off offset:192
	global_load_dwordx4 v[38:41], v[152:153], off offset:192
	global_load_dwordx4 v[42:45], v[154:155], off offset:192
	global_load_dwordx4 v[98:101], v[112:113], off offset:128
	global_load_dwordx4 v[102:105], v[152:153], off offset:128
	global_load_dwordx4 v[106:109], v[154:155], off offset:128
	global_load_dwordx4 v[46:49], v[110:111], off offset:192
	s_nop 0
	global_load_dwordx4 v[110:113], v[110:111], off offset:128
	s_nop 0
	global_load_dwordx4 v[2:5], v[156:157], off offset:192
	global_load_dwordx4 v[6:9], v[156:157], off offset:128
	global_load_dwordx4 v[10:13], v[156:157], off offset:64
	global_load_dwordx4 v[14:17], v[156:157], off
	v_mul_lo_u32 v154, v159, 12
	v_ashrrev_i32_e32 v155, 31, v154
	v_lshl_add_u64 v[152:153], v[154:155], 0, v[130:131]
	v_add_u32_e32 v154, 6, v154
	v_ashrrev_i32_e32 v155, 31, v154
	v_lshl_add_u64 v[130:131], v[154:155], 0, v[130:131]
	v_lshlrev_b64 v[152:153], 13, v[152:153]
	v_lshlrev_b32_e32 v156, 7, v158
	v_lshlrev_b64 v[130:131], 13, v[130:131]
	v_lshl_add_u64 v[160:161], v[132:133], 0, v[152:153]
	v_mov_b32_e32 v157, v1
	v_or_b32_e32 v172, 0x1000, v156
	v_or_b32_e32 v174, 0x1800, v156
	v_lshl_add_u64 v[130:131], v[132:133], 0, v[130:131]
	v_lshl_add_u64 v[152:153], v[160:161], 0, v[156:157]
	v_lshl_add_u64 v[158:159], v[160:161], 0, v[172:173]
	v_lshl_add_u64 v[162:163], v[160:161], 0, v[174:175]
	v_lshl_add_u64 v[154:155], v[130:131], 0, v[156:157]
	v_lshl_add_u64 v[156:157], v[130:131], 0, v[172:173]
	v_lshl_add_u64 v[160:161], v[130:131], 0, v[174:175]
	v_mfma_f32_16x16x32_bf16 v[130:133], v[126:129], v[30:33], 0
	v_or_b32_e32 v173, 64, v0
	v_or_b32_e32 v172, 0x44, v0
	s_waitcnt vmcnt(0)
	v_mfma_f32_16x16x32_bf16 v[126:129], v[126:129], v[26:29], 0
	v_mfma_f32_16x16x32_bf16 v[130:133], v[122:125], v[22:25], v[130:133]
	v_mfma_f32_16x16x32_bf16 v[122:125], v[122:125], v[18:21], v[126:129]
	v_mfma_f32_16x16x32_bf16 v[126:129], v[118:121], v[30:33], 0
	v_mfma_f32_16x16x32_bf16 v[118:121], v[118:121], v[26:29], 0
	v_mfma_f32_16x16x32_bf16 v[126:129], v[114:117], v[22:25], v[126:129]
	v_mfma_f32_16x16x32_bf16 v[114:117], v[114:117], v[18:21], v[118:121]
	s_nop 5
	v_sub_u32_e32 v118, v168, v173
	v_cvt_f32_u32_e32 v119, v118
	v_cmp_lt_i32_e32 vcc, -1, v118
	v_mul_f32_e32 v119, v169, v119
	v_exp_f32_e32 v119, v119
	s_nop 0
	v_cndmask_b32_e32 v119, 0, v119, vcc
	v_cmp_gt_i32_e32 vcc, 1, v118
	v_sub_u32_e32 v118, 0, v118
	v_cvt_f32_u32_e32 v118, v118
	v_mul_f32_e32 v118, v170, v118
	v_exp_f32_e32 v118, v118
	s_nop 0
	v_cndmask_b32_e32 v118, 0, v118, vcc
	v_add_f32_e32 v118, v119, v118
	v_mul_f32_e32 v118, v118, v130
	v_or_b32_e32 v130, 0x41, v0
	v_sub_u32_e32 v119, v168, v130
	v_cvt_f32_u32_e32 v120, v119
	v_cmp_lt_i32_e32 vcc, -1, v119
	v_mul_f32_e32 v120, v169, v120
	v_exp_f32_e32 v120, v120
	s_nop 0
	v_cndmask_b32_e32 v120, 0, v120, vcc
	v_cmp_gt_i32_e32 vcc, 1, v119
	v_sub_u32_e32 v119, 0, v119
	v_cvt_f32_u32_e32 v119, v119
	v_mul_f32_e32 v119, v170, v119
	v_exp_f32_e32 v119, v119
	s_nop 0
	v_cndmask_b32_e32 v119, 0, v119, vcc
	v_add_f32_e32 v119, v120, v119
	v_mul_f32_e32 v119, v119, v131
	v_or_b32_e32 v131, 0x42, v0
	v_sub_u32_e32 v120, v168, v131
	v_cvt_f32_u32_e32 v121, v120
	v_cmp_lt_i32_e32 vcc, -1, v120
	v_cvt_pk_bf16_f32 v118, v118, v119
	v_mul_f32_e32 v121, v169, v121
	v_exp_f32_e32 v121, v121
	s_nop 0
	v_cndmask_b32_e32 v121, 0, v121, vcc
	v_cmp_gt_i32_e32 vcc, 1, v120
	v_sub_u32_e32 v120, 0, v120
	v_cvt_f32_u32_e32 v120, v120
	v_mul_f32_e32 v120, v170, v120
	v_exp_f32_e32 v120, v120
	s_nop 0
	v_cndmask_b32_e32 v120, 0, v120, vcc
	v_add_f32_e32 v120, v121, v120
	v_mul_f32_e32 v120, v120, v132
	v_or_b32_e32 v132, 0x43, v0
	v_sub_u32_e32 v121, v168, v132
	v_cvt_f32_u32_e32 v174, v121
	v_cmp_lt_i32_e32 vcc, -1, v121
	v_mul_f32_e32 v174, v169, v174
	v_exp_f32_e32 v174, v174
	s_nop 0
	v_cndmask_b32_e32 v174, 0, v174, vcc
	v_cmp_gt_i32_e32 vcc, 1, v121
	v_sub_u32_e32 v121, 0, v121
	v_cvt_f32_u32_e32 v121, v121
	v_mul_f32_e32 v121, v170, v121
	v_exp_f32_e32 v121, v121
	s_nop 0
	v_cndmask_b32_e32 v121, 0, v121, vcc
	v_add_f32_e32 v121, v174, v121
	v_mul_f32_e32 v121, v121, v133
	v_sub_u32_e32 v133, v168, v172
	v_cvt_f32_u32_e32 v174, v133
	v_cmp_lt_i32_e32 vcc, -1, v133
	v_cvt_pk_bf16_f32 v119, v120, v121
	v_mul_f32_e32 v174, v169, v174
	v_exp_f32_e32 v174, v174
	s_nop 0
	v_cndmask_b32_e32 v174, 0, v174, vcc
	v_cmp_gt_i32_e32 vcc, 1, v133
	v_sub_u32_e32 v133, 0, v133
	v_cvt_f32_u32_e32 v133, v133
	v_mul_f32_e32 v133, v170, v133
	v_exp_f32_e32 v133, v133
	s_nop 0
	v_cndmask_b32_e32 v133, 0, v133, vcc
	v_add_f32_e32 v133, v174, v133
	v_mul_f32_e32 v133, v133, v126
	v_or_b32_e32 v126, 0x45, v0
	v_sub_u32_e32 v174, v168, v126
	v_cvt_f32_u32_e32 v175, v174
	v_cmp_lt_i32_e32 vcc, -1, v174
	v_mul_f32_e32 v175, v169, v175
	v_exp_f32_e32 v175, v175
	s_nop 0
	v_cndmask_b32_e32 v175, 0, v175, vcc
	v_cmp_gt_i32_e32 vcc, 1, v174
	v_sub_u32_e32 v174, 0, v174
	v_cvt_f32_u32_e32 v174, v174
	v_mul_f32_e32 v174, v170, v174
	v_exp_f32_e32 v174, v174
	s_nop 0
	v_cndmask_b32_e32 v174, 0, v174, vcc
	v_add_f32_e32 v174, v175, v174
	v_mul_f32_e32 v174, v174, v127
	v_or_b32_e32 v127, 0x46, v0
	v_sub_u32_e32 v175, v168, v127
	v_cvt_f32_u32_e32 v176, v175
	v_cmp_lt_i32_e32 vcc, -1, v175
	v_cvt_pk_bf16_f32 v120, v133, v174
	v_mul_f32_e32 v176, v169, v176
	v_exp_f32_e32 v176, v176
	s_nop 0
	v_cndmask_b32_e32 v176, 0, v176, vcc
	v_cmp_gt_i32_e32 vcc, 1, v175
	v_sub_u32_e32 v175, 0, v175
	v_cvt_f32_u32_e32 v175, v175
	v_mul_f32_e32 v175, v170, v175
	v_exp_f32_e32 v175, v175
	s_nop 0
	v_cndmask_b32_e32 v175, 0, v175, vcc
	v_add_f32_e32 v175, v176, v175
	v_mul_f32_e32 v175, v175, v128
	v_or_b32_e32 v128, 0x47, v0
	v_sub_u32_e32 v176, v168, v128
	v_cvt_f32_u32_e32 v177, v176
	v_cmp_lt_i32_e32 vcc, -1, v176
	v_mul_f32_e32 v177, v169, v177
	v_exp_f32_e32 v177, v177
	s_nop 0
	v_cndmask_b32_e32 v177, 0, v177, vcc
	v_cmp_gt_i32_e32 vcc, 1, v176
	v_sub_u32_e32 v176, 0, v176
	v_cvt_f32_u32_e32 v176, v176
	v_mul_f32_e32 v176, v170, v176
	v_exp_f32_e32 v176, v176
	s_nop 0
	v_cndmask_b32_e32 v176, 0, v176, vcc
	v_add_f32_e32 v176, v177, v176
	v_mul_f32_e32 v129, v176, v129
	v_cvt_pk_bf16_f32 v121, v175, v129
	v_sub_u32_e32 v129, v171, v173
	v_cvt_f32_u32_e32 v133, v129
	v_cmp_lt_i32_e32 vcc, -1, v129
	v_mfma_f32_16x16x32_bf16 v[74:77], v[98:101], v[118:121], v[74:77]
	v_mul_f32_e32 v133, v169, v133
	v_exp_f32_e32 v133, v133
	v_mfma_f32_16x16x32_bf16 v[66:69], v[102:105], v[118:121], v[66:69]
	v_cndmask_b32_e32 v133, 0, v133, vcc
	v_cmp_gt_i32_e32 vcc, 1, v129
	v_sub_u32_e32 v129, 0, v129
	v_cvt_f32_u32_e32 v129, v129
	v_mfma_f32_16x16x32_bf16 v[58:61], v[106:109], v[118:121], v[58:61]
	v_mul_f32_e32 v129, v170, v129
	v_exp_f32_e32 v129, v129
	v_mfma_f32_16x16x32_bf16 v[50:53], v[110:113], v[118:121], v[50:53]
	v_cndmask_b32_e32 v129, 0, v129, vcc
	v_add_f32_e32 v129, v133, v129
	v_mul_f32_e32 v122, v129, v122
	v_sub_u32_e32 v129, v171, v130
	v_cvt_f32_u32_e32 v130, v129
	v_cmp_lt_i32_e32 vcc, -1, v129
	v_mul_f32_e32 v130, v169, v130
	v_exp_f32_e32 v130, v130
	s_nop 0
	v_cndmask_b32_e32 v130, 0, v130, vcc
	v_cmp_gt_i32_e32 vcc, 1, v129
	v_sub_u32_e32 v129, 0, v129
	v_cvt_f32_u32_e32 v129, v129
	v_mul_f32_e32 v129, v170, v129
	v_exp_f32_e32 v129, v129
	s_nop 0
	v_cndmask_b32_e32 v129, 0, v129, vcc
	v_add_f32_e32 v129, v130, v129
	v_mul_f32_e32 v123, v129, v123
	v_sub_u32_e32 v129, v171, v131
	v_cvt_f32_u32_e32 v130, v129
	v_cmp_lt_i32_e32 vcc, -1, v129
	v_mul_f32_e32 v130, v169, v130
	v_exp_f32_e32 v130, v130
	s_nop 0
	v_cndmask_b32_e32 v130, 0, v130, vcc
	v_cmp_gt_i32_e32 vcc, 1, v129
	v_sub_u32_e32 v129, 0, v129
	v_cvt_f32_u32_e32 v129, v129
	v_mul_f32_e32 v129, v170, v129
	v_exp_f32_e32 v129, v129
	s_nop 0
	v_cndmask_b32_e32 v129, 0, v129, vcc
	v_add_f32_e32 v129, v130, v129
	v_mul_f32_e32 v124, v129, v124
	v_sub_u32_e32 v129, v171, v132
	v_cvt_f32_u32_e32 v130, v129
	v_cmp_lt_i32_e32 vcc, -1, v129
	v_mul_f32_e32 v130, v169, v130
	v_exp_f32_e32 v130, v130
	s_nop 0
	v_cndmask_b32_e32 v130, 0, v130, vcc
	v_cmp_gt_i32_e32 vcc, 1, v129
	v_sub_u32_e32 v129, 0, v129
	v_cvt_f32_u32_e32 v129, v129
	v_mul_f32_e32 v129, v170, v129
	v_exp_f32_e32 v129, v129
	s_nop 0
	v_cndmask_b32_e32 v129, 0, v129, vcc
	v_add_f32_e32 v129, v130, v129
	v_mul_f32_e32 v125, v129, v125
	v_sub_u32_e32 v129, v171, v172
	v_cvt_f32_u32_e32 v130, v129
	v_cmp_lt_i32_e32 vcc, -1, v129
	v_mul_f32_e32 v130, v169, v130
	v_exp_f32_e32 v130, v130
	s_nop 0
	v_cndmask_b32_e32 v130, 0, v130, vcc
	v_cmp_gt_i32_e32 vcc, 1, v129
	v_sub_u32_e32 v129, 0, v129
	v_cvt_f32_u32_e32 v129, v129
	v_mul_f32_e32 v129, v170, v129
	v_exp_f32_e32 v129, v129
	s_nop 0
	v_cndmask_b32_e32 v129, 0, v129, vcc
	v_add_f32_e32 v129, v130, v129
	v_mul_f32_e32 v129, v129, v114
	v_sub_u32_e32 v114, v171, v126
	v_cvt_f32_u32_e32 v126, v114
	v_cmp_lt_i32_e32 vcc, -1, v114
	v_mul_f32_e32 v126, v169, v126
	v_exp_f32_e32 v126, v126
	s_nop 0
	v_cndmask_b32_e32 v126, 0, v126, vcc
	v_cmp_gt_i32_e32 vcc, 1, v114
	v_sub_u32_e32 v114, 0, v114
	v_cvt_f32_u32_e32 v114, v114
	v_mul_f32_e32 v114, v170, v114
	v_exp_f32_e32 v114, v114
	s_nop 0
	v_cndmask_b32_e32 v114, 0, v114, vcc
	v_add_f32_e32 v114, v126, v114
	v_mul_f32_e32 v126, v114, v115
	v_sub_u32_e32 v114, v171, v127
	v_cvt_f32_u32_e32 v115, v114
	v_cmp_lt_i32_e32 vcc, -1, v114
	v_mul_f32_e32 v115, v169, v115
	v_exp_f32_e32 v115, v115
	s_nop 0
	v_cndmask_b32_e32 v115, 0, v115, vcc
	v_cmp_gt_i32_e32 vcc, 1, v114
	v_sub_u32_e32 v114, 0, v114
	v_cvt_f32_u32_e32 v114, v114
	v_mul_f32_e32 v114, v170, v114
	v_exp_f32_e32 v114, v114
	s_nop 0
	v_cndmask_b32_e32 v114, 0, v114, vcc
	v_add_f32_e32 v114, v115, v114
	v_mul_f32_e32 v127, v114, v116
	v_sub_u32_e32 v114, v171, v128
	v_cvt_f32_u32_e32 v115, v114
	v_cmp_lt_i32_e32 vcc, -1, v114
	v_cvt_pk_bf16_f32 v116, v129, v126
	v_mul_f32_e32 v115, v169, v115
	v_exp_f32_e32 v115, v115
	s_nop 0
	v_cndmask_b32_e32 v115, 0, v115, vcc
	v_cmp_gt_i32_e32 vcc, 1, v114
	v_sub_u32_e32 v114, 0, v114
	v_cvt_f32_u32_e32 v114, v114
	v_mul_f32_e32 v114, v170, v114
	v_exp_f32_e32 v114, v114
	s_nop 0
	v_cndmask_b32_e32 v114, 0, v114, vcc
	v_add_f32_e32 v114, v115, v114
	v_mul_f32_e32 v117, v114, v117
	v_cvt_pk_bf16_f32 v114, v122, v123
	v_cvt_pk_bf16_f32 v115, v124, v125
	v_cvt_pk_bf16_f32 v117, v127, v117
	s_nop 1
	v_mfma_f32_16x16x32_bf16 v[78:81], v[98:101], v[114:117], v[78:81]
	v_mfma_f32_16x16x32_bf16 v[98:101], v[94:97], v[30:33], 0
	v_mfma_f32_16x16x32_bf16 v[94:97], v[94:97], v[26:29], 0
	v_mfma_f32_16x16x32_bf16 v[98:101], v[90:93], v[22:25], v[98:101]
	v_mfma_f32_16x16x32_bf16 v[90:93], v[90:93], v[18:21], v[94:97]
	v_mfma_f32_16x16x32_bf16 v[94:97], v[86:89], v[30:33], 0
	v_mfma_f32_16x16x32_bf16 v[86:89], v[86:89], v[26:29], 0
	v_mfma_f32_16x16x32_bf16 v[70:73], v[102:105], v[114:117], v[70:73]
	v_or_b32_e32 v103, 0x60, v0
	v_or_b32_e32 v102, 0x64, v0
	v_mfma_f32_16x16x32_bf16 v[94:97], v[82:85], v[22:25], v[94:97]
	v_mfma_f32_16x16x32_bf16 v[82:85], v[82:85], v[18:21], v[86:89]
	s_nop 2
	v_sub_u32_e32 v86, v168, v103
	v_cvt_f32_u32_e32 v87, v86
	v_cmp_lt_i32_e32 vcc, -1, v86
	v_mfma_f32_16x16x32_bf16 v[62:65], v[106:109], v[114:117], v[62:65]
	v_mul_f32_e32 v87, v169, v87
	v_exp_f32_e32 v87, v87
	v_mfma_f32_16x16x32_bf16 v[54:57], v[110:113], v[114:117], v[54:57]
	v_cndmask_b32_e32 v87, 0, v87, vcc
	v_cmp_gt_i32_e32 vcc, 1, v86
	v_sub_u32_e32 v86, 0, v86
	v_cvt_f32_u32_e32 v86, v86
	v_mul_f32_e32 v86, v170, v86
	v_exp_f32_e32 v86, v86
	s_nop 0
	v_cndmask_b32_e32 v86, 0, v86, vcc
	v_add_f32_e32 v86, v87, v86
	v_mul_f32_e32 v86, v86, v98
	v_or_b32_e32 v98, 0x61, v0
	v_sub_u32_e32 v87, v168, v98
	v_cvt_f32_u32_e32 v88, v87
	v_cmp_lt_i32_e32 vcc, -1, v87
	v_mul_f32_e32 v88, v169, v88
	v_exp_f32_e32 v88, v88
	s_nop 0
	v_cndmask_b32_e32 v88, 0, v88, vcc
	v_cmp_gt_i32_e32 vcc, 1, v87
	v_sub_u32_e32 v87, 0, v87
	v_cvt_f32_u32_e32 v87, v87
	v_mul_f32_e32 v87, v170, v87
	v_exp_f32_e32 v87, v87
	s_nop 0
	v_cndmask_b32_e32 v87, 0, v87, vcc
	v_add_f32_e32 v87, v88, v87
	v_mul_f32_e32 v87, v87, v99
	v_or_b32_e32 v99, 0x62, v0
	v_sub_u32_e32 v88, v168, v99
	v_cvt_f32_u32_e32 v89, v88
	v_cmp_lt_i32_e32 vcc, -1, v88
	v_cvt_pk_bf16_f32 v86, v86, v87
	v_mul_f32_e32 v89, v169, v89
	v_exp_f32_e32 v89, v89
	s_nop 0
	v_cndmask_b32_e32 v89, 0, v89, vcc
	v_cmp_gt_i32_e32 vcc, 1, v88
	v_sub_u32_e32 v88, 0, v88
	v_cvt_f32_u32_e32 v88, v88
	v_mul_f32_e32 v88, v170, v88
	v_exp_f32_e32 v88, v88
	s_nop 0
	v_cndmask_b32_e32 v88, 0, v88, vcc
	v_add_f32_e32 v88, v89, v88
	v_mul_f32_e32 v88, v88, v100
	v_or_b32_e32 v100, 0x63, v0
	v_sub_u32_e32 v89, v168, v100
	v_cvt_f32_u32_e32 v104, v89
	v_cmp_lt_i32_e32 vcc, -1, v89
	v_mul_f32_e32 v104, v169, v104
	v_exp_f32_e32 v104, v104
	s_nop 0
	v_cndmask_b32_e32 v104, 0, v104, vcc
	v_cmp_gt_i32_e32 vcc, 1, v89
	v_sub_u32_e32 v89, 0, v89
	v_cvt_f32_u32_e32 v89, v89
	v_mul_f32_e32 v89, v170, v89
	v_exp_f32_e32 v89, v89
	s_nop 0
	v_cndmask_b32_e32 v89, 0, v89, vcc
	v_add_f32_e32 v89, v104, v89
	v_mul_f32_e32 v89, v89, v101
	v_sub_u32_e32 v101, v168, v102
	v_cvt_f32_u32_e32 v104, v101
	v_cmp_lt_i32_e32 vcc, -1, v101
	v_cvt_pk_bf16_f32 v87, v88, v89
	v_mul_f32_e32 v104, v169, v104
	v_exp_f32_e32 v104, v104
	s_nop 0
	v_cndmask_b32_e32 v104, 0, v104, vcc
	v_cmp_gt_i32_e32 vcc, 1, v101
	v_sub_u32_e32 v101, 0, v101
	v_cvt_f32_u32_e32 v101, v101
	v_mul_f32_e32 v101, v170, v101
	v_exp_f32_e32 v101, v101
	s_nop 0
	v_cndmask_b32_e32 v101, 0, v101, vcc
	v_add_f32_e32 v101, v104, v101
	v_mul_f32_e32 v101, v101, v94
	v_or_b32_e32 v94, 0x65, v0
	v_sub_u32_e32 v104, v168, v94
	v_cvt_f32_u32_e32 v105, v104
	v_cmp_lt_i32_e32 vcc, -1, v104
	v_sub_u32_e32 v94, v171, v94
	v_mul_f32_e32 v105, v169, v105
	v_exp_f32_e32 v105, v105
	s_nop 0
	v_cndmask_b32_e32 v105, 0, v105, vcc
	v_cmp_gt_i32_e32 vcc, 1, v104
	v_sub_u32_e32 v104, 0, v104
	v_cvt_f32_u32_e32 v104, v104
	v_mul_f32_e32 v104, v170, v104
	v_exp_f32_e32 v104, v104
	s_nop 0
	v_cndmask_b32_e32 v104, 0, v104, vcc
	v_add_f32_e32 v104, v105, v104
	v_mul_f32_e32 v104, v104, v95
	v_or_b32_e32 v95, 0x66, v0
	v_sub_u32_e32 v105, v168, v95
	v_cvt_f32_u32_e32 v106, v105
	v_cmp_lt_i32_e32 vcc, -1, v105
	v_cvt_pk_bf16_f32 v88, v101, v104
	v_mul_f32_e32 v106, v169, v106
	v_exp_f32_e32 v106, v106
	s_nop 0
	v_cndmask_b32_e32 v106, 0, v106, vcc
	v_cmp_gt_i32_e32 vcc, 1, v105
	v_sub_u32_e32 v105, 0, v105
	v_cvt_f32_u32_e32 v105, v105
	v_mul_f32_e32 v105, v170, v105
	v_exp_f32_e32 v105, v105
	s_nop 0
	v_cndmask_b32_e32 v105, 0, v105, vcc
	v_add_f32_e32 v105, v106, v105
	v_mul_f32_e32 v105, v105, v96
	v_or_b32_e32 v96, 0x67, v0
	v_sub_u32_e32 v106, v168, v96
	v_cvt_f32_u32_e32 v107, v106
	v_cmp_lt_i32_e32 vcc, -1, v106
	v_mul_f32_e32 v107, v169, v107
	v_exp_f32_e32 v107, v107
	s_nop 0
	v_cndmask_b32_e32 v107, 0, v107, vcc
	v_cmp_gt_i32_e32 vcc, 1, v106
	v_sub_u32_e32 v106, 0, v106
	v_cvt_f32_u32_e32 v106, v106
	v_mul_f32_e32 v106, v170, v106
	v_exp_f32_e32 v106, v106
	s_nop 0
	v_cndmask_b32_e32 v106, 0, v106, vcc
	v_add_f32_e32 v106, v107, v106
	v_mul_f32_e32 v97, v106, v97
	v_cvt_pk_bf16_f32 v89, v105, v97
	v_sub_u32_e32 v97, v171, v103
	v_cvt_f32_u32_e32 v101, v97
	v_cmp_lt_i32_e32 vcc, -1, v97
	v_mfma_f32_16x16x32_bf16 v[50:53], v[46:49], v[86:89], v[50:53]
	v_mul_f32_e32 v101, v169, v101
	v_exp_f32_e32 v101, v101
	v_mfma_f32_16x16x32_bf16 v[58:61], v[42:45], v[86:89], v[58:61]
	v_cndmask_b32_e32 v101, 0, v101, vcc
	v_cmp_gt_i32_e32 vcc, 1, v97
	v_sub_u32_e32 v97, 0, v97
	v_cvt_f32_u32_e32 v97, v97
	v_mul_f32_e32 v97, v170, v97
	v_exp_f32_e32 v97, v97
	s_nop 0
	v_cndmask_b32_e32 v97, 0, v97, vcc
	v_add_f32_e32 v97, v101, v97
	v_mul_f32_e32 v90, v97, v90
	v_sub_u32_e32 v97, v171, v98
	v_cvt_f32_u32_e32 v98, v97
	v_cmp_lt_i32_e32 vcc, -1, v97
	v_mul_f32_e32 v98, v169, v98
	v_exp_f32_e32 v98, v98
	s_nop 0
	v_cndmask_b32_e32 v98, 0, v98, vcc
	v_cmp_gt_i32_e32 vcc, 1, v97
	v_sub_u32_e32 v97, 0, v97
	v_cvt_f32_u32_e32 v97, v97
	v_mul_f32_e32 v97, v170, v97
	v_exp_f32_e32 v97, v97
	s_nop 0
	v_cndmask_b32_e32 v97, 0, v97, vcc
	v_add_f32_e32 v97, v98, v97
	v_mul_f32_e32 v91, v97, v91
	v_sub_u32_e32 v97, v171, v99
	v_cvt_f32_u32_e32 v98, v97
	v_cmp_lt_i32_e32 vcc, -1, v97
	v_cvt_pk_bf16_f32 v90, v90, v91
	v_mul_f32_e32 v98, v169, v98
	v_exp_f32_e32 v98, v98
	s_nop 0
	v_cndmask_b32_e32 v98, 0, v98, vcc
	v_cmp_gt_i32_e32 vcc, 1, v97
	v_sub_u32_e32 v97, 0, v97
	v_cvt_f32_u32_e32 v97, v97
	v_mul_f32_e32 v97, v170, v97
	v_exp_f32_e32 v97, v97
	s_nop 0
	v_cndmask_b32_e32 v97, 0, v97, vcc
	v_add_f32_e32 v97, v98, v97
	v_mul_f32_e32 v92, v97, v92
	v_sub_u32_e32 v97, v171, v100
	v_cvt_f32_u32_e32 v98, v97
	v_cmp_lt_i32_e32 vcc, -1, v97
	v_mul_f32_e32 v98, v169, v98
	v_exp_f32_e32 v98, v98
	s_nop 0
	v_cndmask_b32_e32 v98, 0, v98, vcc
	v_cmp_gt_i32_e32 vcc, 1, v97
	v_sub_u32_e32 v97, 0, v97
	v_cvt_f32_u32_e32 v97, v97
	v_mul_f32_e32 v97, v170, v97
	v_exp_f32_e32 v97, v97
	s_nop 0
	v_cndmask_b32_e32 v97, 0, v97, vcc
	v_add_f32_e32 v97, v98, v97
	v_mul_f32_e32 v93, v97, v93
	v_sub_u32_e32 v97, v171, v102
	v_cvt_f32_u32_e32 v98, v97
	v_cmp_lt_i32_e32 vcc, -1, v97
	v_cvt_pk_bf16_f32 v91, v92, v93
	v_mul_f32_e32 v98, v169, v98
	v_exp_f32_e32 v98, v98
	s_nop 0
	v_cndmask_b32_e32 v98, 0, v98, vcc
	v_cmp_gt_i32_e32 vcc, 1, v97
	v_sub_u32_e32 v97, 0, v97
	v_cvt_f32_u32_e32 v97, v97
	v_mul_f32_e32 v97, v170, v97
	v_exp_f32_e32 v97, v97
	s_nop 0
	v_cndmask_b32_e32 v97, 0, v97, vcc
	v_add_f32_e32 v97, v98, v97
	v_mul_f32_e32 v82, v97, v82
	v_cvt_f32_u32_e32 v97, v94
	v_cmp_lt_i32_e32 vcc, -1, v94
	v_mul_f32_e32 v97, v169, v97
	v_exp_f32_e32 v97, v97
	s_nop 0
	v_cndmask_b32_e32 v97, 0, v97, vcc
	v_cmp_gt_i32_e32 vcc, 1, v94
	v_sub_u32_e32 v94, 0, v94
	v_cvt_f32_u32_e32 v94, v94
	v_mul_f32_e32 v94, v170, v94
	v_exp_f32_e32 v94, v94
	s_nop 0
	v_cndmask_b32_e32 v94, 0, v94, vcc
	v_add_f32_e32 v94, v97, v94
	v_mul_f32_e32 v83, v94, v83
	v_sub_u32_e32 v94, v171, v95
	v_cvt_f32_u32_e32 v95, v94
	v_cmp_lt_i32_e32 vcc, -1, v94
	v_cvt_pk_bf16_f32 v92, v82, v83
	v_mul_f32_e32 v95, v169, v95
	v_exp_f32_e32 v95, v95
	s_nop 0
	v_cndmask_b32_e32 v95, 0, v95, vcc
	v_cmp_gt_i32_e32 vcc, 1, v94
	v_sub_u32_e32 v94, 0, v94
	v_cvt_f32_u32_e32 v94, v94
	v_mul_f32_e32 v94, v170, v94
	v_exp_f32_e32 v94, v94
	s_nop 0
	v_cndmask_b32_e32 v94, 0, v94, vcc
	v_add_f32_e32 v94, v95, v94
	v_mul_f32_e32 v84, v94, v84
	v_sub_u32_e32 v94, v171, v96
	v_cvt_f32_u32_e32 v95, v94
	v_cmp_lt_i32_e32 vcc, -1, v94
	v_mul_f32_e32 v95, v169, v95
	v_exp_f32_e32 v95, v95
	s_nop 0
	v_cndmask_b32_e32 v95, 0, v95, vcc
	v_cmp_gt_i32_e32 vcc, 1, v94
	v_sub_u32_e32 v94, 0, v94
	v_cvt_f32_u32_e32 v94, v94
	v_mul_f32_e32 v94, v170, v94
	v_exp_f32_e32 v94, v94
	s_nop 0
	v_cndmask_b32_e32 v94, 0, v94, vcc
	v_add_f32_e32 v94, v95, v94
	v_mul_f32_e32 v85, v94, v85
	v_cvt_pk_bf16_f32 v93, v84, v85
	v_cmp_lt_i32_e32 vcc, v210, v208
	v_mfma_f32_16x16x32_bf16 v[54:57], v[46:49], v[90:93], v[54:57]
	v_mfma_f32_16x16x32_bf16 v[62:65], v[42:45], v[90:93], v[62:65]
	v_mfma_f32_16x16x32_bf16 v[46:49], v[38:41], v[86:89], v[66:69]
	v_mfma_f32_16x16x32_bf16 v[66:69], v[38:41], v[90:93], v[70:73]
	v_mfma_f32_16x16x32_bf16 v[38:41], v[34:37], v[86:89], v[74:77]
	v_mfma_f32_16x16x32_bf16 v[70:73], v[34:37], v[90:93], v[78:81]
	global_load_dwordx4 v[34:37], v[162:163], off offset:64
	global_load_dwordx4 v[42:45], v[162:163], off
	global_load_dwordx4 v[74:77], v[158:159], off offset:64
	global_load_dwordx4 v[78:81], v[158:159], off
	global_load_dwordx4 v[82:85], v[152:153], off offset:2112
	global_load_dwordx4 v[86:89], v[152:153], off offset:2048
	global_load_dwordx4 v[90:93], v[152:153], off offset:64
	global_load_dwordx4 v[94:97], v[152:153], off
	global_load_dwordx4 v[98:101], v[160:161], off offset:64
	global_load_dwordx4 v[102:105], v[160:161], off
	global_load_dwordx4 v[106:109], v[156:157], off offset:64
	global_load_dwordx4 v[110:113], v[156:157], off
	global_load_dwordx4 v[114:117], v[154:155], off offset:2112
	global_load_dwordx4 v[118:121], v[154:155], off offset:2048
	global_load_dwordx4 v[122:125], v[154:155], off offset:64
	global_load_dwordx4 v[126:129], v[154:155], off
	s_waitcnt vmcnt(0)
	s_nop 0
	v_mfma_f32_16x16x32_bf16 v[130:133], v[94:97], v[30:33], 0
	v_mfma_f32_16x16x32_bf16 v[94:97], v[94:97], v[26:29], 0
	v_mfma_f32_16x16x32_bf16 v[130:133], v[90:93], v[22:25], v[130:133]
	v_mfma_f32_16x16x32_bf16 v[90:93], v[90:93], v[18:21], v[94:97]
	v_mfma_f32_16x16x32_bf16 v[94:97], v[86:89], v[30:33], 0
	v_mfma_f32_16x16x32_bf16 v[86:89], v[86:89], v[26:29], 0
	v_mfma_f32_16x16x32_bf16 v[94:97], v[82:85], v[22:25], v[94:97]
	v_mfma_f32_16x16x32_bf16 v[82:85], v[82:85], v[18:21], v[86:89]
	v_mfma_f32_16x16x32_bf16 v[86:89], v[78:81], v[30:33], 0
	v_mfma_f32_16x16x32_bf16 v[78:81], v[78:81], v[26:29], 0
	v_mfma_f32_16x16x32_bf16 v[86:89], v[74:77], v[22:25], v[86:89]
	v_mfma_f32_16x16x32_bf16 v[74:77], v[74:77], v[18:21], v[78:81]
	v_mfma_f32_16x16x32_bf16 v[78:81], v[42:45], v[30:33], 0
	v_mfma_f32_16x16x32_bf16 v[42:45], v[42:45], v[26:29], 0
	v_mfma_f32_16x16x32_bf16 v[78:81], v[34:37], v[22:25], v[78:81]
	v_mfma_f32_16x16x32_bf16 v[152:155], v[34:37], v[18:21], v[42:45]
	v_mfma_f32_16x16x32_bf16 v[34:37], v[126:129], v[30:33], 0
	v_mfma_f32_16x16x32_bf16 v[42:45], v[126:129], v[26:29], 0
	v_mfma_f32_16x16x32_bf16 v[126:129], v[122:125], v[22:25], v[34:37]
	v_mfma_f32_16x16x32_bf16 v[122:125], v[122:125], v[18:21], v[42:45]
	v_mfma_f32_16x16x32_bf16 v[34:37], v[118:121], v[30:33], 0
	v_mfma_f32_16x16x32_bf16 v[42:45], v[118:121], v[26:29], 0
	v_mfma_f32_16x16x32_bf16 v[118:121], v[114:117], v[22:25], v[34:37]
	v_mfma_f32_16x16x32_bf16 v[114:117], v[114:117], v[18:21], v[42:45]
	v_mfma_f32_16x16x32_bf16 v[34:37], v[110:113], v[30:33], 0
	v_mfma_f32_16x16x32_bf16 v[42:45], v[110:113], v[26:29], 0
	v_mfma_f32_16x16x32_bf16 v[30:33], v[102:105], v[30:33], 0
	v_mfma_f32_16x16x32_bf16 v[26:29], v[102:105], v[26:29], 0
	v_mfma_f32_16x16x32_bf16 v[34:37], v[106:109], v[22:25], v[34:37]
	v_mfma_f32_16x16x32_bf16 v[106:109], v[106:109], v[18:21], v[42:45]
	v_mfma_f32_16x16x32_bf16 v[22:25], v[98:101], v[22:25], v[30:33]
	v_mfma_f32_16x16x32_bf16 v[98:101], v[98:101], v[18:21], v[26:29]
	v_sub_u32_e32 v18, 0x80, v171
	v_cvt_f32_ubyte0_e32 v18, v18
	v_mul_f32_e32 v18, v170, v18
	s_nop 0
	v_exp_f32_e32 v28, v18
	v_add_u32_e32 v18, 1, v168
	v_cvt_f32_ubyte0_e32 v18, v18
	v_mul_f32_e32 v18, v169, v18
	v_exp_f32_e32 v18, v18
	s_nop 0
	v_pk_fma_f32 v[20:21], v[18:19], v[80:81], v[40:41] op_sel_hi:[0,1,1]
	v_pk_fma_f32 v[26:27], v[18:19], v[78:79], v[38:39] op_sel_hi:[0,1,1]
	v_sub_u32_e32 v19, 0x80, v168
	v_cvt_f32_ubyte0_e32 v19, v19
	v_mul_f32_e32 v19, v170, v19
	v_exp_f32_e32 v30, v19
	s_nop 0
	v_pk_fma_f32 v[42:43], v[30:31], v[24:25], v[20:21] op_sel_hi:[0,1,1]
	v_pk_fma_f32 v[20:21], v[18:19], v[88:89], v[48:49] op_sel_hi:[0,1,1]
	v_pk_fma_f32 v[44:45], v[30:31], v[22:23], v[26:27] op_sel_hi:[0,1,1]
	v_pk_fma_f32 v[22:23], v[18:19], v[86:87], v[46:47] op_sel_hi:[0,1,1]
	v_pk_fma_f32 v[46:47], v[30:31], v[36:37], v[20:21] op_sel_hi:[0,1,1]
	v_pk_fma_f32 v[20:21], v[18:19], v[96:97], v[60:61] op_sel_hi:[0,1,1]
	v_pk_fma_f32 v[48:49], v[30:31], v[34:35], v[22:23] op_sel_hi:[0,1,1]
	v_pk_fma_f32 v[22:23], v[18:19], v[94:95], v[58:59] op_sel_hi:[0,1,1]
	v_pk_fma_f32 v[34:35], v[30:31], v[120:121], v[20:21] op_sel_hi:[0,1,1]
	v_pk_fma_f32 v[20:21], v[18:19], v[132:133], v[52:53] op_sel_hi:[0,1,1]
	v_pk_fma_f32 v[18:19], v[18:19], v[130:131], v[50:51] op_sel_hi:[0,1,1]
	v_pk_fma_f32 v[40:41], v[30:31], v[126:127], v[18:19] op_sel_hi:[0,1,1]
	v_add_u32_e32 v18, 17, v168
	v_cvt_f32_ubyte0_e32 v18, v18
	v_mul_f32_e32 v18, v169, v18
	v_exp_f32_e32 v18, v18
	v_pk_fma_f32 v[36:37], v[30:31], v[118:119], v[22:23] op_sel_hi:[0,1,1]
	v_pk_fma_f32 v[38:39], v[30:31], v[128:129], v[20:21] op_sel_hi:[0,1,1]
	v_and_b32_e32 v58, 0xffff0000, v151
	v_pk_fma_f32 v[26:27], v[18:19], v[154:155], v[72:73] op_sel_hi:[0,1,1]
	v_pk_fma_f32 v[50:51], v[18:19], v[152:153], v[70:71] op_sel_hi:[0,1,1]
	v_pk_fma_f32 v[30:31], v[18:19], v[76:77], v[68:69] op_sel_hi:[0,1,1]
	v_pk_fma_f32 v[32:33], v[18:19], v[74:75], v[66:67] op_sel_hi:[0,1,1]
	v_pk_fma_f32 v[20:21], v[18:19], v[84:85], v[64:65] op_sel_hi:[0,1,1]
	v_pk_fma_f32 v[52:53], v[18:19], v[82:83], v[62:63] op_sel_hi:[0,1,1]
	v_pk_fma_f32 v[22:23], v[18:19], v[92:93], v[56:57] op_sel_hi:[0,1,1]
	v_pk_fma_f32 v[18:19], v[18:19], v[90:91], v[54:55] op_sel_hi:[0,1,1]
	v_pk_fma_f32 v[22:23], v[28:29], v[124:125], v[22:23] op_sel_hi:[0,1,1]
	v_pk_fma_f32 v[24:25], v[28:29], v[122:123], v[18:19] op_sel_hi:[0,1,1]
	v_pk_fma_f32 v[18:19], v[28:29], v[116:117], v[20:21] op_sel_hi:[0,1,1]
	v_pk_fma_f32 v[20:21], v[28:29], v[114:115], v[52:53] op_sel_hi:[0,1,1]
	v_pk_fma_f32 v[30:31], v[28:29], v[108:109], v[30:31] op_sel_hi:[0,1,1]
	v_pk_fma_f32 v[32:33], v[28:29], v[106:107], v[32:33] op_sel_hi:[0,1,1]
	v_pk_fma_f32 v[26:27], v[28:29], v[100:101], v[26:27] op_sel_hi:[0,1,1]
	v_pk_fma_f32 v[28:29], v[28:29], v[98:99], v[50:51] op_sel_hi:[0,1,1]
	v_cndmask_b32_e32 v50, v207, v210, vcc
	v_cmp_lt_i32_e32 vcc, v209, v208
	v_lshlrev_b32_e32 v54, 2, v50
	v_mov_b32_e32 v51, v36
	v_cndmask_b32_e32 v50, v207, v209, vcc
	v_lshlrev_b32_e32 v55, 2, v50
	v_mov_b32_e32 v50, v40
	v_mov_b32_e32 v52, v41
	v_mov_b32_e32 v53, v37
	v_pk_add_f32 v[50:51], v[50:51], v[52:53]
	v_mov_b32_e32 v52, v38
	v_mov_b32_e32 v53, v34
	v_pk_add_f32 v[50:51], v[52:53], v[50:51]
	v_mov_b32_e32 v52, v39
	v_mov_b32_e32 v53, v35
	v_pk_add_f32 v[50:51], v[52:53], v[50:51]
	v_mov_b32_e32 v52, v49
	v_add_f32_e32 v50, 0, v50
	v_add_f32_e32 v56, v50, v51
	v_mov_b32_e32 v50, v48
	v_mov_b32_e32 v51, v44
	v_mov_b32_e32 v53, v45
	v_pk_add_f32 v[50:51], v[50:51], v[52:53]
	v_mov_b32_e32 v52, v46
	v_mov_b32_e32 v53, v42
	v_pk_add_f32 v[50:51], v[52:53], v[50:51]
	v_mov_b32_e32 v52, v47
	v_mov_b32_e32 v53, v43
	v_pk_add_f32 v[50:51], v[52:53], v[50:51]
	v_lshlrev_b32_e32 v57, 16, v151
	v_add_f32_e32 v50, v56, v50
	v_add_f32_e32 v50, v50, v51
	ds_bpermute_b32 v51, v54, v50
	s_waitcnt lgkmcnt(0)
	v_add_f32_e32 v50, v50, v51
	ds_bpermute_b32 v51, v55, v50
	s_waitcnt lgkmcnt(0)
	v_add_f32_e32 v51, v50, v51
	v_fmac_f32_e32 v41, 0xbc800000, v51
	v_fmamk_f32 v40, v51, 0xbc800000, v40
	v_mul_f32_e32 v56, v41, v41
	v_fmac_f32_e32 v56, v40, v40
	v_fmamk_f32 v38, v51, 0xbc800000, v38
	v_fmac_f32_e32 v56, v38, v38
	v_fmac_f32_e32 v39, 0xbc800000, v51
	v_fmac_f32_e32 v56, v39, v39
	v_fmamk_f32 v36, v51, 0xbc800000, v36
	v_fmac_f32_e32 v56, v36, v36
	v_fmac_f32_e32 v37, 0xbc800000, v51
	v_mul_f32_e32 v50, 0x3c800000, v51
	v_fmac_f32_e32 v56, v37, v37
	v_fmamk_f32 v34, v51, 0xbc800000, v34
	v_fmac_f32_e32 v56, v34, v34
	v_fmac_f32_e32 v35, 0xbc800000, v51
	v_pk_add_f32 v[48:49], v[48:49], v[50:51] op_sel_hi:[1,0] neg_lo:[0,1] neg_hi:[0,1]
	v_fmac_f32_e32 v56, v35, v35
	v_pk_mul_f32 v[52:53], v[48:49], v[48:49]
	s_nop 0
	v_add_f32_e32 v51, v52, v56
	v_add_f32_e32 v51, v53, v51
	v_pk_add_f32 v[46:47], v[46:47], v[50:51] op_sel_hi:[1,0] neg_lo:[0,1] neg_hi:[0,1]
	v_and_b32_e32 v56, 0xffff0000, v150
	v_pk_mul_f32 v[52:53], v[46:47], v[46:47]
	s_nop 0
	v_add_f32_e32 v51, v52, v51
	v_add_f32_e32 v51, v53, v51
	v_pk_add_f32 v[44:45], v[44:45], v[50:51] op_sel_hi:[1,0] neg_lo:[0,1] neg_hi:[0,1]
	s_nop 0
	v_pk_mul_f32 v[52:53], v[44:45], v[44:45]
	s_nop 0
	v_add_f32_e32 v51, v52, v51
	v_pk_add_f32 v[42:43], v[42:43], v[50:51] op_sel_hi:[1,0] neg_lo:[0,1] neg_hi:[0,1]
	v_add_f32_e32 v52, v53, v51
	v_pk_mul_f32 v[50:51], v[42:43], v[42:43]
	v_lshlrev_b32_e32 v53, 16, v150
	v_add_f32_e32 v50, v50, v52
	v_add_f32_e32 v50, v51, v50
	ds_bpermute_b32 v51, v54, v50
	s_waitcnt lgkmcnt(0)
	v_add_f32_e32 v50, v50, v51
	ds_bpermute_b32 v51, v55, v50
	s_waitcnt lgkmcnt(0)
	v_add_f32_e32 v50, v50, v51
	v_fmamk_f32 v50, v50, 0x3c800000, v203
	v_cmp_gt_f32_e32 vcc, s28, v50
	v_mul_f32_e32 v51, 0x4b800000, v50
	s_nop 0
	v_cndmask_b32_e32 v50, v50, v51, vcc
	v_rsq_f32_e32 v50, v50
	s_nop 0
	v_mul_f32_e32 v51, 0x45800000, v50
	v_cndmask_b32_e32 v52, v50, v51, vcc
	v_cmp_gt_i32_e32 vcc, s37, v167
	v_mul_f32_e32 v40, v40, v52
	v_mul_f32_e32 v38, v38, v52
	v_cndmask_b32_e64 v50, 3, 1, vcc
	v_add_u32_e32 v50, v50, v167
	v_ashrrev_i32_e32 v51, 31, v50
	v_lshlrev_b64 v[50:51], 11, v[50:51]
	v_mul_f32_e32 v40, v14, v40
	v_mul_f32_e32 v41, v41, v52
	v_mul_f32_e32 v38, v16, v38
	v_lshl_add_u64 v[50:51], s[8:9], 0, v[50:51]
	v_mul_f32_e32 v40, v40, v53
	v_mul_f32_e32 v41, v15, v41
	v_mul_f32_e32 v53, v38, v57
	v_mul_f32_e32 v38, v39, v52
	v_lshl_add_u64 v[50:51], v[50:51], 0, v[134:135]
	v_mul_f32_e32 v41, v41, v56
	v_mul_f32_e32 v38, v17, v38
	v_mul_f32_e32 v39, v38, v58
	v_cvt_pk_bf16_f32 v38, v40, v41
	v_lshl_add_u64 v[40:41], v[50:51], 0, v[0:1]
	v_lshl_add_u64 v[50:51], v[40:41], 0, s[54:55]
	v_add_co_u32_e32 v40, vcc, s34, v40
	v_mul_f32_e32 v36, v36, v52
	s_nop 0
	v_addc_co_u32_e32 v41, vcc, 0, v41, vcc
	v_mul_f32_e32 v34, v34, v52
	v_cvt_pk_bf16_f32 v39, v53, v39
	global_store_dwordx2 v[40:41], v[38:39], off offset:1280
	v_lshlrev_b32_e32 v38, 16, v148
	v_lshlrev_b32_e32 v40, 16, v149
	v_mul_f32_e32 v36, v10, v36
	v_mul_f32_e32 v34, v12, v34
	v_mul_f32_e32 v36, v36, v38
	v_mul_f32_e32 v38, v34, v40
	v_mul_f32_e32 v34, v35, v52
	v_and_b32_e32 v41, 0xffff0000, v149
	v_mul_f32_e32 v37, v37, v52
	v_mul_f32_e32 v34, v13, v34
	v_and_b32_e32 v39, 0xffff0000, v148
	v_mul_f32_e32 v37, v11, v37
	v_mul_f32_e32 v35, v34, v41
	v_mul_f32_e32 v37, v37, v39
	v_cvt_pk_bf16_f32 v34, v36, v37
	v_cvt_pk_bf16_f32 v35, v38, v35
	v_mul_f32_e32 v38, v48, v52
	global_store_dwordx2 v[50:51], v[34:35], off offset:32
	v_lshlrev_b32_e32 v34, 16, v146
	v_mul_f32_e32 v38, v6, v38
	v_mul_f32_e32 v34, v38, v34
	v_mul_f32_e32 v38, v49, v52
	v_and_b32_e32 v35, 0xffff0000, v146
	v_mul_f32_e32 v38, v7, v38
	v_mul_f32_e32 v35, v38, v35
	v_mul_f32_e32 v38, v46, v52
	v_lshlrev_b32_e32 v36, 16, v147
	v_mul_f32_e32 v38, v8, v38
	v_mul_f32_e32 v36, v38, v36
	v_mul_f32_e32 v38, v47, v52
	v_and_b32_e32 v37, 0xffff0000, v147
	v_mul_f32_e32 v38, v9, v38
	v_mul_f32_e32 v37, v38, v37
	v_cvt_pk_bf16_f32 v34, v34, v35
	v_mul_f32_e32 v38, v44, v52
	v_cvt_pk_bf16_f32 v35, v36, v37
	global_store_dwordx2 v[50:51], v[34:35], off offset:64
	v_lshlrev_b32_e32 v34, 16, v144
	v_mul_f32_e32 v38, v2, v38
	v_mul_f32_e32 v34, v38, v34
	v_mul_f32_e32 v38, v45, v52
	v_and_b32_e32 v35, 0xffff0000, v144
	v_mul_f32_e32 v38, v3, v38
	v_mul_f32_e32 v35, v38, v35
	v_mul_f32_e32 v38, v42, v52
	v_lshlrev_b32_e32 v36, 16, v145
	v_mul_f32_e32 v38, v4, v38
	v_mul_f32_e32 v36, v38, v36
	v_mul_f32_e32 v38, v43, v52
	v_and_b32_e32 v37, 0xffff0000, v145
	v_mul_f32_e32 v38, v5, v38
	v_mul_f32_e32 v37, v38, v37
	v_cvt_pk_bf16_f32 v34, v34, v35
	v_cvt_pk_bf16_f32 v35, v36, v37
	global_store_dwordx2 v[50:51], v[34:35], off offset:96
	v_mov_b32_e32 v34, v24
	v_mov_b32_e32 v35, v20
	v_mov_b32_e32 v36, v25
	v_mov_b32_e32 v37, v21
	v_pk_add_f32 v[34:35], v[34:35], v[36:37]
	v_mov_b32_e32 v36, v22
	v_mov_b32_e32 v37, v18
	v_pk_add_f32 v[34:35], v[36:37], v[34:35]
	v_mov_b32_e32 v36, v23
	v_mov_b32_e32 v37, v19
	v_pk_add_f32 v[34:35], v[36:37], v[34:35]
	v_mov_b32_e32 v36, v33
	v_add_f32_e32 v34, 0, v34
	v_add_f32_e32 v38, v34, v35
	v_mov_b32_e32 v34, v32
	v_mov_b32_e32 v35, v28
	v_mov_b32_e32 v37, v29
	v_pk_add_f32 v[34:35], v[34:35], v[36:37]
	v_mov_b32_e32 v36, v30
	v_mov_b32_e32 v37, v26
	v_pk_add_f32 v[34:35], v[36:37], v[34:35]
	v_mov_b32_e32 v36, v31
	v_mov_b32_e32 v37, v27
	v_pk_add_f32 v[34:35], v[36:37], v[34:35]
	v_lshlrev_b32_e32 v39, 16, v143
	v_add_f32_e32 v34, v38, v34
	v_add_f32_e32 v34, v34, v35
	ds_bpermute_b32 v35, v54, v34
	v_and_b32_e32 v40, 0xffff0000, v143
	s_waitcnt lgkmcnt(0)
	v_add_f32_e32 v34, v34, v35
	ds_bpermute_b32 v35, v55, v34
	s_waitcnt lgkmcnt(0)
	v_add_f32_e32 v35, v34, v35
	v_fmac_f32_e32 v25, 0xbc800000, v35
	v_fmamk_f32 v24, v35, 0xbc800000, v24
	v_mul_f32_e32 v38, v25, v25
	v_fmac_f32_e32 v38, v24, v24
	v_fmamk_f32 v22, v35, 0xbc800000, v22
	v_fmac_f32_e32 v38, v22, v22
	v_fmac_f32_e32 v23, 0xbc800000, v35
	v_fmac_f32_e32 v38, v23, v23
	v_fmamk_f32 v20, v35, 0xbc800000, v20
	v_fmac_f32_e32 v38, v20, v20
	v_fmac_f32_e32 v21, 0xbc800000, v35
	v_mul_f32_e32 v34, 0x3c800000, v35
	v_fmac_f32_e32 v38, v21, v21
	v_fmamk_f32 v18, v35, 0xbc800000, v18
	v_fmac_f32_e32 v38, v18, v18
	v_fmac_f32_e32 v19, 0xbc800000, v35
	v_pk_add_f32 v[32:33], v[32:33], v[34:35] op_sel_hi:[1,0] neg_lo:[0,1] neg_hi:[0,1]
	v_fmac_f32_e32 v38, v19, v19
	v_pk_mul_f32 v[36:37], v[32:33], v[32:33]
	s_nop 0
	v_add_f32_e32 v35, v36, v38
	v_add_f32_e32 v35, v37, v35
	v_pk_add_f32 v[30:31], v[30:31], v[34:35] op_sel_hi:[1,0] neg_lo:[0,1] neg_hi:[0,1]
	v_and_b32_e32 v38, 0xffff0000, v142
	v_pk_mul_f32 v[36:37], v[30:31], v[30:31]
	s_nop 0
	v_add_f32_e32 v35, v36, v35
	v_add_f32_e32 v35, v37, v35
	v_pk_add_f32 v[28:29], v[28:29], v[34:35] op_sel_hi:[1,0] neg_lo:[0,1] neg_hi:[0,1]
	s_nop 0
	v_pk_mul_f32 v[36:37], v[28:29], v[28:29]
	s_nop 0
	v_add_f32_e32 v35, v36, v35
	v_pk_add_f32 v[26:27], v[26:27], v[34:35] op_sel_hi:[1,0] neg_lo:[0,1] neg_hi:[0,1]
	v_add_f32_e32 v36, v37, v35
	v_pk_mul_f32 v[34:35], v[26:27], v[26:27]
	v_lshlrev_b32_e32 v37, 16, v142
	v_add_f32_e32 v34, v34, v36
	v_add_f32_e32 v34, v35, v34
	ds_bpermute_b32 v35, v54, v34
	s_waitcnt lgkmcnt(0)
	v_add_f32_e32 v34, v34, v35
	ds_bpermute_b32 v35, v55, v34
	s_waitcnt lgkmcnt(0)
	v_add_f32_e32 v34, v34, v35
	v_fmamk_f32 v34, v34, 0x3c800000, v203
	v_cmp_gt_f32_e32 vcc, s28, v34
	v_mul_f32_e32 v35, 0x4b800000, v34
	s_nop 0
	v_cndmask_b32_e32 v34, v34, v35, vcc
	v_rsq_f32_e32 v34, v34
	s_nop 0
	v_mul_f32_e32 v35, 0x45800000, v34
	v_cndmask_b32_e32 v36, v34, v35, vcc
	v_cmp_gt_i32_e32 vcc, s37, v166
	v_mul_f32_e32 v24, v24, v36
	v_mul_f32_e32 v22, v22, v36
	v_cndmask_b32_e64 v34, 3, 1, vcc
	v_add_u32_e32 v34, v34, v166
	v_ashrrev_i32_e32 v35, 31, v34
	v_lshlrev_b64 v[34:35], 11, v[34:35]
	v_mul_f32_e32 v14, v14, v24
	v_mul_f32_e32 v24, v25, v36
	v_mul_f32_e32 v16, v16, v22
	v_mul_f32_e32 v22, v23, v36
	v_lshl_add_u64 v[34:35], s[8:9], 0, v[34:35]
	v_mul_f32_e32 v15, v15, v24
	v_mul_f32_e32 v17, v17, v22
	v_lshl_add_u64 v[34:35], v[34:35], 0, v[134:135]
	v_mul_f32_e32 v14, v14, v37
	v_mul_f32_e32 v15, v15, v38
	v_mul_f32_e32 v16, v16, v39
	v_mul_f32_e32 v17, v17, v40
	v_cvt_pk_bf16_f32 v14, v14, v15
	v_cvt_pk_bf16_f32 v15, v16, v17
	v_lshl_add_u64 v[16:17], v[34:35], 0, v[0:1]
	v_lshl_add_u64 v[22:23], v[16:17], 0, s[54:55]
	v_add_co_u32_e32 v16, vcc, s34, v16
	v_lshlrev_b32_e32 v0, 16, v140
	s_nop 0
	v_addc_co_u32_e32 v17, vcc, 0, v17, vcc
	global_store_dwordx2 v[16:17], v[14:15], off offset:1280
	v_mul_f32_e32 v17, v20, v36
	v_mul_f32_e32 v10, v10, v17
	v_mul_f32_e32 v0, v10, v0
	v_mul_f32_e32 v10, v21, v36
	v_mul_f32_e32 v10, v11, v10
	v_mul_f32_e32 v11, v18, v36
	v_and_b32_e32 v14, 0xffff0000, v140
	v_mul_f32_e32 v11, v12, v11
	v_mul_f32_e32 v12, v19, v36
	v_mul_f32_e32 v10, v10, v14
	v_mul_f32_e32 v12, v13, v12
	v_mul_f32_e32 v13, v32, v36
	v_cvt_pk_bf16_f32 v10, v0, v10
	v_lshlrev_b32_e32 v0, 16, v138
	v_mul_f32_e32 v6, v6, v13
	v_lshlrev_b32_e32 v15, 16, v141
	v_mul_f32_e32 v0, v6, v0
	v_mul_f32_e32 v6, v33, v36
	v_and_b32_e32 v16, 0xffff0000, v141
	v_mul_f32_e32 v11, v11, v15
	v_mul_f32_e32 v6, v7, v6
	v_mul_f32_e32 v7, v30, v36
	v_mul_f32_e32 v12, v12, v16
	v_cvt_pk_bf16_f32 v11, v11, v12
	global_store_dwordx2 v[22:23], v[10:11], off offset:32
	v_and_b32_e32 v10, 0xffff0000, v138
	v_mul_f32_e32 v7, v8, v7
	v_mul_f32_e32 v8, v31, v36
	v_mul_f32_e32 v6, v6, v10
	v_mul_f32_e32 v8, v9, v8
	v_mul_f32_e32 v9, v28, v36
	v_lshlrev_b32_e32 v11, 16, v139
	v_cvt_pk_bf16_f32 v6, v0, v6
	v_lshlrev_b32_e32 v0, 16, v136
	v_mul_f32_e32 v2, v2, v9
	v_and_b32_e32 v12, 0xffff0000, v139
	v_mul_f32_e32 v7, v7, v11
	v_mul_f32_e32 v0, v2, v0
	v_mul_f32_e32 v2, v29, v36
	v_mul_f32_e32 v8, v8, v12
	v_cvt_pk_bf16_f32 v7, v7, v8
	v_mul_f32_e32 v2, v3, v2
	v_mul_f32_e32 v3, v26, v36
	global_store_dwordx2 v[22:23], v[6:7], off offset:64
	v_and_b32_e32 v6, 0xffff0000, v136
	v_lshlrev_b32_e32 v7, 16, v137
	v_mul_f32_e32 v3, v4, v3
	v_mul_f32_e32 v4, v27, v36
	v_cmp_le_i32_e32 vcc, s2, v164
	v_and_b32_e32 v8, 0xffff0000, v137
	v_mul_f32_e32 v2, v2, v6
	v_mul_f32_e32 v3, v3, v7
	v_mul_f32_e32 v4, v5, v4
	s_or_b64 s[40:41], vcc, s[40:41]
	v_mul_f32_e32 v4, v4, v8
	v_cvt_pk_bf16_f32 v2, v0, v2
	v_cvt_pk_bf16_f32 v3, v3, v4
	global_store_dwordx2 v[22:23], v[2:3], off offset:96
	s_andn2_b64 exec, exec, s[40:41]
	s_cbranch_execnz .LBB0_149

.LBB0_160:
	v_bfe_i32 v4, v0, 27, 1
	v_lshlrev_b32_e32 v2, 4, v0
	v_lshrrev_b32_e32 v4, 22, v4
	v_add_u32_e32 v4, v2, v4
	v_and_b32_e32 v4, 0xfffffc00, v4
	v_sub_u32_e32 v4, v2, v4
	s_mul_i32 s3, s62, 0x1880000
	v_readlane_b32 s12, v255, 5
	v_ashrrev_i32_e32 v3, 31, v0
	v_lshrrev_b32_e32 v5, 4, v4
	s_mul_hi_i32 s2, s62, 0x1880000
	v_readlane_b32 s13, v255, 6
	s_add_u32 s12, s12, s3
	v_lshrrev_b32_e32 v3, 26, v3
	v_bitop3_b32 v5, v5, v4, 32 bitop3:0x6c
	v_ashrrev_i32_e32 v4, 31, v4
	s_addc_u32 s13, s13, s2
	v_add_u32_e32 v3, v0, v3
	v_lshrrev_b32_e32 v4, 26, v4
	s_and_b64 s[2:3], s[0:1], exec
	v_ashrrev_i32_e32 v3, 6, v3
	v_add_u32_e32 v4, v5, v4
	s_cselect_b32 s2, s18, 0xc404000
	v_lshlrev_b32_e32 v6, 3, v3
	v_ashrrev_i32_e32 v4, 6, v4
	v_lshlrev_b32_e32 v3, 5, v3
	s_add_u32 s50, s8, s2
	v_and_b32_e32 v6, 0x7ffffff0, v6
	v_and_b32_e32 v14, 32, v3
	v_mul_i32_i24_e32 v3, 64, v4
	s_addc_u32 s51, s9, 0
	v_add_u32_e32 v6, v4, v6
	v_sub_u32_e32 v3, v5, v3
	s_and_b64 s[2:3], s[0:1], exec
	v_ashrrev_i16_sdwa v3, v206, sext(v3) dst_sel:DWORD dst_unused:UNUSED_PAD src0_sel:DWORD src1_sel:BYTE_0
	v_mul_lo_u32 v16, v6, s46
	s_mov_b32 s2, 0x600000
	v_bfe_i32 v15, v3, 0, 16
	v_or_b32_e32 v3, v16, v14
	v_add_u32_e32 v2, 0x2000, v2
	s_cselect_b32 s2, s2, 0x1300000
	v_add_lshl_u32 v170, v3, v15, 1
	v_ashrrev_i32_e32 v3, 31, v2
	s_add_u32 s52, s12, s2
	v_lshrrev_b32_e32 v3, 22, v3
	s_addc_u32 s53, s13, 0
	v_add_u32_e32 v3, v2, v3
	v_readlane_b32 s12, v254, 38
	v_ashrrev_i32_e32 v3, 10, v3
	s_ashr_i32 s3, s49, 6
	v_readlane_b32 s13, v254, 39
	s_ashr_i32 s2, s49, 8
	v_mul_i32_i24_e32 v4, 0x400, v3
	s_lshl_b32 s18, s46, 8
	s_mov_b32 s19, s13
	s_lshl_b32 s54, s3, 10
	s_mul_hi_i32 s13, s17, s46
	s_mul_i32 s12, s17, s46
	s_ashr_i32 s17, s45, 31
	v_sub_u32_e32 v2, v2, v4
	s_add_u32 s12, s12, s45
	v_lshrrev_b32_e32 v4, 4, v2
	s_addc_u32 s13, s13, s17
	v_bitop3_b32 v2, v4, v2, 32 bitop3:0x6c
	s_lshl_b64 s[12:13], s[12:13], 1
	s_mul_i32 s22, s18, s87
	v_ashrrev_i32_e32 v5, 31, v2
	s_mul_hi_i32 s23, s18, s87
	s_add_u32 s22, s22, s45
	v_lshrrev_b32_e32 v5, 26, v5
	s_addc_u32 s23, s23, s17
	v_lshlrev_b32_e32 v4, 3, v3
	v_add_u32_e32 v5, v2, v5
	v_lshlrev_b32_e32 v3, 5, v3
	s_lshl_b64 s[22:23], s[22:23], 1
	v_and_b32_e32 v4, 0x7ffffff0, v4
	v_ashrrev_i32_e32 v6, 6, v5
	v_and_b32_e32 v17, 32, v3
	v_and_b32_e32 v3, 0xc0, v5
	s_add_u32 s42, s52, s22
	v_add_u32_e32 v4, v6, v4
	v_sub_u32_e32 v2, v2, v3
	s_addc_u32 s43, s53, s23
	s_add_i32 s55, s54, 0
	v_ashrrev_i16_sdwa v2, v206, sext(v2) dst_sel:DWORD dst_unused:UNUSED_PAD src0_sel:DWORD src1_sel:BYTE_0
	v_mul_lo_u32 v19, v4, s46
	s_add_i32 m0, s55, 0x10000
	v_bfe_i32 v18, v2, 0, 16
	v_or_b32_e32 v2, v19, v17
	global_load_lds_dwordx4 v170, s[42:43]
	s_add_i32 m0, s55, 0x12000
	v_add_lshl_u32 v172, v2, v18, 1
	s_add_u32 s34, s50, s12
	global_load_lds_dwordx4 v172, s[42:43]
	s_addc_u32 s35, s51, s13
	s_mov_b32 m0, s55
	s_add_i32 s58, s55, 0x2000
	global_load_lds_dwordx4 v170, s[34:35]
	s_mov_b32 m0, s58
	s_add_u32 s12, s42, s18
	global_load_lds_dwordx4 v172, s[34:35]
	s_addc_u32 s13, s43, 0
	s_add_i32 m0, s55, 0x14000
	v_mov_b32_e32 v171, v1
	v_mov_b32_e32 v173, v1
	global_load_lds_dwordx4 v170, s[12:13]
	s_add_i32 m0, s55, 0x16000
	v_lshl_add_u64 v[10:11], s[12:13], 0, v[170:171]
	v_lshl_add_u64 v[12:13], s[12:13], 0, v[172:173]
	global_load_lds_dwordx4 v172, s[12:13]
	s_add_u32 s12, s34, s18
	s_addc_u32 s13, s35, 0
	s_add_i32 s59, s55, 0x4000
	s_mov_b32 m0, s59
	s_add_i32 s77, s55, 0x6000
	global_load_lds_dwordx4 v170, s[12:13]
	s_mov_b32 m0, s77
	v_lshl_add_u64 v[2:3], s[42:43], 0, v[170:171]
	global_load_lds_dwordx4 v172, s[12:13]
	v_lshl_add_u64 v[4:5], s[42:43], 0, v[172:173]
	v_lshl_add_u64 v[6:7], s[34:35], 0, v[170:171]
	v_lshl_add_u64 v[8:9], s[34:35], 0, v[172:173]
	s_cmp_lg_u32 s2, 1
	s_cbranch_scc1 .LBB0_162
	s_setprio 1
	s_barrier

.LBB0_182:
	s_add_i32 s91, s2, 2
	s_add_u32 s12, s34, 0x80
	s_addc_u32 s3, s35, 0
	s_add_i32 s13, 0, 0x10000
	v_add_u32_e32 v142, s13, v183
	ds_read_b128 v[130:133], v142
	ds_read_b128 v[134:137], v142 offset:1024
	ds_read_b128 v[138:141], v142 offset:2048
	ds_read_b128 v[142:145], v142 offset:3072
	s_cmp_eq_u32 s88, s2
	s_cselect_b32 s2, s0, s12
	s_cselect_b32 s3, s1, s3
	s_cselect_b32 s43, s41, s90
	s_cselect_b32 s42, s40, s89
	v_lshl_add_u64 v[190:191], s[34:35], 0, v[174:175]
	s_add_i32 m0, s55, 0xc000
	ds_read_b128 v[146:149], v184
	ds_read_b128 v[150:153], v184 offset:1024
	ds_read_b128 v[154:157], v184 offset:2048
	ds_read_b128 v[158:161], v184 offset:3072
	ds_read_b128 v[162:165], v184 offset:4096
	ds_read_b128 v[166:169], v184 offset:5120
	ds_read_b128 v[178:181], v184 offset:6144
	ds_read_b128 v[186:189], v184 offset:7168
	global_load_lds_dwordx4 v[190:191], off
	v_lshl_add_u64 v[190:191], s[34:35], 0, v[176:177]
	s_add_i32 m0, s55, 0xe000
	s_nop 0
	global_load_lds_dwordx4 v[190:191], off
	s_waitcnt lgkmcnt(8)
	s_barrier
	s_waitcnt lgkmcnt(0)
	s_waitcnt lgkmcnt(0)
	v_mfma_f32_16x16x32_bf16 v[126:129], v[130:133], v[146:149], v[126:129]
	v_mfma_f32_16x16x32_bf16 v[122:125], v[138:141], v[146:149], v[122:125]
	v_mfma_f32_16x16x32_bf16 v[118:121], v[130:133], v[154:157], v[118:121]
	v_mfma_f32_16x16x32_bf16 v[114:117], v[138:141], v[154:157], v[114:117]
	v_mfma_f32_16x16x32_bf16 v[110:113], v[130:133], v[162:165], v[110:113]
	v_mfma_f32_16x16x32_bf16 v[106:109], v[138:141], v[162:165], v[106:109]
	v_mfma_f32_16x16x32_bf16 v[102:105], v[130:133], v[178:181], v[102:105]
	v_mfma_f32_16x16x32_bf16 v[98:101], v[138:141], v[178:181], v[98:101]
	v_mfma_f32_16x16x32_bf16 v[126:129], v[134:137], v[150:153], v[126:129]
	v_mfma_f32_16x16x32_bf16 v[122:125], v[142:145], v[150:153], v[122:125]
	v_mfma_f32_16x16x32_bf16 v[118:121], v[134:137], v[158:161], v[118:121]
	v_mfma_f32_16x16x32_bf16 v[114:117], v[142:145], v[158:161], v[114:117]
	v_mfma_f32_16x16x32_bf16 v[110:113], v[134:137], v[166:169], v[110:113]
	v_mfma_f32_16x16x32_bf16 v[106:109], v[142:145], v[166:169], v[106:109]
	v_mfma_f32_16x16x32_bf16 v[102:105], v[134:137], v[186:189], v[102:105]
	v_mfma_f32_16x16x32_bf16 v[98:101], v[142:145], v[186:189], v[98:101]
	s_barrier
	s_add_i32 s92, 0, 0x14000
	s_add_i32 s12, s13, s54
	v_add_u32_e32 v185, s92, v183
	v_lshl_add_u64 v[230:231], s[42:43], 0, v[170:171]
	s_mov_b32 m0, s12
	ds_read_b128 v[190:193], v185
	ds_read_b128 v[194:197], v185 offset:1024
	ds_read_b128 v[198:201], v185 offset:2048
	ds_read_b128 v[226:229], v185 offset:3072
	global_load_lds_dwordx4 v[230:231], off
	v_lshl_add_u64 v[232:233], s[42:43], 0, v[172:173]
	s_add_i32 m0, s12, 0x2000
	s_nop 0
	global_load_lds_dwordx4 v[232:233], off
	s_barrier
	s_waitcnt lgkmcnt(0)
	s_waitcnt lgkmcnt(0)
	v_mfma_f32_16x16x32_bf16 v[62:65], v[190:193], v[146:149], v[62:65]
	v_mfma_f32_16x16x32_bf16 v[58:61], v[198:201], v[146:149], v[58:61]
	v_mfma_f32_16x16x32_bf16 v[54:57], v[190:193], v[154:157], v[54:57]
	v_mfma_f32_16x16x32_bf16 v[50:53], v[198:201], v[154:157], v[50:53]
	v_mfma_f32_16x16x32_bf16 v[46:49], v[190:193], v[162:165], v[46:49]
	v_mfma_f32_16x16x32_bf16 v[42:45], v[198:201], v[162:165], v[42:45]
	v_mfma_f32_16x16x32_bf16 v[38:41], v[190:193], v[178:181], v[38:41]
	v_mfma_f32_16x16x32_bf16 v[34:37], v[198:201], v[178:181], v[34:37]
	v_mfma_f32_16x16x32_bf16 v[62:65], v[194:197], v[150:153], v[62:65]
	v_mfma_f32_16x16x32_bf16 v[58:61], v[226:229], v[150:153], v[58:61]
	v_mfma_f32_16x16x32_bf16 v[54:57], v[194:197], v[158:161], v[54:57]
	v_mfma_f32_16x16x32_bf16 v[50:53], v[226:229], v[158:161], v[50:53]
	v_mfma_f32_16x16x32_bf16 v[46:49], v[194:197], v[166:169], v[46:49]
	v_mfma_f32_16x16x32_bf16 v[42:45], v[226:229], v[166:169], v[42:45]
	v_mfma_f32_16x16x32_bf16 v[38:41], v[194:197], v[186:189], v[38:41]
	v_mfma_f32_16x16x32_bf16 v[34:37], v[226:229], v[186:189], v[34:37]
	s_mov_b32 m0, s55
	v_lshl_add_u64 v[234:235], s[2:3], 0, v[170:171]
	s_barrier
	ds_read_b128 v[146:149], v184 offset:16384
	ds_read_b128 v[150:153], v184 offset:17408
	ds_read_b128 v[154:157], v184 offset:18432
	ds_read_b128 v[158:161], v184 offset:19456
	ds_read_b128 v[162:165], v184 offset:20480
	ds_read_b128 v[166:169], v184 offset:21504
	ds_read_b128 v[178:181], v184 offset:22528
	ds_read_b128 v[186:189], v184 offset:23552
	global_load_lds_dwordx4 v[234:235], off
	v_lshl_add_u64 v[236:237], s[2:3], 0, v[172:173]
	s_mov_b32 m0, s58
	s_nop 0
	global_load_lds_dwordx4 v[236:237], off
	s_barrier
	s_waitcnt lgkmcnt(0)
	s_waitcnt lgkmcnt(0)
	v_mfma_f32_16x16x32_bf16 v[94:97], v[130:133], v[146:149], v[94:97]
	v_mfma_f32_16x16x32_bf16 v[90:93], v[138:141], v[146:149], v[90:93]
	v_mfma_f32_16x16x32_bf16 v[86:89], v[130:133], v[154:157], v[86:89]
	v_mfma_f32_16x16x32_bf16 v[82:85], v[138:141], v[154:157], v[82:85]
	v_mfma_f32_16x16x32_bf16 v[78:81], v[130:133], v[162:165], v[78:81]
	v_mfma_f32_16x16x32_bf16 v[74:77], v[138:141], v[162:165], v[74:77]
	v_mfma_f32_16x16x32_bf16 v[70:73], v[130:133], v[178:181], v[70:73]
	v_mfma_f32_16x16x32_bf16 v[66:69], v[138:141], v[178:181], v[66:69]
	v_mfma_f32_16x16x32_bf16 v[94:97], v[134:137], v[150:153], v[94:97]
	v_mfma_f32_16x16x32_bf16 v[90:93], v[142:145], v[150:153], v[90:93]
	v_mfma_f32_16x16x32_bf16 v[86:89], v[134:137], v[158:161], v[86:89]
	v_mfma_f32_16x16x32_bf16 v[82:85], v[142:145], v[158:161], v[82:85]
	v_mfma_f32_16x16x32_bf16 v[78:81], v[134:137], v[166:169], v[78:81]
	v_mfma_f32_16x16x32_bf16 v[74:77], v[142:145], v[166:169], v[74:77]
	v_mfma_f32_16x16x32_bf16 v[70:73], v[134:137], v[186:189], v[70:73]
	v_mfma_f32_16x16x32_bf16 v[66:69], v[142:145], v[186:189], v[66:69]
	s_barrier
	s_add_u32 s12, s42, s18
	s_addc_u32 s13, s43, 0
	s_add_i32 s42, s92, s54
	v_lshl_add_u64 v[242:243], s[12:13], 0, v[170:171]
	s_mov_b32 m0, s42
	v_lshl_add_u64 v[244:245], s[12:13], 0, v[172:173]
	global_load_lds_dwordx4 v[242:243], off
	s_add_i32 m0, s42, 0x2000
	s_nop 0
	global_load_lds_dwordx4 v[244:245], off
	s_waitcnt vmcnt(6)
	s_barrier
	v_mfma_f32_16x16x32_bf16 v[30:33], v[190:193], v[146:149], v[30:33]
	v_mfma_f32_16x16x32_bf16 v[26:29], v[198:201], v[146:149], v[26:29]
	v_mfma_f32_16x16x32_bf16 v[22:25], v[190:193], v[154:157], v[22:25]
	v_mfma_f32_16x16x32_bf16 v[18:21], v[198:201], v[154:157], v[18:21]
	v_mfma_f32_16x16x32_bf16 v[14:17], v[190:193], v[162:165], v[14:17]
	v_mfma_f32_16x16x32_bf16 v[10:13], v[198:201], v[162:165], v[10:13]
	v_mfma_f32_16x16x32_bf16 v[6:9], v[190:193], v[178:181], v[6:9]
	v_mfma_f32_16x16x32_bf16 v[2:5], v[198:201], v[178:181], v[2:5]
	v_mfma_f32_16x16x32_bf16 v[30:33], v[194:197], v[150:153], v[30:33]
	v_mfma_f32_16x16x32_bf16 v[26:29], v[226:229], v[150:153], v[26:29]
	v_mfma_f32_16x16x32_bf16 v[22:25], v[194:197], v[158:161], v[22:25]
	v_mfma_f32_16x16x32_bf16 v[18:21], v[226:229], v[158:161], v[18:21]
	v_mfma_f32_16x16x32_bf16 v[14:17], v[194:197], v[166:169], v[14:17]
	v_mfma_f32_16x16x32_bf16 v[10:13], v[226:229], v[166:169], v[10:13]
	v_mfma_f32_16x16x32_bf16 v[6:9], v[194:197], v[186:189], v[6:9]
	v_mfma_f32_16x16x32_bf16 v[2:5], v[226:229], v[186:189], v[2:5]
	s_add_i32 s12, 0, 0x18000
	v_add_u32_e32 v142, s12, v183
	s_barrier
	ds_read_b128 v[130:133], v142
	ds_read_b128 v[134:137], v142 offset:1024
	ds_read_b128 v[138:141], v142 offset:2048
	ds_read_b128 v[142:145], v142 offset:3072
	s_add_u32 s2, s2, s18
	s_addc_u32 s3, s3, 0
	s_mov_b32 m0, s59
	v_lshl_add_u64 v[190:191], s[2:3], 0, v[170:171]
	ds_read_b128 v[146:149], v184 offset:32768
	ds_read_b128 v[150:153], v184 offset:33792
	ds_read_b128 v[154:157], v184 offset:34816
	ds_read_b128 v[158:161], v184 offset:35840
	ds_read_b128 v[162:165], v184 offset:36864
	ds_read_b128 v[166:169], v184 offset:37888
	ds_read_b128 v[178:181], v184 offset:38912
	ds_read_b128 v[186:189], v184 offset:39936
	global_load_lds_dwordx4 v[190:191], off
	v_lshl_add_u64 v[190:191], s[2:3], 0, v[172:173]
	s_mov_b32 m0, s77
	s_nop 0
	global_load_lds_dwordx4 v[190:191], off
	s_waitcnt lgkmcnt(8)
	s_barrier
	s_waitcnt lgkmcnt(0)
	s_waitcnt lgkmcnt(0)
	v_mfma_f32_16x16x32_bf16 v[126:129], v[130:133], v[146:149], v[126:129]
	v_mfma_f32_16x16x32_bf16 v[122:125], v[138:141], v[146:149], v[122:125]
	v_mfma_f32_16x16x32_bf16 v[118:121], v[130:133], v[154:157], v[118:121]
	v_mfma_f32_16x16x32_bf16 v[114:117], v[138:141], v[154:157], v[114:117]
	v_mfma_f32_16x16x32_bf16 v[110:113], v[130:133], v[162:165], v[110:113]
	v_mfma_f32_16x16x32_bf16 v[106:109], v[138:141], v[162:165], v[106:109]
	v_mfma_f32_16x16x32_bf16 v[102:105], v[130:133], v[178:181], v[102:105]
	v_mfma_f32_16x16x32_bf16 v[98:101], v[138:141], v[178:181], v[98:101]
	v_mfma_f32_16x16x32_bf16 v[126:129], v[134:137], v[150:153], v[126:129]
	v_mfma_f32_16x16x32_bf16 v[122:125], v[142:145], v[150:153], v[122:125]
	v_mfma_f32_16x16x32_bf16 v[118:121], v[134:137], v[158:161], v[118:121]
	v_mfma_f32_16x16x32_bf16 v[114:117], v[142:145], v[158:161], v[114:117]
	v_mfma_f32_16x16x32_bf16 v[110:113], v[134:137], v[166:169], v[110:113]
	v_mfma_f32_16x16x32_bf16 v[106:109], v[142:145], v[166:169], v[106:109]
	v_mfma_f32_16x16x32_bf16 v[102:105], v[134:137], v[186:189], v[102:105]
	v_mfma_f32_16x16x32_bf16 v[98:101], v[142:145], v[186:189], v[98:101]
	s_barrier
	s_add_i32 s2, 0, 0x1c000
	s_add_i32 s3, s12, s54
	v_add_u32_e32 v185, s2, v183
	v_lshl_add_u64 v[230:231], v[230:231], 0, s[20:21]
	s_mov_b32 m0, s3
	ds_read_b128 v[190:193], v185
	ds_read_b128 v[194:197], v185 offset:1024
	ds_read_b128 v[198:201], v185 offset:2048
	ds_read_b128 v[226:229], v185 offset:3072
	global_load_lds_dwordx4 v[230:231], off
	v_lshl_add_u64 v[230:231], v[232:233], 0, s[20:21]
	s_add_i32 m0, s3, 0x2000
	s_nop 0
	global_load_lds_dwordx4 v[230:231], off
	s_barrier
	s_waitcnt lgkmcnt(0)
	s_waitcnt lgkmcnt(0)
	v_mfma_f32_16x16x32_bf16 v[62:65], v[190:193], v[146:149], v[62:65]
	v_mfma_f32_16x16x32_bf16 v[58:61], v[198:201], v[146:149], v[58:61]
	v_mfma_f32_16x16x32_bf16 v[54:57], v[190:193], v[154:157], v[54:57]
	v_mfma_f32_16x16x32_bf16 v[50:53], v[198:201], v[154:157], v[50:53]
	v_mfma_f32_16x16x32_bf16 v[46:49], v[190:193], v[162:165], v[46:49]
	v_mfma_f32_16x16x32_bf16 v[42:45], v[198:201], v[162:165], v[42:45]
	v_mfma_f32_16x16x32_bf16 v[38:41], v[190:193], v[178:181], v[38:41]
	v_mfma_f32_16x16x32_bf16 v[34:37], v[198:201], v[178:181], v[34:37]
	v_mfma_f32_16x16x32_bf16 v[62:65], v[194:197], v[150:153], v[62:65]
	v_mfma_f32_16x16x32_bf16 v[58:61], v[226:229], v[150:153], v[58:61]
	v_mfma_f32_16x16x32_bf16 v[54:57], v[194:197], v[158:161], v[54:57]
	v_mfma_f32_16x16x32_bf16 v[50:53], v[226:229], v[158:161], v[50:53]
	v_mfma_f32_16x16x32_bf16 v[46:49], v[194:197], v[166:169], v[46:49]
	v_mfma_f32_16x16x32_bf16 v[42:45], v[226:229], v[166:169], v[42:45]
	v_mfma_f32_16x16x32_bf16 v[38:41], v[194:197], v[186:189], v[38:41]
	v_mfma_f32_16x16x32_bf16 v[34:37], v[226:229], v[186:189], v[34:37]
	s_mov_b32 m0, s80
	v_lshl_add_u64 v[230:231], v[234:235], 0, s[20:21]
	s_barrier
	ds_read_b128 v[146:149], v184 offset:49152
	ds_read_b128 v[150:153], v184 offset:50176
	ds_read_b128 v[154:157], v184 offset:51200
	ds_read_b128 v[158:161], v184 offset:52224
	ds_read_b128 v[162:165], v184 offset:53248
	ds_read_b128 v[166:169], v184 offset:54272
	ds_read_b128 v[178:181], v184 offset:55296
	ds_read_b128 v[186:189], v184 offset:56320
	global_load_lds_dwordx4 v[230:231], off
	v_lshl_add_u64 v[230:231], v[236:237], 0, s[20:21]
	s_mov_b32 m0, s81
	s_nop 0
	global_load_lds_dwordx4 v[230:231], off
	s_barrier
	s_waitcnt lgkmcnt(0)
	s_waitcnt lgkmcnt(0)
	v_mfma_f32_16x16x32_bf16 v[94:97], v[130:133], v[146:149], v[94:97]
	v_mfma_f32_16x16x32_bf16 v[90:93], v[138:141], v[146:149], v[90:93]
	v_mfma_f32_16x16x32_bf16 v[86:89], v[130:133], v[154:157], v[86:89]
	v_mfma_f32_16x16x32_bf16 v[82:85], v[138:141], v[154:157], v[82:85]
	v_mfma_f32_16x16x32_bf16 v[78:81], v[130:133], v[162:165], v[78:81]
	v_mfma_f32_16x16x32_bf16 v[74:77], v[138:141], v[162:165], v[74:77]
	v_mfma_f32_16x16x32_bf16 v[70:73], v[130:133], v[178:181], v[70:73]
	v_mfma_f32_16x16x32_bf16 v[66:69], v[138:141], v[178:181], v[66:69]
	v_mfma_f32_16x16x32_bf16 v[94:97], v[134:137], v[150:153], v[94:97]
	v_mfma_f32_16x16x32_bf16 v[90:93], v[142:145], v[150:153], v[90:93]
	v_mfma_f32_16x16x32_bf16 v[86:89], v[134:137], v[158:161], v[86:89]
	v_mfma_f32_16x16x32_bf16 v[82:85], v[142:145], v[158:161], v[82:85]
	v_mfma_f32_16x16x32_bf16 v[78:81], v[134:137], v[166:169], v[78:81]
	v_mfma_f32_16x16x32_bf16 v[74:77], v[142:145], v[166:169], v[74:77]
	v_mfma_f32_16x16x32_bf16 v[70:73], v[134:137], v[186:189], v[70:73]
	v_mfma_f32_16x16x32_bf16 v[66:69], v[142:145], v[186:189], v[66:69]
	s_barrier
	s_add_i32 s2, s2, s54
	v_lshl_add_u64 v[130:131], v[242:243], 0, s[20:21]
	s_mov_b32 m0, s2
	s_nop 0
	global_load_lds_dwordx4 v[130:131], off
	v_lshl_add_u64 v[130:131], v[244:245], 0, s[20:21]
	s_add_i32 m0, s2, 0x2000
	s_nop 0
	global_load_lds_dwordx4 v[130:131], off
	s_waitcnt vmcnt(6)
	s_barrier
	v_mfma_f32_16x16x32_bf16 v[30:33], v[190:193], v[146:149], v[30:33]
	v_mfma_f32_16x16x32_bf16 v[26:29], v[198:201], v[146:149], v[26:29]
	v_mfma_f32_16x16x32_bf16 v[22:25], v[190:193], v[154:157], v[22:25]
	v_mfma_f32_16x16x32_bf16 v[18:21], v[198:201], v[154:157], v[18:21]
	v_mfma_f32_16x16x32_bf16 v[14:17], v[190:193], v[162:165], v[14:17]
	v_mfma_f32_16x16x32_bf16 v[10:13], v[198:201], v[162:165], v[10:13]
	v_mfma_f32_16x16x32_bf16 v[6:9], v[190:193], v[178:181], v[6:9]
	v_mfma_f32_16x16x32_bf16 v[2:5], v[198:201], v[178:181], v[2:5]
	v_mfma_f32_16x16x32_bf16 v[30:33], v[194:197], v[150:153], v[30:33]
	v_mfma_f32_16x16x32_bf16 v[26:29], v[226:229], v[150:153], v[26:29]
	v_mfma_f32_16x16x32_bf16 v[22:25], v[194:197], v[158:161], v[22:25]
	v_mfma_f32_16x16x32_bf16 v[18:21], v[226:229], v[158:161], v[18:21]
	v_mfma_f32_16x16x32_bf16 v[14:17], v[194:197], v[166:169], v[14:17]
	v_mfma_f32_16x16x32_bf16 v[10:13], v[226:229], v[166:169], v[10:13]
	v_mfma_f32_16x16x32_bf16 v[6:9], v[194:197], v[186:189], v[6:9]
	v_mfma_f32_16x16x32_bf16 v[2:5], v[226:229], v[186:189], v[2:5]
	s_add_u32 s34, s34, 0x100
	s_addc_u32 s35, s35, 0
	s_add_u32 s89, s89, 0x100
	s_addc_u32 s90, s90, 0
	s_cmp_ge_i32 s91, s44
	s_mov_b32 s2, s91
	s_barrier
	s_cbranch_scc0 .LBB0_182
	s_cmp_lt_i32 s86, 64
	s_cselect_b64 s[34:35], -1, 0
	s_ashr_i32 s2, s45, 8
	s_ashr_i32 s3, s2, 31
	s_lshl_b64 s[2:3], s[2:3], 18
	s_add_u32 s2, s2, 0x3232000
	s_addc_u32 s3, s3, 0
	s_cmp_gt_i32 s86, 63
	s_cselect_b32 s12, 0x6000, 0
	s_cselect_b32 s45, s3, 0
	s_cselect_b32 s44, s2, 0
	s_add_u32 s12, s78, s12
	s_addc_u32 s13, s79, 0
	s_lshl_b32 s2, s87, 8
	s_ashr_i32 s3, s2, 31
	s_lshl_b64 s[2:3], s[2:3], 2
	s_add_u32 s12, s12, s2
	s_addc_u32 s13, s13, s3
	v_readlane_b32 s88, v254, 38
	s_add_u32 s42, s12, s88
	s_addc_u32 s43, s13, 0
	global_load_dwordx4 v[134:137], v0, s[42:43]
	global_load_dwordx4 v[130:133], v0, s[42:43] offset:64
	v_lshl_add_u32 v138, s86, 8, v182
	v_ashrrev_i32_e32 v139, 31, v138
	v_readlane_b32 s12, v252, 5
	v_lshlrev_b64 v[138:139], 12, v[138:139]
	v_readlane_b32 s13, v252, 6
	v_readlane_b32 s89, v254, 39
	s_and_b64 vcc, exec, s[34:35]
	v_lshl_add_u64 v[138:139], s[12:13], 0, v[138:139]
	v_lshl_add_u64 v[138:139], v[138:139], 0, s[2:3]
	v_lshl_add_u64 v[138:139], v[138:139], 0, s[88:89]
	v_lshl_add_u64 v[178:179], v[138:139], 0, v[0:1]
	v_lshl_add_u64 v[180:181], v[178:179], 0, s[22:23]
	s_mov_b64 s[2:3], -1
	s_mov_b32 s12, 0x10000
	s_cbranch_vccz .LBB0_185
	v_add_co_u32_e32 v138, vcc, 0x30000, v180
	s_mov_b32 s2, 0x20000
	s_nop 0
	v_addc_co_u32_e32 v139, vcc, 0, v181, vcc
	global_load_dwordx4 v[166:169], v[138:139], off offset:64
	global_load_dwordx4 v[186:189], v[138:139], off
	v_add_co_u32_e32 v138, vcc, 0x20000, v180
	s_nop 1
	v_addc_co_u32_e32 v139, vcc, 0, v181, vcc
	global_load_dwordx4 v[190:193], v[138:139], off offset:64
	global_load_dwordx4 v[194:197], v[138:139], off
	v_add_co_u32_e32 v138, vcc, 0x10000, v180
	s_nop 1
	v_addc_co_u32_e32 v139, vcc, 0, v181, vcc
	v_add_co_u32_e32 v142, vcc, 0xb0000, v180
	global_load_dwordx4 v[198:201], v[138:139], off offset:64
	global_load_dwordx4 v[226:229], v[138:139], off
	global_load_dwordx4 v[230:233], v[180:181], off offset:64
	global_load_dwordx4 v[234:237], v[180:181], off
	v_addc_co_u32_e32 v143, vcc, 0, v181, vcc
	v_add_co_u32_e32 v150, vcc, 0xa0000, v180
	global_load_dwordx4 v[138:141], v[142:143], off offset:64
	s_nop 0
	global_load_dwordx4 v[142:145], v[142:143], off
	v_addc_co_u32_e32 v151, vcc, 0, v181, vcc
	v_add_co_u32_e32 v158, vcc, 0x90000, v180
	global_load_dwordx4 v[146:149], v[150:151], off offset:64
	s_nop 0
	global_load_dwordx4 v[150:153], v[150:151], off
	v_addc_co_u32_e32 v159, vcc, 0, v181, vcc
	v_add_co_u32_e32 v242, vcc, 0x80000, v180
	global_load_dwordx4 v[154:157], v[158:159], off offset:64
	s_nop 0
	global_load_dwordx4 v[158:161], v[158:159], off
	v_addc_co_u32_e32 v243, vcc, 0, v181, vcc
	global_load_dwordx4 v[162:165], v[242:243], off offset:64
	s_nop 0
	global_load_dwordx4 v[242:245], v[242:243], off
	s_waitcnt vmcnt(0)
	s_nop 0
	v_pk_fma_f32 v[232:233], v[124:125], v[132:133], v[232:233]
	v_pk_fma_f32 v[230:231], v[122:123], v[130:131], v[230:231]
	global_store_dwordx4 v[178:179], v[230:233], off offset:64
	v_pk_fma_f32 v[200:201], v[116:117], v[132:133], v[200:201]
	v_pk_fma_f32 v[198:199], v[114:115], v[130:131], v[198:199]
	v_add_co_u32_e32 v230, vcc, s12, v178
	v_pk_fma_f32 v[192:193], v[108:109], v[132:133], v[192:193]
	s_nop 0
	v_addc_co_u32_e32 v231, vcc, 0, v179, vcc
	global_store_dwordx4 v[230:231], v[198:201], off offset:64
	v_pk_fma_f32 v[190:191], v[106:107], v[130:131], v[190:191]
	v_pk_fma_f32 v[188:189], v[104:105], v[136:137], v[188:189]
	v_add_co_u32_e32 v198, vcc, s2, v178
	v_pk_fma_f32 v[186:187], v[102:103], v[134:135], v[186:187]
	s_nop 0
	v_addc_co_u32_e32 v199, vcc, 0, v179, vcc
	global_store_dwordx4 v[198:199], v[190:193], off offset:64
	s_mov_b32 s2, 0x80000
	v_pk_fma_f32 v[164:165], v[92:93], v[132:133], v[164:165]
	v_add_co_u32_e32 v190, vcc, s36, v178
	v_pk_fma_f32 v[162:163], v[90:91], v[130:131], v[162:163]
	s_nop 0
	v_addc_co_u32_e32 v191, vcc, 0, v179, vcc
	global_store_dwordx4 v[190:191], v[186:189], off
	v_pk_fma_f32 v[156:157], v[84:85], v[132:133], v[156:157]
	v_pk_fma_f32 v[154:155], v[82:83], v[130:131], v[154:155]
	v_add_co_u32_e32 v186, vcc, s2, v178
	s_mov_b32 s2, 0x90000
	s_nop 0
	v_addc_co_u32_e32 v187, vcc, 0, v179, vcc
	global_store_dwordx4 v[186:187], v[162:165], off offset:64
	v_pk_fma_f32 v[148:149], v[76:77], v[132:133], v[148:149]
	v_pk_fma_f32 v[146:147], v[74:75], v[130:131], v[146:147]
	v_add_co_u32_e32 v162, vcc, s2, v178
	s_mov_b32 s2, 0xa0000
	s_nop 0
	v_addc_co_u32_e32 v163, vcc, 0, v179, vcc
	global_store_dwordx4 v[162:163], v[154:157], off offset:64
	v_pk_fma_f32 v[168:169], v[100:101], v[132:133], v[168:169]
	v_pk_fma_f32 v[166:167], v[98:99], v[130:131], v[166:167]
	v_add_co_u32_e32 v154, vcc, s2, v178
	v_pk_fma_f32 v[236:237], v[128:129], v[136:137], v[236:237]
	s_nop 0
	v_addc_co_u32_e32 v155, vcc, 0, v179, vcc
	global_store_dwordx4 v[154:155], v[146:149], off offset:64
	v_pk_fma_f32 v[234:235], v[126:127], v[134:135], v[234:235]
	v_pk_fma_f32 v[228:229], v[120:121], v[136:137], v[228:229]
	v_add_co_u32_e32 v146, vcc, 0xb0000, v178
	v_pk_fma_f32 v[226:227], v[118:119], v[134:135], v[226:227]
	v_pk_fma_f32 v[196:197], v[112:113], v[136:137], v[196:197]
	v_pk_fma_f32 v[194:195], v[110:111], v[134:135], v[194:195]
	global_store_dwordx4 v[190:191], v[166:169], off offset:64
	v_pk_fma_f32 v[160:161], v[88:89], v[136:137], v[160:161]
	v_pk_fma_f32 v[158:159], v[86:87], v[134:135], v[158:159]
	v_pk_fma_f32 v[168:169], v[96:97], v[136:137], v[244:245]
	v_pk_fma_f32 v[166:167], v[94:95], v[134:135], v[242:243]
	v_pk_fma_f32 v[152:153], v[80:81], v[136:137], v[152:153]
	v_pk_fma_f32 v[150:151], v[78:79], v[134:135], v[150:151]
	v_pk_fma_f32 v[144:145], v[72:73], v[136:137], v[144:145]
	v_pk_fma_f32 v[142:143], v[70:71], v[134:135], v[142:143]
	v_addc_co_u32_e32 v147, vcc, 0, v179, vcc
	global_store_dwordx4 v[178:179], v[234:237], off
	global_store_dwordx4 v[230:231], v[226:229], off
	global_store_dwordx4 v[198:199], v[194:197], off
	global_store_dwordx4 v[186:187], v[166:169], off
	global_store_dwordx4 v[162:163], v[158:161], off
	global_store_dwordx4 v[154:155], v[150:153], off
	global_store_dwordx4 v[146:147], v[142:145], off
	v_pk_fma_f32 v[140:141], v[68:69], v[132:133], v[140:141]
	v_pk_fma_f32 v[138:139], v[66:67], v[130:131], v[138:139]
	s_mov_b64 s[2:3], 0

.LBB0_191:
	s_setprio 0
	s_waitcnt vmcnt(0)
	s_cmpk_gt_u32 s49, 0xff
	s_cbranch_scc1 .LBB0_193
	s_barrier

.LBB0_196:
	s_cmp_gt_i32 s97, 1
	s_mov_b64 s[0:1], -1
	s_cbranch_scc0 .LBB0_350
	s_cmp_gt_i32 s97, 2
	s_cbranch_scc0 .LBB0_204
	v_lshrrev_b32_e32 v2, 6, v202
	s_nop 0
	v_readfirstlane_b32 s0, v2
	s_cmp_gt_u32 s0, 2
	s_cbranch_scc1 .Lscan_done
	v_readlane_b32 s1, v252, 19
	s_lshr_b32 s1, s1, 9
	s_mul_i32 s1, s1, 3
	s_add_i32 s70, s1, s0
	s_lshr_b32 s71, s56, 9
	s_mul_i32 s71, s71, 3
	s_cmpk_lt_u32 s70, 0x300
	s_cbranch_scc0 .Lscan_done
.Lscan_loop:
	s_lshl_b32 s1, s70, 6
	s_cmp_ge_u32 s1, 0x6000
	s_cselect_b32 s2, 1, 0
	s_cselect_b32 s3, 0x6000, 0
	s_sub_u32 s3, s1, s3
	s_lshr_b32 s12, s3, 12
	s_and_b32 s3, s3, 0xfff
	v_readlane_b32 s14, v254, 13
	v_readlane_b32 s15, v254, 14
	v_readlane_b32 s16, v254, 15
	v_readlane_b32 s17, v254, 16
	s_mul_i32 s13, s62, 6
	s_add_i32 s13, s13, s12
	s_lshl_b32 s13, s13, 2
	s_cmp_lg_u32 s2, 0
	s_cselect_b32 s14, s16, s14
	s_cselect_b32 s15, s17, s15
	s_load_dword s18, s[14:15], s13
	s_mul_i32 s13, s2, 6
	s_add_i32 s13, s13, s12
	s_lshl_b32 s13, s13, 12
	s_add_i32 s13, s13, s3
	v_and_b32_e32 v2, 63, v202
	v_add_u32_e32 v2, s13, v2
	v_lshlrev_b32_e32 v3, 2, v2
	v_lshlrev_b32_e32 v4, 1, v2
	s_cmp_lg_u32 s2, 0
	s_mov_b32 s0, 0x1800000
	s_cselect_b32 s0, 0x1830000, s0
	s_mov_b32 s60, 0x30000
	s_cselect_b32 s60, 0xfffd0000, s60
	s_cselect_b32 s61, -1, 0
	s_cselect_b32 s64, 0, 0xfe7a0000
	s_cselect_b32 s65, 0, -1
	s_mov_b32 s1, 0xc00000
	s_cselect_b32 s1, 0xc18000, s1
	s_mov_b32 s66, 0x18000
	s_cselect_b32 s66, 0xfffe8000, s66
	s_cselect_b32 s67, -1, 0
	s_cselect_b32 s68, 0, 0xff3d0000
	s_cselect_b32 s69, 0, -1
	s_add_u32 s14, s8, 0x15234000
	s_addc_u32 s15, s9, 0
	s_add_u32 s14, s14, s0
	s_addc_u32 s15, s15, 0
	s_add_u32 s16, s8, 0x139d4000
	s_addc_u32 s17, s9, 0
	s_add_u32 s16, s16, s1
	s_addc_u32 s17, s17, 0
	global_load_dword v10, v3, s[14:15]
	s_add_u32 s14, s14, s60
	s_addc_u32 s15, s15, s61
	global_load_dword v11, v3, s[14:15]
	s_add_u32 s14, s14, s60
	s_addc_u32 s15, s15, s61
	s_add_u32 s14, s14, s64
	s_addc_u32 s15, s15, s65
	global_load_dword v12, v3, s[14:15]
	s_add_u32 s14, s14, s60
	s_addc_u32 s15, s15, s61
	global_load_dword v13, v3, s[14:15]
	s_add_u32 s14, s14, s60
	s_addc_u32 s15, s15, s61
	global_load_dword v14, v3, s[14:15]
	s_add_u32 s14, s14, s60
	s_addc_u32 s15, s15, s61
	global_load_dword v15, v3, s[14:15]
	s_add_u32 s14, s14, s60
	s_addc_u32 s15, s15, s61
	global_load_dword v16, v3, s[14:15]
	s_add_u32 s14, s14, s60
	s_addc_u32 s15, s15, s61
	global_load_dword v17, v3, s[14:15]
	s_add_u32 s14, s14, s60
	s_addc_u32 s15, s15, s61
	global_load_dword v18, v3, s[14:15]
	s_add_u32 s14, s14, s60
	s_addc_u32 s15, s15, s61
	global_load_dword v19, v3, s[14:15]
	s_add_u32 s14, s14, s60
	s_addc_u32 s15, s15, s61
	global_load_dword v20, v3, s[14:15]
	s_add_u32 s14, s14, s60
	s_addc_u32 s15, s15, s61
	global_load_dword v21, v3, s[14:15]
	s_add_u32 s14, s14, s60
	s_addc_u32 s15, s15, s61
	global_load_dword v22, v3, s[14:15]
	s_add_u32 s14, s14, s60
	s_addc_u32 s15, s15, s61
	global_load_dword v23, v3, s[14:15]
	s_add_u32 s14, s14, s60
	s_addc_u32 s15, s15, s61
	global_load_dword v24, v3, s[14:15]
	s_add_u32 s14, s14, s60
	s_addc_u32 s15, s15, s61
	global_load_dword v25, v3, s[14:15]
	s_add_u32 s14, s14, s60
	s_addc_u32 s15, s15, s61
	global_load_dword v26, v3, s[14:15]
	s_add_u32 s14, s14, s60
	s_addc_u32 s15, s15, s61
	global_load_dword v27, v3, s[14:15]
	s_add_u32 s14, s14, s60
	s_addc_u32 s15, s15, s61
	global_load_dword v28, v3, s[14:15]
	s_add_u32 s14, s14, s60
	s_addc_u32 s15, s15, s61
	global_load_dword v29, v3, s[14:15]
	s_add_u32 s14, s14, s60
	s_addc_u32 s15, s15, s61
	global_load_dword v30, v3, s[14:15]
	s_add_u32 s14, s14, s60
	s_addc_u32 s15, s15, s61
	global_load_dword v31, v3, s[14:15]
	s_add_u32 s14, s14, s60
	s_addc_u32 s15, s15, s61
	global_load_dword v32, v3, s[14:15]
	s_add_u32 s14, s14, s60
	s_addc_u32 s15, s15, s61
	global_load_dword v33, v3, s[14:15]
	s_add_u32 s14, s14, s60
	s_addc_u32 s15, s15, s61
	global_load_dword v34, v3, s[14:15]
	s_add_u32 s14, s14, s60
	s_addc_u32 s15, s15, s61
	global_load_dword v35, v3, s[14:15]
	s_add_u32 s14, s14, s60
	s_addc_u32 s15, s15, s61
	global_load_dword v36, v3, s[14:15]
	s_add_u32 s14, s14, s60
	s_addc_u32 s15, s15, s61
	global_load_dword v37, v3, s[14:15]
	s_add_u32 s14, s14, s60
	s_addc_u32 s15, s15, s61
	global_load_dword v38, v3, s[14:15]
	s_add_u32 s14, s14, s60
	s_addc_u32 s15, s15, s61
	global_load_dword v39, v3, s[14:15]
	s_add_u32 s14, s14, s60
	s_addc_u32 s15, s15, s61
	global_load_dword v40, v3, s[14:15]
	s_add_u32 s14, s14, s60
	s_addc_u32 s15, s15, s61
	global_load_dword v41, v3, s[14:15]
	s_add_u32 s14, s14, s60
	s_addc_u32 s15, s15, s61
	global_load_dword v42, v3, s[14:15]
	s_add_u32 s14, s14, s60
	s_addc_u32 s15, s15, s61
	global_load_dword v43, v3, s[14:15]
	s_add_u32 s14, s14, s60
	s_addc_u32 s15, s15, s61
	global_load_dword v44, v3, s[14:15]
	s_add_u32 s14, s14, s60
	s_addc_u32 s15, s15, s61
	global_load_dword v45, v3, s[14:15]
	s_add_u32 s14, s14, s60
	s_addc_u32 s15, s15, s61
	global_load_dword v46, v3, s[14:15]
	s_add_u32 s14, s14, s60
	s_addc_u32 s15, s15, s61
	global_load_dword v47, v3, s[14:15]
	s_add_u32 s14, s14, s60
	s_addc_u32 s15, s15, s61
	global_load_dword v48, v3, s[14:15]
	s_add_u32 s14, s14, s60
	s_addc_u32 s15, s15, s61
	global_load_dword v49, v3, s[14:15]
	s_add_u32 s14, s14, s60
	s_addc_u32 s15, s15, s61
	global_load_dword v50, v3, s[14:15]
	s_add_u32 s14, s14, s60
	s_addc_u32 s15, s15, s61
	global_load_dword v51, v3, s[14:15]
	s_add_u32 s14, s14, s60
	s_addc_u32 s15, s15, s61
	global_load_dword v52, v3, s[14:15]
	s_add_u32 s14, s14, s60
	s_addc_u32 s15, s15, s61
	global_load_dword v53, v3, s[14:15]
	s_add_u32 s14, s14, s60
	s_addc_u32 s15, s15, s61
	global_load_dword v54, v3, s[14:15]
	s_add_u32 s14, s14, s60
	s_addc_u32 s15, s15, s61
	global_load_dword v55, v3, s[14:15]
	s_add_u32 s14, s14, s60
	s_addc_u32 s15, s15, s61
	global_load_dword v56, v3, s[14:15]
	s_add_u32 s14, s14, s60
	s_addc_u32 s15, s15, s61
	global_load_dword v57, v3, s[14:15]
	s_add_u32 s14, s14, s60
	s_addc_u32 s15, s15, s61
	global_load_dword v58, v3, s[14:15]
	s_add_u32 s14, s14, s60
	s_addc_u32 s15, s15, s61
	global_load_dword v59, v3, s[14:15]
	s_add_u32 s14, s14, s60
	s_addc_u32 s15, s15, s61
	global_load_dword v60, v3, s[14:15]
	s_add_u32 s14, s14, s60
	s_addc_u32 s15, s15, s61
	global_load_dword v61, v3, s[14:15]
	s_add_u32 s14, s14, s60
	s_addc_u32 s15, s15, s61
	global_load_dword v62, v3, s[14:15]
	s_add_u32 s14, s14, s60
	s_addc_u32 s15, s15, s61
	global_load_dword v63, v3, s[14:15]
	s_add_u32 s14, s14, s60
	s_addc_u32 s15, s15, s61
	global_load_dword v64, v3, s[14:15]
	s_add_u32 s14, s14, s60
	s_addc_u32 s15, s15, s61
	global_load_dword v65, v3, s[14:15]
	s_add_u32 s14, s14, s60
	s_addc_u32 s15, s15, s61
	global_load_dword v66, v3, s[14:15]
	s_add_u32 s14, s14, s60
	s_addc_u32 s15, s15, s61
	global_load_dword v67, v3, s[14:15]
	s_add_u32 s14, s14, s60
	s_addc_u32 s15, s15, s61
	global_load_dword v68, v3, s[14:15]
	s_add_u32 s14, s14, s60
	s_addc_u32 s15, s15, s61
	global_load_dword v69, v3, s[14:15]
	s_add_u32 s14, s14, s60
	s_addc_u32 s15, s15, s61
	global_load_dword v70, v3, s[14:15]
	s_add_u32 s14, s14, s60
	s_addc_u32 s15, s15, s61
	global_load_dword v71, v3, s[14:15]
	s_add_u32 s14, s14, s60
	s_addc_u32 s15, s15, s61
	global_load_dword v72, v3, s[14:15]
	s_add_u32 s14, s14, s60
	s_addc_u32 s15, s15, s61
	global_load_dword v73, v3, s[14:15]
	s_add_u32 s14, s14, s60
	s_addc_u32 s15, s15, s61
	global_load_dword v74, v3, s[14:15]
	s_add_u32 s14, s14, s60
	s_addc_u32 s15, s15, s61
	global_load_dword v75, v3, s[14:15]
	s_add_u32 s14, s14, s60
	s_addc_u32 s15, s15, s61
	global_load_dword v76, v3, s[14:15]
	s_add_u32 s14, s14, s60
	s_addc_u32 s15, s15, s61
	global_load_dword v77, v3, s[14:15]
	s_add_u32 s14, s14, s60
	s_addc_u32 s15, s15, s61
	global_load_dword v78, v3, s[14:15]
	s_add_u32 s14, s14, s60
	s_addc_u32 s15, s15, s61
	global_load_dword v79, v3, s[14:15]
	s_add_u32 s14, s14, s60
	s_addc_u32 s15, s15, s61
	global_load_dword v80, v3, s[14:15]
	s_add_u32 s14, s14, s60
	s_addc_u32 s15, s15, s61
	global_load_dword v81, v3, s[14:15]
	s_add_u32 s14, s14, s60
	s_addc_u32 s15, s15, s61
	global_load_dword v82, v3, s[14:15]
	s_add_u32 s14, s14, s60
	s_addc_u32 s15, s15, s61
	global_load_dword v83, v3, s[14:15]
	s_add_u32 s14, s14, s60
	s_addc_u32 s15, s15, s61
	global_load_dword v84, v3, s[14:15]
	s_add_u32 s14, s14, s60
	s_addc_u32 s15, s15, s61
	global_load_dword v85, v3, s[14:15]
	s_add_u32 s14, s14, s60
	s_addc_u32 s15, s15, s61
	global_load_dword v86, v3, s[14:15]
	s_add_u32 s14, s14, s60
	s_addc_u32 s15, s15, s61
	global_load_dword v87, v3, s[14:15]
	s_add_u32 s14, s14, s60
	s_addc_u32 s15, s15, s61
	global_load_dword v88, v3, s[14:15]
	s_add_u32 s14, s14, s60
	s_addc_u32 s15, s15, s61
	global_load_dword v89, v3, s[14:15]
	s_add_u32 s14, s14, s60
	s_addc_u32 s15, s15, s61
	global_load_dword v90, v3, s[14:15]
	s_add_u32 s14, s14, s60
	s_addc_u32 s15, s15, s61
	global_load_dword v91, v3, s[14:15]
	s_add_u32 s14, s14, s60
	s_addc_u32 s15, s15, s61
	global_load_dword v92, v3, s[14:15]
	s_add_u32 s14, s14, s60
	s_addc_u32 s15, s15, s61
	global_load_dword v93, v3, s[14:15]
	s_add_u32 s14, s14, s60
	s_addc_u32 s15, s15, s61
	global_load_dword v94, v3, s[14:15]
	s_add_u32 s14, s14, s60
	s_addc_u32 s15, s15, s61
	global_load_dword v95, v3, s[14:15]
	s_add_u32 s14, s14, s60
	s_addc_u32 s15, s15, s61
	global_load_dword v96, v3, s[14:15]
	s_add_u32 s14, s14, s60
	s_addc_u32 s15, s15, s61
	global_load_dword v97, v3, s[14:15]
	s_add_u32 s14, s14, s60
	s_addc_u32 s15, s15, s61
	global_load_dword v98, v3, s[14:15]
	s_add_u32 s14, s14, s60
	s_addc_u32 s15, s15, s61
	global_load_dword v99, v3, s[14:15]
	s_add_u32 s14, s14, s60
	s_addc_u32 s15, s15, s61
	global_load_dword v100, v3, s[14:15]
	s_add_u32 s14, s14, s60
	s_addc_u32 s15, s15, s61
	global_load_dword v101, v3, s[14:15]
	s_add_u32 s14, s14, s60
	s_addc_u32 s15, s15, s61
	global_load_dword v102, v3, s[14:15]
	s_add_u32 s14, s14, s60
	s_addc_u32 s15, s15, s61
	global_load_dword v103, v3, s[14:15]
	s_add_u32 s14, s14, s60
	s_addc_u32 s15, s15, s61
	global_load_dword v104, v3, s[14:15]
	s_add_u32 s14, s14, s60
	s_addc_u32 s15, s15, s61
	global_load_dword v105, v3, s[14:15]
	s_add_u32 s14, s14, s60
	s_addc_u32 s15, s15, s61
	global_load_dword v106, v3, s[14:15]
	s_add_u32 s14, s14, s60
	s_addc_u32 s15, s15, s61
	global_load_dword v107, v3, s[14:15]
	s_add_u32 s14, s14, s60
	s_addc_u32 s15, s15, s61
	global_load_dword v108, v3, s[14:15]
	s_add_u32 s14, s14, s60
	s_addc_u32 s15, s15, s61
	global_load_dword v109, v3, s[14:15]
	s_add_u32 s14, s14, s60
	s_addc_u32 s15, s15, s61
	global_load_dword v110, v3, s[14:15]
	s_add_u32 s14, s14, s60
	s_addc_u32 s15, s15, s61
	global_load_dword v111, v3, s[14:15]
	s_add_u32 s14, s14, s60
	s_addc_u32 s15, s15, s61
	global_load_dword v112, v3, s[14:15]
	s_add_u32 s14, s14, s60
	s_addc_u32 s15, s15, s61
	global_load_dword v113, v3, s[14:15]
	s_add_u32 s14, s14, s60
	s_addc_u32 s15, s15, s61
	global_load_dword v114, v3, s[14:15]
	s_add_u32 s14, s14, s60
	s_addc_u32 s15, s15, s61
	global_load_dword v115, v3, s[14:15]
	s_add_u32 s14, s14, s60
	s_addc_u32 s15, s15, s61
	global_load_dword v116, v3, s[14:15]
	s_add_u32 s14, s14, s60
	s_addc_u32 s15, s15, s61
	global_load_dword v117, v3, s[14:15]
	s_add_u32 s14, s14, s60
	s_addc_u32 s15, s15, s61
	global_load_dword v118, v3, s[14:15]
	s_add_u32 s14, s14, s60
	s_addc_u32 s15, s15, s61
	global_load_dword v119, v3, s[14:15]
	s_add_u32 s14, s14, s60
	s_addc_u32 s15, s15, s61
	global_load_dword v120, v3, s[14:15]
	s_add_u32 s14, s14, s60
	s_addc_u32 s15, s15, s61
	global_load_dword v121, v3, s[14:15]
	s_add_u32 s14, s14, s60
	s_addc_u32 s15, s15, s61
	global_load_dword v122, v3, s[14:15]
	s_add_u32 s14, s14, s60
	s_addc_u32 s15, s15, s61
	global_load_dword v123, v3, s[14:15]
	s_add_u32 s14, s14, s60
	s_addc_u32 s15, s15, s61
	global_load_dword v124, v3, s[14:15]
	s_add_u32 s14, s14, s60
	s_addc_u32 s15, s15, s61
	global_load_dword v125, v3, s[14:15]
	s_add_u32 s14, s14, s60
	s_addc_u32 s15, s15, s61
	global_load_dword v126, v3, s[14:15]
	s_add_u32 s14, s14, s60
	s_addc_u32 s15, s15, s61
	global_load_dword v127, v3, s[14:15]
	s_add_u32 s14, s14, s60
	s_addc_u32 s15, s15, s61
	global_load_dword v128, v3, s[14:15]
	s_add_u32 s14, s14, s60
	s_addc_u32 s15, s15, s61
	global_load_dword v129, v3, s[14:15]
	s_add_u32 s14, s14, s60
	s_addc_u32 s15, s15, s61
	global_load_dword v130, v3, s[14:15]
	s_add_u32 s14, s14, s60
	s_addc_u32 s15, s15, s61
	global_load_dword v131, v3, s[14:15]
	s_add_u32 s14, s14, s60
	s_addc_u32 s15, s15, s61
	global_load_dword v132, v3, s[14:15]
	s_add_u32 s14, s14, s60
	s_addc_u32 s15, s15, s61
	global_load_dword v133, v3, s[14:15]
	s_add_u32 s14, s14, s60
	s_addc_u32 s15, s15, s61
	global_load_dword v134, v3, s[14:15]
	s_add_u32 s14, s14, s60
	s_addc_u32 s15, s15, s61
	global_load_dword v135, v3, s[14:15]
	s_add_u32 s14, s14, s60
	s_addc_u32 s15, s15, s61
	global_load_dword v136, v3, s[14:15]
	s_add_u32 s14, s14, s60
	s_addc_u32 s15, s15, s61
	global_load_dword v137, v3, s[14:15]
	s_add_u32 s14, s14, s60
	s_addc_u32 s15, s15, s61
	global_load_dword v138, v3, s[14:15]
	s_add_u32 s14, s14, s60
	s_addc_u32 s15, s15, s61
	global_load_dword v139, v3, s[14:15]
	s_add_u32 s14, s14, s60
	s_addc_u32 s15, s15, s61
	s_waitcnt lgkmcnt(0)
	v_mov_b32_e32 v5, s18
	v_mul_f32_e32 v5, 0x43000000, v5
	v_mul_f32_e32 v5, 0x3fb8aa3b, v5
	v_exp_f32_e32 v5, v5
	v_mov_b32_e32 v6, 0
	s_waitcnt vmcnt(63)
	v_cvt_pk_bf16_f32 v7, v6, v1
	global_store_short v4, v7, s[16:17]
	s_add_u32 s16, s16, s66
	s_addc_u32 s17, s17, s67
	v_fma_f32 v6, v6, v5, v10
	v_cvt_pk_bf16_f32 v8, v6, v1
	global_store_short v4, v8, s[16:17]
	s_add_u32 s16, s16, s66
	s_addc_u32 s17, s17, s67
	s_add_u32 s16, s16, s68
	s_addc_u32 s17, s17, s69
	v_fma_f32 v6, v6, v5, v11
	v_cvt_pk_bf16_f32 v7, v6, v1
	global_store_short v4, v7, s[16:17]
	s_add_u32 s16, s16, s66
	s_addc_u32 s17, s17, s67
	v_fma_f32 v6, v6, v5, v12
	v_cvt_pk_bf16_f32 v8, v6, v1
	global_store_short v4, v8, s[16:17]
	s_add_u32 s16, s16, s66
	s_addc_u32 s17, s17, s67
	v_fma_f32 v6, v6, v5, v13
	v_cvt_pk_bf16_f32 v7, v6, v1
	global_store_short v4, v7, s[16:17]
	s_add_u32 s16, s16, s66
	s_addc_u32 s17, s17, s67
	v_fma_f32 v6, v6, v5, v14
	v_cvt_pk_bf16_f32 v8, v6, v1
	global_store_short v4, v8, s[16:17]
	s_add_u32 s16, s16, s66
	s_addc_u32 s17, s17, s67
	v_fma_f32 v6, v6, v5, v15
	v_cvt_pk_bf16_f32 v7, v6, v1
	global_store_short v4, v7, s[16:17]
	s_add_u32 s16, s16, s66
	s_addc_u32 s17, s17, s67
	v_fma_f32 v6, v6, v5, v16
	v_cvt_pk_bf16_f32 v8, v6, v1
	global_store_short v4, v8, s[16:17]
	s_add_u32 s16, s16, s66
	s_addc_u32 s17, s17, s67
	v_fma_f32 v6, v6, v5, v17
	v_cvt_pk_bf16_f32 v7, v6, v1
	global_store_short v4, v7, s[16:17]
	s_add_u32 s16, s16, s66
	s_addc_u32 s17, s17, s67
	v_fma_f32 v6, v6, v5, v18
	v_cvt_pk_bf16_f32 v8, v6, v1
	global_store_short v4, v8, s[16:17]
	s_add_u32 s16, s16, s66
	s_addc_u32 s17, s17, s67
	v_fma_f32 v6, v6, v5, v19
	v_cvt_pk_bf16_f32 v7, v6, v1
	global_store_short v4, v7, s[16:17]
	s_add_u32 s16, s16, s66
	s_addc_u32 s17, s17, s67
	v_fma_f32 v6, v6, v5, v20
	v_cvt_pk_bf16_f32 v8, v6, v1
	global_store_short v4, v8, s[16:17]
	s_add_u32 s16, s16, s66
	s_addc_u32 s17, s17, s67
	v_fma_f32 v6, v6, v5, v21
	v_cvt_pk_bf16_f32 v7, v6, v1
	global_store_short v4, v7, s[16:17]
	s_add_u32 s16, s16, s66
	s_addc_u32 s17, s17, s67
	v_fma_f32 v6, v6, v5, v22
	v_cvt_pk_bf16_f32 v8, v6, v1
	global_store_short v4, v8, s[16:17]
	s_add_u32 s16, s16, s66
	s_addc_u32 s17, s17, s67
	v_fma_f32 v6, v6, v5, v23
	v_cvt_pk_bf16_f32 v7, v6, v1
	global_store_short v4, v7, s[16:17]
	s_add_u32 s16, s16, s66
	s_addc_u32 s17, s17, s67
	v_fma_f32 v6, v6, v5, v24
	v_cvt_pk_bf16_f32 v8, v6, v1
	global_store_short v4, v8, s[16:17]
	s_add_u32 s16, s16, s66
	s_addc_u32 s17, s17, s67
	v_fma_f32 v6, v6, v5, v25
	v_cvt_pk_bf16_f32 v7, v6, v1
	global_store_short v4, v7, s[16:17]
	s_add_u32 s16, s16, s66
	s_addc_u32 s17, s17, s67
	v_fma_f32 v6, v6, v5, v26
	v_cvt_pk_bf16_f32 v8, v6, v1
	global_store_short v4, v8, s[16:17]
	s_add_u32 s16, s16, s66
	s_addc_u32 s17, s17, s67
	v_fma_f32 v6, v6, v5, v27
	v_cvt_pk_bf16_f32 v7, v6, v1
	global_store_short v4, v7, s[16:17]
	s_add_u32 s16, s16, s66
	s_addc_u32 s17, s17, s67
	v_fma_f32 v6, v6, v5, v28
	v_cvt_pk_bf16_f32 v8, v6, v1
	global_store_short v4, v8, s[16:17]
	s_add_u32 s16, s16, s66
	s_addc_u32 s17, s17, s67
	v_fma_f32 v6, v6, v5, v29
	v_cvt_pk_bf16_f32 v7, v6, v1
	global_store_short v4, v7, s[16:17]
	s_add_u32 s16, s16, s66
	s_addc_u32 s17, s17, s67
	v_fma_f32 v6, v6, v5, v30
	v_cvt_pk_bf16_f32 v8, v6, v1
	global_store_short v4, v8, s[16:17]
	s_add_u32 s16, s16, s66
	s_addc_u32 s17, s17, s67
	v_fma_f32 v6, v6, v5, v31
	v_cvt_pk_bf16_f32 v7, v6, v1
	global_store_short v4, v7, s[16:17]
	s_add_u32 s16, s16, s66
	s_addc_u32 s17, s17, s67
	v_fma_f32 v6, v6, v5, v32
	v_cvt_pk_bf16_f32 v8, v6, v1
	global_store_short v4, v8, s[16:17]
	s_add_u32 s16, s16, s66
	s_addc_u32 s17, s17, s67
	v_fma_f32 v6, v6, v5, v33
	v_cvt_pk_bf16_f32 v7, v6, v1
	global_store_short v4, v7, s[16:17]
	s_add_u32 s16, s16, s66
	s_addc_u32 s17, s17, s67
	v_fma_f32 v6, v6, v5, v34
	v_cvt_pk_bf16_f32 v8, v6, v1
	global_store_short v4, v8, s[16:17]
	s_add_u32 s16, s16, s66
	s_addc_u32 s17, s17, s67
	v_fma_f32 v6, v6, v5, v35
	v_cvt_pk_bf16_f32 v7, v6, v1
	global_store_short v4, v7, s[16:17]
	s_add_u32 s16, s16, s66
	s_addc_u32 s17, s17, s67
	v_fma_f32 v6, v6, v5, v36
	v_cvt_pk_bf16_f32 v8, v6, v1
	global_store_short v4, v8, s[16:17]
	s_add_u32 s16, s16, s66
	s_addc_u32 s17, s17, s67
	v_fma_f32 v6, v6, v5, v37
	v_cvt_pk_bf16_f32 v7, v6, v1
	global_store_short v4, v7, s[16:17]
	s_add_u32 s16, s16, s66
	s_addc_u32 s17, s17, s67
	v_fma_f32 v6, v6, v5, v38
	v_cvt_pk_bf16_f32 v8, v6, v1
	global_store_short v4, v8, s[16:17]
	s_add_u32 s16, s16, s66
	s_addc_u32 s17, s17, s67
	v_fma_f32 v6, v6, v5, v39
	v_cvt_pk_bf16_f32 v7, v6, v1
	global_store_short v4, v7, s[16:17]
	s_add_u32 s16, s16, s66
	s_addc_u32 s17, s17, s67
	v_fma_f32 v6, v6, v5, v40
	v_cvt_pk_bf16_f32 v8, v6, v1
	global_store_short v4, v8, s[16:17]
	s_add_u32 s16, s16, s66
	s_addc_u32 s17, s17, s67
	v_fma_f32 v6, v6, v5, v41
	v_cvt_pk_bf16_f32 v7, v6, v1
	global_store_short v4, v7, s[16:17]
	s_add_u32 s16, s16, s66
	s_addc_u32 s17, s17, s67
	v_fma_f32 v6, v6, v5, v42
	v_cvt_pk_bf16_f32 v8, v6, v1
	global_store_short v4, v8, s[16:17]
	s_add_u32 s16, s16, s66
	s_addc_u32 s17, s17, s67
	v_fma_f32 v6, v6, v5, v43
	v_cvt_pk_bf16_f32 v7, v6, v1
	global_store_short v4, v7, s[16:17]
	s_add_u32 s16, s16, s66
	s_addc_u32 s17, s17, s67
	v_fma_f32 v6, v6, v5, v44
	v_cvt_pk_bf16_f32 v8, v6, v1
	global_store_short v4, v8, s[16:17]
	s_add_u32 s16, s16, s66
	s_addc_u32 s17, s17, s67
	v_fma_f32 v6, v6, v5, v45
	v_cvt_pk_bf16_f32 v7, v6, v1
	global_store_short v4, v7, s[16:17]
	s_add_u32 s16, s16, s66
	s_addc_u32 s17, s17, s67
	v_fma_f32 v6, v6, v5, v46
	v_cvt_pk_bf16_f32 v8, v6, v1
	global_store_short v4, v8, s[16:17]
	s_add_u32 s16, s16, s66
	s_addc_u32 s17, s17, s67
	v_fma_f32 v6, v6, v5, v47
	v_cvt_pk_bf16_f32 v7, v6, v1
	global_store_short v4, v7, s[16:17]
	s_add_u32 s16, s16, s66
	s_addc_u32 s17, s17, s67
	v_fma_f32 v6, v6, v5, v48
	v_cvt_pk_bf16_f32 v8, v6, v1
	global_store_short v4, v8, s[16:17]
	s_add_u32 s16, s16, s66
	s_addc_u32 s17, s17, s67
	v_fma_f32 v6, v6, v5, v49
	v_cvt_pk_bf16_f32 v7, v6, v1
	global_store_short v4, v7, s[16:17]
	s_add_u32 s16, s16, s66
	s_addc_u32 s17, s17, s67
	v_fma_f32 v6, v6, v5, v50
	v_cvt_pk_bf16_f32 v8, v6, v1
	global_store_short v4, v8, s[16:17]
	s_add_u32 s16, s16, s66
	s_addc_u32 s17, s17, s67
	v_fma_f32 v6, v6, v5, v51
	v_cvt_pk_bf16_f32 v7, v6, v1
	global_store_short v4, v7, s[16:17]
	s_add_u32 s16, s16, s66
	s_addc_u32 s17, s17, s67
	v_fma_f32 v6, v6, v5, v52
	v_cvt_pk_bf16_f32 v8, v6, v1
	global_store_short v4, v8, s[16:17]
	s_add_u32 s16, s16, s66
	s_addc_u32 s17, s17, s67
	v_fma_f32 v6, v6, v5, v53
	v_cvt_pk_bf16_f32 v7, v6, v1
	global_store_short v4, v7, s[16:17]
	s_add_u32 s16, s16, s66
	s_addc_u32 s17, s17, s67
	v_fma_f32 v6, v6, v5, v54
	v_cvt_pk_bf16_f32 v8, v6, v1
	global_store_short v4, v8, s[16:17]
	s_add_u32 s16, s16, s66
	s_addc_u32 s17, s17, s67
	v_fma_f32 v6, v6, v5, v55
	v_cvt_pk_bf16_f32 v7, v6, v1
	global_store_short v4, v7, s[16:17]
	s_add_u32 s16, s16, s66
	s_addc_u32 s17, s17, s67
	v_fma_f32 v6, v6, v5, v56
	v_cvt_pk_bf16_f32 v8, v6, v1
	global_store_short v4, v8, s[16:17]
	s_add_u32 s16, s16, s66
	s_addc_u32 s17, s17, s67
	v_fma_f32 v6, v6, v5, v57
	v_cvt_pk_bf16_f32 v7, v6, v1
	global_store_short v4, v7, s[16:17]
	s_add_u32 s16, s16, s66
	s_addc_u32 s17, s17, s67
	v_fma_f32 v6, v6, v5, v58
	v_cvt_pk_bf16_f32 v8, v6, v1
	global_store_short v4, v8, s[16:17]
	s_add_u32 s16, s16, s66
	s_addc_u32 s17, s17, s67
	v_fma_f32 v6, v6, v5, v59
	v_cvt_pk_bf16_f32 v7, v6, v1
	global_store_short v4, v7, s[16:17]
	s_add_u32 s16, s16, s66
	s_addc_u32 s17, s17, s67
	v_fma_f32 v6, v6, v5, v60
	v_cvt_pk_bf16_f32 v8, v6, v1
	global_store_short v4, v8, s[16:17]
	s_add_u32 s16, s16, s66
	s_addc_u32 s17, s17, s67
	v_fma_f32 v6, v6, v5, v61
	v_cvt_pk_bf16_f32 v7, v6, v1
	global_store_short v4, v7, s[16:17]
	s_add_u32 s16, s16, s66
	s_addc_u32 s17, s17, s67
	v_fma_f32 v6, v6, v5, v62
	v_cvt_pk_bf16_f32 v8, v6, v1
	global_store_short v4, v8, s[16:17]
	s_add_u32 s16, s16, s66
	s_addc_u32 s17, s17, s67
	v_fma_f32 v6, v6, v5, v63
	v_cvt_pk_bf16_f32 v7, v6, v1
	global_store_short v4, v7, s[16:17]
	s_add_u32 s16, s16, s66
	s_addc_u32 s17, s17, s67
	v_fma_f32 v6, v6, v5, v64
	v_cvt_pk_bf16_f32 v8, v6, v1
	global_store_short v4, v8, s[16:17]
	s_add_u32 s16, s16, s66
	s_addc_u32 s17, s17, s67
	v_fma_f32 v6, v6, v5, v65
	v_cvt_pk_bf16_f32 v7, v6, v1
	global_store_short v4, v7, s[16:17]
	s_add_u32 s16, s16, s66
	s_addc_u32 s17, s17, s67
	v_fma_f32 v6, v6, v5, v66
	v_cvt_pk_bf16_f32 v8, v6, v1
	global_store_short v4, v8, s[16:17]
	s_add_u32 s16, s16, s66
	s_addc_u32 s17, s17, s67
	v_fma_f32 v6, v6, v5, v67
	v_cvt_pk_bf16_f32 v7, v6, v1
	global_store_short v4, v7, s[16:17]
	s_add_u32 s16, s16, s66
	s_addc_u32 s17, s17, s67
	v_fma_f32 v6, v6, v5, v68
	v_cvt_pk_bf16_f32 v8, v6, v1
	global_store_short v4, v8, s[16:17]
	s_add_u32 s16, s16, s66
	s_addc_u32 s17, s17, s67
	v_fma_f32 v6, v6, v5, v69
	v_cvt_pk_bf16_f32 v7, v6, v1
	global_store_short v4, v7, s[16:17]
	s_add_u32 s16, s16, s66
	s_addc_u32 s17, s17, s67
	v_fma_f32 v6, v6, v5, v70
	v_cvt_pk_bf16_f32 v8, v6, v1
	global_store_short v4, v8, s[16:17]
	s_add_u32 s16, s16, s66
	s_addc_u32 s17, s17, s67
	v_fma_f32 v6, v6, v5, v71
	v_cvt_pk_bf16_f32 v7, v6, v1
	global_store_short v4, v7, s[16:17]
	s_add_u32 s16, s16, s66
	s_addc_u32 s17, s17, s67
	v_fma_f32 v6, v6, v5, v72
	v_cvt_pk_bf16_f32 v8, v6, v1
	global_store_short v4, v8, s[16:17]
	s_add_u32 s16, s16, s66
	s_addc_u32 s17, s17, s67
	v_fma_f32 v6, v6, v5, v73
	s_waitcnt vmcnt(63)
	v_cvt_pk_bf16_f32 v7, v6, v1
	global_store_short v4, v7, s[16:17]
	s_add_u32 s16, s16, s66
	s_addc_u32 s17, s17, s67
	v_fma_f32 v6, v6, v5, v74
	v_cvt_pk_bf16_f32 v8, v6, v1
	global_store_short v4, v8, s[16:17]
	s_add_u32 s16, s16, s66
	s_addc_u32 s17, s17, s67
	v_fma_f32 v6, v6, v5, v75
	v_cvt_pk_bf16_f32 v7, v6, v1
	global_store_short v4, v7, s[16:17]
	s_add_u32 s16, s16, s66
	s_addc_u32 s17, s17, s67
	v_fma_f32 v6, v6, v5, v76
	v_cvt_pk_bf16_f32 v8, v6, v1
	global_store_short v4, v8, s[16:17]
	s_add_u32 s16, s16, s66
	s_addc_u32 s17, s17, s67
	v_fma_f32 v6, v6, v5, v77
	v_cvt_pk_bf16_f32 v7, v6, v1
	global_store_short v4, v7, s[16:17]
	s_add_u32 s16, s16, s66
	s_addc_u32 s17, s17, s67
	v_fma_f32 v6, v6, v5, v78
	v_cvt_pk_bf16_f32 v8, v6, v1
	global_store_short v4, v8, s[16:17]
	s_add_u32 s16, s16, s66
	s_addc_u32 s17, s17, s67
	v_fma_f32 v6, v6, v5, v79
	v_cvt_pk_bf16_f32 v7, v6, v1
	global_store_short v4, v7, s[16:17]
	s_add_u32 s16, s16, s66
	s_addc_u32 s17, s17, s67
	v_fma_f32 v6, v6, v5, v80
	v_cvt_pk_bf16_f32 v8, v6, v1
	global_store_short v4, v8, s[16:17]
	s_add_u32 s16, s16, s66
	s_addc_u32 s17, s17, s67
	v_fma_f32 v6, v6, v5, v81
	v_cvt_pk_bf16_f32 v7, v6, v1
	global_store_short v4, v7, s[16:17]
	s_add_u32 s16, s16, s66
	s_addc_u32 s17, s17, s67
	v_fma_f32 v6, v6, v5, v82
	v_cvt_pk_bf16_f32 v8, v6, v1
	global_store_short v4, v8, s[16:17]
	s_add_u32 s16, s16, s66
	s_addc_u32 s17, s17, s67
	v_fma_f32 v6, v6, v5, v83
	v_cvt_pk_bf16_f32 v7, v6, v1
	global_store_short v4, v7, s[16:17]
	s_add_u32 s16, s16, s66
	s_addc_u32 s17, s17, s67
	v_fma_f32 v6, v6, v5, v84
	v_cvt_pk_bf16_f32 v8, v6, v1
	global_store_short v4, v8, s[16:17]
	s_add_u32 s16, s16, s66
	s_addc_u32 s17, s17, s67
	v_fma_f32 v6, v6, v5, v85
	v_cvt_pk_bf16_f32 v7, v6, v1
	global_store_short v4, v7, s[16:17]
	s_add_u32 s16, s16, s66
	s_addc_u32 s17, s17, s67
	v_fma_f32 v6, v6, v5, v86
	v_cvt_pk_bf16_f32 v8, v6, v1
	global_store_short v4, v8, s[16:17]
	s_add_u32 s16, s16, s66
	s_addc_u32 s17, s17, s67
	v_fma_f32 v6, v6, v5, v87
	v_cvt_pk_bf16_f32 v7, v6, v1
	global_store_short v4, v7, s[16:17]
	s_add_u32 s16, s16, s66
	s_addc_u32 s17, s17, s67
	v_fma_f32 v6, v6, v5, v88
	v_cvt_pk_bf16_f32 v8, v6, v1
	global_store_short v4, v8, s[16:17]
	s_add_u32 s16, s16, s66
	s_addc_u32 s17, s17, s67
	v_fma_f32 v6, v6, v5, v89
	v_cvt_pk_bf16_f32 v7, v6, v1
	global_store_short v4, v7, s[16:17]
	s_add_u32 s16, s16, s66
	s_addc_u32 s17, s17, s67
	v_fma_f32 v6, v6, v5, v90
	v_cvt_pk_bf16_f32 v8, v6, v1
	global_store_short v4, v8, s[16:17]
	s_add_u32 s16, s16, s66
	s_addc_u32 s17, s17, s67
	v_fma_f32 v6, v6, v5, v91
	v_cvt_pk_bf16_f32 v7, v6, v1
	global_store_short v4, v7, s[16:17]
	s_add_u32 s16, s16, s66
	s_addc_u32 s17, s17, s67
	v_fma_f32 v6, v6, v5, v92
	v_cvt_pk_bf16_f32 v8, v6, v1
	global_store_short v4, v8, s[16:17]
	s_add_u32 s16, s16, s66
	s_addc_u32 s17, s17, s67
	v_fma_f32 v6, v6, v5, v93
	v_cvt_pk_bf16_f32 v7, v6, v1
	global_store_short v4, v7, s[16:17]
	s_add_u32 s16, s16, s66
	s_addc_u32 s17, s17, s67
	v_fma_f32 v6, v6, v5, v94
	v_cvt_pk_bf16_f32 v8, v6, v1
	global_store_short v4, v8, s[16:17]
	s_add_u32 s16, s16, s66
	s_addc_u32 s17, s17, s67
	v_fma_f32 v6, v6, v5, v95
	v_cvt_pk_bf16_f32 v7, v6, v1
	global_store_short v4, v7, s[16:17]
	s_add_u32 s16, s16, s66
	s_addc_u32 s17, s17, s67
	v_fma_f32 v6, v6, v5, v96
	v_cvt_pk_bf16_f32 v8, v6, v1
	global_store_short v4, v8, s[16:17]
	s_add_u32 s16, s16, s66
	s_addc_u32 s17, s17, s67
	v_fma_f32 v6, v6, v5, v97
	v_cvt_pk_bf16_f32 v7, v6, v1
	global_store_short v4, v7, s[16:17]
	s_add_u32 s16, s16, s66
	s_addc_u32 s17, s17, s67
	v_fma_f32 v6, v6, v5, v98
	v_cvt_pk_bf16_f32 v8, v6, v1
	global_store_short v4, v8, s[16:17]
	s_add_u32 s16, s16, s66
	s_addc_u32 s17, s17, s67
	v_fma_f32 v6, v6, v5, v99
	v_cvt_pk_bf16_f32 v7, v6, v1
	global_store_short v4, v7, s[16:17]
	s_add_u32 s16, s16, s66
	s_addc_u32 s17, s17, s67
	v_fma_f32 v6, v6, v5, v100
	v_cvt_pk_bf16_f32 v8, v6, v1
	global_store_short v4, v8, s[16:17]
	s_add_u32 s16, s16, s66
	s_addc_u32 s17, s17, s67
	v_fma_f32 v6, v6, v5, v101
	v_cvt_pk_bf16_f32 v7, v6, v1
	global_store_short v4, v7, s[16:17]
	s_add_u32 s16, s16, s66
	s_addc_u32 s17, s17, s67
	v_fma_f32 v6, v6, v5, v102
	v_cvt_pk_bf16_f32 v8, v6, v1
	global_store_short v4, v8, s[16:17]
	s_add_u32 s16, s16, s66
	s_addc_u32 s17, s17, s67
	v_fma_f32 v6, v6, v5, v103
	v_cvt_pk_bf16_f32 v7, v6, v1
	global_store_short v4, v7, s[16:17]
	s_add_u32 s16, s16, s66
	s_addc_u32 s17, s17, s67
	v_fma_f32 v6, v6, v5, v104
	v_cvt_pk_bf16_f32 v8, v6, v1
	global_store_short v4, v8, s[16:17]
	s_add_u32 s16, s16, s66
	s_addc_u32 s17, s17, s67
	v_fma_f32 v6, v6, v5, v105
	v_cvt_pk_bf16_f32 v7, v6, v1
	global_store_short v4, v7, s[16:17]
	s_add_u32 s16, s16, s66
	s_addc_u32 s17, s17, s67
	v_fma_f32 v6, v6, v5, v106
	v_cvt_pk_bf16_f32 v8, v6, v1
	global_store_short v4, v8, s[16:17]
	s_add_u32 s16, s16, s66
	s_addc_u32 s17, s17, s67
	v_fma_f32 v6, v6, v5, v107
	v_cvt_pk_bf16_f32 v7, v6, v1
	global_store_short v4, v7, s[16:17]
	s_add_u32 s16, s16, s66
	s_addc_u32 s17, s17, s67
	v_fma_f32 v6, v6, v5, v108
	v_cvt_pk_bf16_f32 v8, v6, v1
	global_store_short v4, v8, s[16:17]
	s_add_u32 s16, s16, s66
	s_addc_u32 s17, s17, s67
	v_fma_f32 v6, v6, v5, v109
	v_cvt_pk_bf16_f32 v7, v6, v1
	global_store_short v4, v7, s[16:17]
	s_add_u32 s16, s16, s66
	s_addc_u32 s17, s17, s67
	v_fma_f32 v6, v6, v5, v110
	v_cvt_pk_bf16_f32 v8, v6, v1
	global_store_short v4, v8, s[16:17]
	s_add_u32 s16, s16, s66
	s_addc_u32 s17, s17, s67
	v_fma_f32 v6, v6, v5, v111
	v_cvt_pk_bf16_f32 v7, v6, v1
	global_store_short v4, v7, s[16:17]
	s_add_u32 s16, s16, s66
	s_addc_u32 s17, s17, s67
	v_fma_f32 v6, v6, v5, v112
	v_cvt_pk_bf16_f32 v8, v6, v1
	global_store_short v4, v8, s[16:17]
	s_add_u32 s16, s16, s66
	s_addc_u32 s17, s17, s67
	v_fma_f32 v6, v6, v5, v113
	v_cvt_pk_bf16_f32 v7, v6, v1
	global_store_short v4, v7, s[16:17]
	s_add_u32 s16, s16, s66
	s_addc_u32 s17, s17, s67
	v_fma_f32 v6, v6, v5, v114
	v_cvt_pk_bf16_f32 v8, v6, v1
	global_store_short v4, v8, s[16:17]
	s_add_u32 s16, s16, s66
	s_addc_u32 s17, s17, s67
	v_fma_f32 v6, v6, v5, v115
	v_cvt_pk_bf16_f32 v7, v6, v1
	global_store_short v4, v7, s[16:17]
	s_add_u32 s16, s16, s66
	s_addc_u32 s17, s17, s67
	v_fma_f32 v6, v6, v5, v116
	v_cvt_pk_bf16_f32 v8, v6, v1
	global_store_short v4, v8, s[16:17]
	s_add_u32 s16, s16, s66
	s_addc_u32 s17, s17, s67
	v_fma_f32 v6, v6, v5, v117
	v_cvt_pk_bf16_f32 v7, v6, v1
	global_store_short v4, v7, s[16:17]
	s_add_u32 s16, s16, s66
	s_addc_u32 s17, s17, s67
	v_fma_f32 v6, v6, v5, v118
	v_cvt_pk_bf16_f32 v8, v6, v1
	global_store_short v4, v8, s[16:17]
	s_add_u32 s16, s16, s66
	s_addc_u32 s17, s17, s67
	v_fma_f32 v6, v6, v5, v119
	v_cvt_pk_bf16_f32 v7, v6, v1
	global_store_short v4, v7, s[16:17]
	s_add_u32 s16, s16, s66
	s_addc_u32 s17, s17, s67
	v_fma_f32 v6, v6, v5, v120
	v_cvt_pk_bf16_f32 v8, v6, v1
	global_store_short v4, v8, s[16:17]
	s_add_u32 s16, s16, s66
	s_addc_u32 s17, s17, s67
	v_fma_f32 v6, v6, v5, v121
	v_cvt_pk_bf16_f32 v7, v6, v1
	global_store_short v4, v7, s[16:17]
	s_add_u32 s16, s16, s66
	s_addc_u32 s17, s17, s67
	v_fma_f32 v6, v6, v5, v122
	v_cvt_pk_bf16_f32 v8, v6, v1
	global_store_short v4, v8, s[16:17]
	s_add_u32 s16, s16, s66
	s_addc_u32 s17, s17, s67
	v_fma_f32 v6, v6, v5, v123
	v_cvt_pk_bf16_f32 v7, v6, v1
	global_store_short v4, v7, s[16:17]
	s_add_u32 s16, s16, s66
	s_addc_u32 s17, s17, s67
	v_fma_f32 v6, v6, v5, v124
	v_cvt_pk_bf16_f32 v8, v6, v1
	global_store_short v4, v8, s[16:17]
	s_add_u32 s16, s16, s66
	s_addc_u32 s17, s17, s67
	v_fma_f32 v6, v6, v5, v125
	v_cvt_pk_bf16_f32 v7, v6, v1
	global_store_short v4, v7, s[16:17]
	s_add_u32 s16, s16, s66
	s_addc_u32 s17, s17, s67
	v_fma_f32 v6, v6, v5, v126
	v_cvt_pk_bf16_f32 v8, v6, v1
	global_store_short v4, v8, s[16:17]
	s_add_u32 s16, s16, s66
	s_addc_u32 s17, s17, s67
	v_fma_f32 v6, v6, v5, v127
	v_cvt_pk_bf16_f32 v7, v6, v1
	global_store_short v4, v7, s[16:17]
	s_add_u32 s16, s16, s66
	s_addc_u32 s17, s17, s67
	v_fma_f32 v6, v6, v5, v128
	v_cvt_pk_bf16_f32 v8, v6, v1
	global_store_short v4, v8, s[16:17]
	s_add_u32 s16, s16, s66
	s_addc_u32 s17, s17, s67
	v_fma_f32 v6, v6, v5, v129
	v_cvt_pk_bf16_f32 v7, v6, v1
	global_store_short v4, v7, s[16:17]
	s_add_u32 s16, s16, s66
	s_addc_u32 s17, s17, s67
	v_fma_f32 v6, v6, v5, v130
	v_cvt_pk_bf16_f32 v8, v6, v1
	global_store_short v4, v8, s[16:17]
	s_add_u32 s16, s16, s66
	s_addc_u32 s17, s17, s67
	v_fma_f32 v6, v6, v5, v131
	v_cvt_pk_bf16_f32 v7, v6, v1
	global_store_short v4, v7, s[16:17]
	s_add_u32 s16, s16, s66
	s_addc_u32 s17, s17, s67
	v_fma_f32 v6, v6, v5, v132
	v_cvt_pk_bf16_f32 v8, v6, v1
	global_store_short v4, v8, s[16:17]
	s_add_u32 s16, s16, s66
	s_addc_u32 s17, s17, s67
	v_fma_f32 v6, v6, v5, v133
	v_cvt_pk_bf16_f32 v7, v6, v1
	global_store_short v4, v7, s[16:17]
	s_add_u32 s16, s16, s66
	s_addc_u32 s17, s17, s67
	v_fma_f32 v6, v6, v5, v134
	v_cvt_pk_bf16_f32 v8, v6, v1
	global_store_short v4, v8, s[16:17]
	s_add_u32 s16, s16, s66
	s_addc_u32 s17, s17, s67
	v_fma_f32 v6, v6, v5, v135
	v_cvt_pk_bf16_f32 v7, v6, v1
	global_store_short v4, v7, s[16:17]
	s_add_u32 s16, s16, s66
	s_addc_u32 s17, s17, s67
	v_fma_f32 v6, v6, v5, v136
	v_cvt_pk_bf16_f32 v8, v6, v1
	global_store_short v4, v8, s[16:17]
	s_add_u32 s16, s16, s66
	s_addc_u32 s17, s17, s67
	v_fma_f32 v6, v6, v5, v137
	v_cvt_pk_bf16_f32 v7, v6, v1
	global_store_short v4, v7, s[16:17]
	s_add_u32 s16, s16, s66
	s_addc_u32 s17, s17, s67
	v_fma_f32 v6, v6, v5, v138
	v_cvt_pk_bf16_f32 v8, v6, v1
	global_store_short v4, v8, s[16:17]
	s_add_u32 s16, s16, s66
	s_addc_u32 s17, s17, s67
	v_fma_f32 v6, v6, v5, v139
	s_add_i32 s70, s70, s71
	s_cmpk_lt_u32 s70, 0x300
	s_cbranch_scc1 .Lscan_loop
.Lscan_done:
.LBB0_203:
	s_or_b64 exec, exec, s[0:1]
	s_mov_b64 s[0:1], 0

.LBB0_245:
	s_or_b64 exec, exec, s[0:1]
	v_readlane_b32 s0, v252, 34
	v_readlane_b32 s1, v252, 35
	s_and_b64 s[0:1], s[0:1], s[50:51]
	s_ashr_i32 s3, s38, 6
	s_and_b32 s2, 0xffff, s34
	s_cmp_lg_u32 s2, 0
	s_cselect_b64 s[14:15], -1, 0
	s_cmp_lg_u64 s[14:15], 0
	v_readlane_b32 s2, v252, 37
	s_addc_u32 s2, s2, 0
	s_mul_hi_i32 s2, s2, 0x2aaaaaab
	s_lshr_b32 s12, s2, 31
	s_add_i32 s2, s2, s12
	s_ashr_i32 s12, s2, 31
	s_abs_i32 s2, s2
	v_cvt_f32_u32_e32 v0, s2
	v_readlane_b32 s13, v253, 58
	s_xor_b32 s77, s13, s12
	s_sub_i32 s13, 0, s2
	v_rcp_iflag_f32_e32 v0, v0
	v_readlane_b32 s18, v253, 59
	s_mov_b64 s[60:61], s[50:51]
	v_readlane_b32 s23, v252, 36
	v_mul_f32_e32 v0, 0x4f7ffffe, v0
	v_cvt_u32_f32_e32 v0, v0
	v_and_b32_e32 v139, 15, v138
	v_mov_b64_e32 v[2:3], s[8:9]
	v_readlane_b32 s46, v252, 38
	v_readfirstlane_b32 s16, v0
	s_mul_i32 s13, s13, s16
	s_mul_hi_u32 s13, s16, s13
	s_add_i32 s16, s16, s13
	s_mul_hi_u32 s13, s18, s16
	s_mul_i32 s17, s13, s2
	s_sub_i32 s17, s18, s17
	s_add_i32 s18, s13, 1
	s_sub_i32 s19, s17, s2
	s_cmp_ge_u32 s17, s2
	s_cselect_b32 s13, s18, s13
	s_cselect_b32 s17, s19, s17
	s_add_i32 s18, s13, 1
	s_cmp_ge_u32 s17, s2
	s_cselect_b32 s13, s18, s13
	s_xor_b32 s78, s13, s77
	v_readlane_b32 s13, v253, 61
	v_readlane_b32 s17, v253, 60
	s_xor_b32 s12, s13, s12
	s_mul_hi_u32 s13, s17, s16
	s_mul_i32 s16, s13, s2
	s_sub_i32 s16, s17, s16
	s_sub_i32 s22, s78, s77
	s_add_i32 s17, s13, 1
	s_sub_i32 s18, s16, s2
	s_cmp_ge_u32 s16, s2
	s_cselect_b32 s13, s17, s13
	s_cselect_b32 s16, s18, s16
	s_add_i32 s17, s13, 1
	s_cmp_ge_u32 s16, s2
	s_cselect_b32 s2, s17, s13
	s_xor_b32 s2, s2, s12
	s_sub_i32 s2, s2, s12
	s_sub_i32 s12, s2, s22
	s_lshl_b32 s13, s3, 4
	s_lshl_b32 s12, s12, 2
	s_and_b32 s34, s13, 48
	s_cmp_eq_u32 s3, s12
	s_cselect_b64 s[16:17], -1, 0
	s_ashr_i32 s79, s38, 8
	s_and_b64 s[50:51], s[0:1], s[16:17]
	s_add_i32 s92, s22, s79
	s_cmp_lt_i32 s3, s12
	s_cselect_b64 s[16:17], -1, 0
	s_and_b64 s[18:19], s[16:17], exec
	s_cselect_b32 s13, s92, s22
	s_lshl_b32 s13, s13, 6
	s_or_b32 s13, s13, s34
	s_and_b64 s[18:19], s[50:51], exec
	s_cselect_b32 s13, s23, s13
	v_or_b32_e32 v0, s13, v139
	v_mad_i64_i32 v[4:5], s[18:19], v0, s57, v[2:3]
	v_readlane_b32 s47, v252, 39
	v_and_b32_e32 v0, 48, v138
	s_mov_b64 s[48:49], 0xc404200
	v_lshl_add_u64 v[4:5], v[4:5], 0, s[46:47]
	v_lshl_add_u64 v[4:5], v[4:5], 0, v[0:1]
	s_mov_b32 s39, 0xc404000
	v_lshl_add_u64 v[6:7], v[4:5], 0, s[48:49]
	v_add_co_u32_e32 v4, vcc, s39, v4
	s_add_i32 s13, s3, 8
	s_nop 0
	v_addc_co_u32_e32 v5, vcc, 0, v5, vcc
	global_load_dwordx4 v[52:55], v[4:5], off offset:512
	global_load_dwordx4 v[56:59], v[6:7], off offset:64
	s_cmp_eq_u32 s13, s12
	s_cselect_b64 s[18:19], -1, 0
	s_ashr_i32 s80, s13, 2
	s_and_b64 s[68:69], s[0:1], s[18:19]
	s_add_i32 s55, s80, s22
	s_cmp_lt_i32 s13, s12
	s_cselect_b64 s[18:19], -1, 0
	s_and_b64 s[40:41], s[18:19], exec
	s_cselect_b32 s13, s55, s22
	s_lshl_b32 s13, s13, 6
	s_or_b32 s13, s13, s34
	s_and_b64 s[40:41], s[68:69], exec
	s_cselect_b32 s13, s23, s13
	v_or_b32_e32 v4, s13, v139
	v_mad_i64_i32 v[4:5], s[40:41], v4, s57, v[2:3]
	v_lshl_add_u64 v[4:5], v[4:5], 0, s[46:47]
	v_lshl_add_u64 v[4:5], v[4:5], 0, v[0:1]
	v_lshl_add_u64 v[6:7], v[4:5], 0, s[48:49]
	v_add_co_u32_e32 v4, vcc, s39, v4
	s_add_i32 s13, s3, 16
	s_nop 0
	v_addc_co_u32_e32 v5, vcc, 0, v5, vcc
	s_cmp_eq_u32 s13, s12
	s_cselect_b64 s[40:41], -1, 0
	s_ashr_i32 s81, s13, 2
	s_and_b64 s[66:67], s[0:1], s[40:41]
	s_add_i32 s54, s81, s22
	s_cmp_lt_i32 s13, s12
	s_cselect_b64 s[40:41], -1, 0
	s_and_b64 s[42:43], s[40:41], exec
	s_cselect_b32 s13, s54, s22
	s_lshl_b32 s13, s13, 6
	s_or_b32 s13, s13, s34
	s_and_b64 s[42:43], s[66:67], exec
	s_cselect_b32 s13, s23, s13
	v_and_b32_e32 v22, 63, v138
	v_lshl_or_b32 v23, s3, 8, v22
	v_and_b32_e32 v27, 31, v138
	v_bfe_u32 v157, v138, 4, 2
	v_and_b32_e32 v164, 3, v138
	v_lshlrev_b32_e32 v163, 1, v139
	v_bitop3_b32 v158, v157, v138, 3 bitop3:0x78
	v_bitop3_b32 v159, v157, v164, 4 bitop3:0x36
	global_load_dwordx4 v[60:63], v[4:5], off offset:512
	global_load_dwordx4 v[64:67], v[6:7], off offset:64
	v_or_b32_e32 v4, s13, v139
	v_mad_i64_i32 v[4:5], s[42:43], v4, s57, v[2:3]
	v_lshl_add_u64 v[4:5], v[4:5], 0, s[46:47]
	v_lshl_add_u64 v[4:5], v[4:5], 0, v[0:1]
	v_lshl_add_u64 v[8:9], v[4:5], 0, s[48:49]
	v_add_co_u32_e32 v4, vcc, s39, v4
	s_add_i32 s13, s3, 24
	s_nop 0
	v_addc_co_u32_e32 v5, vcc, 0, v5, vcc
	s_cmp_eq_u32 s13, s12
	s_cselect_b64 s[42:43], -1, 0
	s_ashr_i32 s82, s13, 2
	s_and_b64 s[64:65], s[0:1], s[42:43]
	s_add_i32 s35, s82, s22
	s_cmp_lt_i32 s13, s12
	s_cselect_b64 s[52:53], -1, 0
	s_and_b64 s[0:1], s[52:53], exec
	s_cselect_b32 s0, s35, s22
	s_lshl_b32 s0, s0, 6
	s_or_b32 s12, s0, s34
	s_and_b64 s[0:1], s[64:65], exec
	s_cselect_b32 s0, s23, s12
	v_or_b32_e32 v12, s0, v139
	v_mad_i64_i32 v[2:3], s[0:1], v12, s57, v[2:3]
	v_lshl_add_u64 v[2:3], v[2:3], 0, s[46:47]
	v_lshl_add_u64 v[2:3], v[2:3], 0, v[0:1]
	v_lshl_add_u64 v[16:17], v[2:3], 0, s[48:49]
	v_add_co_u32_e32 v2, vcc, s39, v2
	v_readlane_b32 s0, v252, 40
	s_nop 0
	v_addc_co_u32_e32 v3, vcc, 0, v3, vcc
	v_ashrrev_i32_e32 v0, 3, v23
	v_readlane_b32 s1, v252, 41
	v_xor_b32_e32 v24, v0, v138
	v_add_u32_e32 v0, 0x4000, v0
	s_lshl_b32 s12, s3, 2
	s_or_b32 s13, s12, 2
	s_mov_b64 s[46:47], 0x8000
	global_load_dwordx4 v[4:7], v[4:5], off offset:512
	s_nop 0
	global_load_dwordx4 v[8:11], v[8:9], off offset:64
	global_load_dwordx4 v[12:15], v[2:3], off offset:512
	s_nop 0
	global_load_dwordx4 v[16:19], v[16:17], off offset:64
	v_mov_b64_e32 v[2:3], s[0:1]
	v_mad_i64_i32 v[20:21], s[0:1], v0, s57, v[2:3]
	v_lshlrev_b32_e32 v0, 4, v24
	s_or_b32 s1, s12, 1
	v_and_b32_e32 v0, 0x70, v0
	s_lshl_b32 s0, s3, 12
	v_lshl_or_b32 v24, s1, 6, v22
	v_lshl_add_u64 v[20:21], v[20:21], 0, v[0:1]
	s_add_i32 s0, s0, 0
	v_ashrrev_i32_e32 v0, 3, v24
	s_mov_b32 m0, s0
	v_xor_b32_e32 v25, v0, v138
	v_add_u32_e32 v0, 0x4000, v0
	s_lshl_b32 s1, s1, 10
	s_add_i32 s1, s1, 0
	s_or_b32 s12, s12, 3
	s_lshl_b32 s3, s3, 10
	global_load_lds_dwordx4 v[20:21], off
	v_mad_i64_i32 v[20:21], s[42:43], v0, s57, v[2:3]
	v_lshlrev_b32_e32 v0, 4, v25
	v_and_b32_e32 v0, 0x70, v0
	v_lshl_or_b32 v25, s13, 6, v22
	v_lshl_add_u64 v[20:21], v[20:21], 0, v[0:1]
	v_ashrrev_i32_e32 v0, 3, v25
	s_mov_b32 m0, s1
	v_xor_b32_e32 v26, v0, v138
	v_add_u32_e32 v0, 0x4000, v0
	global_load_lds_dwordx4 v[20:21], off
	v_mad_i64_i32 v[20:21], s[42:43], v0, s57, v[2:3]
	v_lshlrev_b32_e32 v0, 4, v26
	v_and_b32_e32 v0, 0x70, v0
	s_lshl_b32 s13, s13, 10
	v_lshl_or_b32 v26, s12, 6, v22
	v_lshl_add_u64 v[20:21], v[20:21], 0, v[0:1]
	s_add_i32 s23, s13, 0
	v_ashrrev_i32_e32 v0, 3, v26
	s_mov_b32 m0, s23
	v_xor_b32_e32 v22, v0, v138
	v_add_u32_e32 v0, 0x4000, v0
	global_load_lds_dwordx4 v[20:21], off
	v_mad_i64_i32 v[20:21], s[42:43], v0, s57, v[2:3]
	v_lshlrev_b32_e32 v0, 4, v22
	s_lshl_b32 s12, s12, 10
	v_and_b32_e32 v0, 0x70, v0
	s_add_i32 s39, s12, 0
	v_readlane_b32 s12, v252, 44
	v_lshl_add_u64 v[20:21], v[20:21], 0, v[0:1]
	s_mov_b32 m0, s39
	v_ashrrev_i32_e32 v0, 5, v23
	v_readlane_b32 s13, v252, 45
	global_load_lds_dwordx4 v[20:21], off
	v_bitop3_b32 v28, v0, v27, 1 bitop3:0x6c
	v_mov_b64_e32 v[20:21], s[12:13]
	s_mov_b32 s12, 0x8200
	v_mad_i64_i32 v[22:23], s[42:43], v0, s12, v[20:21]
	v_lshlrev_b32_e32 v0, 4, v28
	v_lshl_add_u64 v[22:23], v[22:23], 0, v[0:1]
	v_ashrrev_i32_e32 v0, 5, v24
	v_lshl_add_u64 v[22:23], v[22:23], 0, s[46:47]
	s_add_i32 m0, s0, 0x8000
	v_bitop3_b32 v24, v0, v27, 3 bitop3:0x6c
	global_load_lds_dwordx4 v[22:23], off
	v_mad_i64_i32 v[22:23], s[42:43], v0, s12, v[20:21]
	v_lshlrev_b32_e32 v0, 4, v24
	v_lshl_add_u64 v[22:23], v[22:23], 0, v[0:1]
	v_ashrrev_i32_e32 v0, 5, v25
	v_lshl_add_u64 v[22:23], v[22:23], 0, s[46:47]
	s_add_i32 m0, s1, 0x8000
	v_bitop3_b32 v24, v0, v27, 5 bitop3:0x6c
	global_load_lds_dwordx4 v[22:23], off
	v_mad_i64_i32 v[22:23], s[0:1], v0, s12, v[20:21]
	v_lshlrev_b32_e32 v0, 4, v24
	v_lshl_add_u64 v[22:23], v[22:23], 0, v[0:1]
	v_ashrrev_i32_e32 v0, 5, v26
	v_lshl_add_u64 v[22:23], v[22:23], 0, s[46:47]
	s_add_i32 m0, s23, 0x8000
	v_bitop3_b32 v24, v0, v27, 7 bitop3:0x6c
	global_load_lds_dwordx4 v[22:23], off
	v_mad_i64_i32 v[22:23], s[0:1], v0, s12, v[20:21]
	v_lshlrev_b32_e32 v0, 4, v24
	v_lshl_add_u64 v[22:23], v[22:23], 0, v[0:1]
	v_bfrev_b32_e32 v0, -0.5
	v_med3_i32 v0, s2, 5, v0
	s_movk_i32 s1, 0xffc0
	v_readfirstlane_b32 s2, v0
	v_mov_b32_e32 v0, s38
	v_lshl_add_u64 v[22:23], v[22:23], 0, s[46:47]
	s_add_i32 m0, s39, 0x8000
	v_bfi_b32 v0, s1, v0, v138
	global_load_lds_dwordx4 v[22:23], off
	v_ashrrev_i32_e32 v23, 3, v0
	v_xor_b32_e32 v0, v23, v138
	v_lshlrev_b32_e32 v0, 4, v0
	v_med3_i32 v22, s22, 4, v216
	v_mad_i64_i32 v[2:3], s[22:23], v23, s57, v[2:3]
	v_and_b32_e32 v0, 0x70, v0
	v_readfirstlane_b32 s83, v22
	v_lshl_add_u64 v[76:77], v[2:3], 0, v[0:1]
	v_mad_i64_i32 v[2:3], s[22:23], v23, s12, v[20:21]
	s_add_i32 s0, s83, -4
	s_add_i32 s2, s2, 2
	v_readlane_b32 s22, v254, 38
	s_min_u32 s12, s0, s2
	v_readlane_b32 s23, v254, 39
	s_mul_i32 s22, s12, 0x5c000
	s_mov_b32 s13, s23
	v_lshl_add_u64 v[78:79], v[2:3], 0, v[0:1]
	v_lshl_add_u64 v[2:3], v[76:77], 0, s[22:23]
	s_add_i32 s1, s3, 0
	s_lshl_b32 s22, s12, 7
	v_writelane_b32 v254, s12, 38
	v_add_u32_e32 v0, -3, v22
	s_add_i32 m0, s1, 0x10000
	v_writelane_b32 v254, s13, 39
	v_min_u32_e32 v20, s2, v0
	s_mov_b32 s12, 0x5c000
	global_load_lds_dwordx4 v[2:3], off
	v_lshl_add_u64 v[2:3], v[78:79], 0, s[22:23]
	s_add_i32 m0, s1, 0x12000
	v_mul_lo_u32 v0, v20, s12
	global_load_lds_dwordx4 v[2:3], off
	v_lshl_add_u64 v[2:3], v[76:77], 0, v[0:1]
	s_add_i32 m0, s1, 0x14000
	v_lshlrev_b32_e32 v0, 7, v20
	global_load_lds_dwordx4 v[2:3], off
	v_lshl_add_u64 v[2:3], v[78:79], 0, v[0:1]
	v_add_u32_e32 v0, -2, v22
	v_min_u32_e32 v20, s2, v0
	s_add_i32 m0, s1, 0x16000
	v_mul_lo_u32 v0, v20, s12
	global_load_lds_dwordx4 v[2:3], off
	v_lshl_add_u64 v[2:3], v[76:77], 0, v[0:1]
	s_add_i32 m0, s1, 0x18000
	v_lshlrev_b32_e32 v0, 7, v20
	global_load_lds_dwordx4 v[2:3], off
	v_lshl_add_u64 v[2:3], v[78:79], 0, v[0:1]
	s_add_i32 m0, s1, 0x1a000
	s_cmp_le_u32 s0, s2
	global_load_lds_dwordx4 v[2:3], off
	s_cbranch_scc0 .LBB0_320
	v_med3_u32 v2, s34, 8, 40
	v_add_u32_e32 v3, -8, v2
	v_and_b32_e32 v22, 24, v163
	v_or_b32_e32 v23, v3, v164
	v_add_u32_e32 v22, v23, v22
	v_or_b32_e32 v23, 4, v157
	v_lshlrev_b32_e32 v80, 7, v22
	v_or_b32_e32 v22, 4, v22
	v_lshlrev_b32_e32 v0, 3, v157
	v_or_b32_e32 v20, s34, v139
	v_lshlrev_b32_e32 v83, 7, v22
	v_bitop3_b32 v24, v22, v157, 7 bitop3:0x6c
	v_bitop3_b32 v22, v22, v23, 7 bitop3:0x6c
	v_med3_u32 v20, v20, 8, 56
	v_lshlrev_b32_e32 v117, 4, v22
	v_add_u32_e32 v22, v3, v0
	v_lshrrev_b32_e32 v3, 3, v3
	v_add_u32_e32 v21, -8, v20
	v_add_u32_e32 v20, 8, v20
	v_add_u32_e32 v3, v3, v157
	v_cmp_ge_u32_e32 vcc, v22, v21
	v_cmp_lt_u32_e64 s[0:1], v22, v20
	v_or_b32_e32 v23, 1, v22
	v_bitop3_b32 v3, v3, v138, 7 bitop3:0x78
	s_and_b64 s[22:23], vcc, s[0:1]
	v_cmp_ge_u32_e32 vcc, v23, v21
	v_cmp_lt_u32_e64 s[0:1], v23, v20
	v_or_b32_e32 v23, 2, v22
	v_lshlrev_b32_e32 v119, 4, v3
	v_med3_i32 v3, s92, 4, v216
	s_and_b64 s[38:39], vcc, s[0:1]
	v_cmp_ge_u32_e32 vcc, v23, v21
	v_cmp_lt_u32_e64 s[0:1], v23, v20
	v_or_b32_e32 v23, 3, v22
	v_add_u32_e32 v120, -4, v3
	v_add_u32_e32 v121, 4, v3
	v_med3_i32 v3, s55, 4, v216
	s_and_b64 s[48:49], vcc, s[0:1]
	v_cmp_ge_u32_e32 vcc, v23, v21
	v_cmp_lt_u32_e64 s[0:1], v23, v20
	v_or_b32_e32 v23, 4, v22
	v_add_u32_e32 v122, -4, v3
	v_add_u32_e32 v123, 4, v3
	v_med3_i32 v3, s54, 4, v216
	s_and_b64 s[58:59], vcc, s[0:1]
	v_cmp_ge_u32_e32 vcc, v23, v21
	v_cmp_lt_u32_e64 s[0:1], v23, v20
	v_or_b32_e32 v23, 5, v22
	v_add_u32_e32 v124, -4, v3
	v_add_u32_e32 v125, 4, v3
	v_med3_i32 v3, s35, 4, v216
	s_and_b64 s[96:97], vcc, s[0:1]
	v_cmp_ge_u32_e32 vcc, v23, v21
	v_cmp_lt_u32_e64 s[0:1], v23, v20
	v_or_b32_e32 v23, 6, v22
	v_add_u32_e32 v126, -4, v3
	v_add_u32_e32 v127, 4, v3
	v_add3_u32 v3, v2, -1, v0
	s_and_b64 s[42:43], vcc, s[0:1]
	v_cmp_ge_u32_e32 vcc, v23, v21
	v_cmp_lt_u32_e64 s[0:1], v23, v20
	v_or_b32_e32 v23, 7, v22
	v_sub_u32_e32 v3, v3, v139
	s_and_b64 s[44:45], vcc, s[0:1]
	v_cmp_ge_u32_e32 vcc, v23, v21
	v_cmp_lt_u32_e64 s[0:1], v23, v20
	v_subrev_u32_e32 v3, s34, v3
	s_and_b64 s[46:47], vcc, s[0:1]
	v_med3_i32 v3, v3, -15, 15
	s_add_i32 s0, s78, s82
	v_lshlrev_b32_e32 v3, 2, v3
	s_mulk_i32 s0, 0x7c
	v_subrev_u32_e32 v20, s0, v3
	v_readlane_b32 s1, v254, 35
	v_lshlrev_b32_e32 v116, 4, v24
	s_add_i32 s77, s77, s83
	v_add_u32_e32 v128, s1, v20
	v_add3_u32 v20, v2, -2, v0
	v_sub_u32_e32 v20, v20, v139
	v_subrev_u32_e32 v20, s34, v20
	v_med3_i32 v20, v20, -15, 15
	v_lshlrev_b32_e32 v20, 2, v20
	v_subrev_u32_e32 v21, s0, v20
	v_add_u32_e32 v129, s1, v21
	v_add3_u32 v21, v2, -3, v0
	v_sub_u32_e32 v21, v21, v139
	v_subrev_u32_e32 v21, s34, v21
	v_med3_i32 v21, v21, -15, 15
	v_lshlrev_b32_e32 v21, 2, v21
	v_subrev_u32_e32 v23, s0, v21
	v_add_u32_e32 v130, s1, v23
	v_add3_u32 v23, v2, -4, v0
	v_sub_u32_e32 v23, v23, v139
	v_subrev_u32_e32 v23, s34, v23
	v_med3_i32 v23, v23, -15, 15
	v_lshlrev_b32_e32 v23, 2, v23
	v_subrev_u32_e32 v24, s0, v23
	v_add_u32_e32 v131, s1, v24
	v_add3_u32 v24, v2, -5, v0
	v_sub_u32_e32 v24, v24, v139
	v_subrev_u32_e32 v24, s34, v24
	v_med3_i32 v24, v24, -15, 15
	v_lshlrev_b32_e32 v24, 2, v24
	v_subrev_u32_e32 v25, s0, v24
	v_add_u32_e32 v132, s1, v25
	v_add3_u32 v25, v2, -6, v0
	v_add3_u32 v0, v2, -7, v0
	v_sub_u32_e32 v0, v0, v139
	v_subrev_u32_e32 v0, s34, v0
	v_med3_i32 v0, v0, -15, 15
	v_lshlrev_b32_e32 v0, 2, v0
	v_subrev_u32_e32 v2, s0, v0
	v_sub_u32_e32 v25, v25, v139
	v_add_u32_e32 v134, s1, v2
	v_sub_u32_e32 v2, v22, v139
	v_subrev_u32_e32 v25, s34, v25
	v_subrev_u32_e32 v2, s34, v2
	v_med3_i32 v25, v25, -15, 15
	v_med3_i32 v2, v2, -15, 15
	v_lshlrev_b32_e32 v25, 2, v25
	v_lshlrev_b32_e32 v2, 2, v2
	v_subrev_u32_e32 v26, s0, v25
	v_subrev_u32_e32 v22, s0, v2
	s_add_i32 s0, s78, s81
	s_mulk_i32 s0, 0x7c
	v_add_u32_e32 v135, s1, v22
	v_subrev_u32_e32 v22, s0, v3
	v_add_u32_e32 v142, s1, v22
	v_subrev_u32_e32 v22, s0, v20
	v_add_u32_e32 v143, s1, v22
	v_subrev_u32_e32 v22, s0, v21
	v_add_u32_e32 v144, s1, v22
	v_subrev_u32_e32 v22, s0, v23
	v_add_u32_e32 v145, s1, v22
	v_subrev_u32_e32 v22, s0, v24
	v_add_u32_e32 v146, s1, v22
	v_subrev_u32_e32 v22, s0, v25
	v_add_u32_e32 v147, s1, v22
	v_subrev_u32_e32 v22, s0, v0
	v_add_u32_e32 v148, s1, v22
	v_subrev_u32_e32 v22, s0, v2
	s_add_i32 s0, s78, s80
	s_mulk_i32 s0, 0x7c
	v_add_u32_e32 v149, s1, v22
	v_subrev_u32_e32 v22, s0, v3
	v_add_u32_e32 v150, s1, v22
	v_subrev_u32_e32 v22, s0, v20
	v_add_u32_e32 v151, s1, v22
	v_subrev_u32_e32 v22, s0, v21
	v_add_u32_e32 v152, s1, v22
	v_subrev_u32_e32 v22, s0, v23
	v_add_u32_e32 v153, s1, v22
	v_subrev_u32_e32 v22, s0, v24
	v_add_u32_e32 v154, s1, v22
	v_subrev_u32_e32 v22, s0, v25
	v_add_u32_e32 v155, s1, v22
	v_subrev_u32_e32 v22, s0, v0
	v_add_u32_e32 v162, s1, v22
	v_subrev_u32_e32 v22, s0, v2
	s_add_i32 s0, s78, s79
	s_mulk_i32 s0, 0x7c
	v_subrev_u32_e32 v3, s0, v3
	v_add_u32_e32 v168, s1, v3
	v_subrev_u32_e32 v3, s0, v20
	v_add_u32_e32 v169, s1, v3
	v_subrev_u32_e32 v3, s0, v21
	v_add_u32_e32 v170, s1, v3
	v_subrev_u32_e32 v3, s0, v23
	v_add_u32_e32 v171, s1, v3
	v_subrev_u32_e32 v3, s0, v24
	v_add_u32_e32 v172, s1, v3
	v_subrev_u32_e32 v3, s0, v25
	v_subrev_u32_e32 v0, s0, v0
	v_add_u32_e32 v173, s1, v3
	v_add_u32_e32 v174, s1, v0
	v_subrev_u32_e32 v0, s0, v2
	v_mov_b32_e32 v2, v1
	v_mov_b32_e32 v3, v1
	v_add_u32_e32 v133, s1, v26
	v_add_u32_e32 v167, s1, v22
	v_add_u32_e32 v175, s1, v0
	v_mov_b32_e32 v0, v1
	v_mov_b64_e32 v[86:87], v[2:3]
	v_mov_b64_e32 v[90:91], v[2:3]
	v_mov_b64_e32 v[94:95], v[2:3]
	v_mov_b64_e32 v[98:99], v[2:3]
	v_mov_b64_e32 v[114:115], v[2:3]
	v_mov_b64_e32 v[110:111], v[2:3]
	v_mov_b64_e32 v[106:107], v[2:3]
	v_mov_b64_e32 v[102:103], v[2:3]
	v_mov_b64_e32 v[22:23], v[2:3]
	v_mov_b64_e32 v[26:27], v[2:3]
	v_mov_b64_e32 v[34:35], v[2:3]
	v_mov_b64_e32 v[46:47], v[2:3]
	v_mov_b64_e32 v[30:31], v[2:3]
	v_mov_b64_e32 v[38:39], v[2:3]
	v_mov_b64_e32 v[42:43], v[2:3]
	v_mov_b64_e32 v[50:51], v[2:3]
	v_lshlrev_b32_e32 v81, 4, v158
	v_lshlrev_b32_e32 v82, 4, v159
	v_lshlrev_b32_e32 v118, 7, v139
	s_mulk_i32 s77, 0x7c
	s_add_i32 s79, s83, -5
	s_mov_b32 s78, 0
	v_mov_b32_e32 v165, 0xf149f2ca
	v_mov_b32_e32 v141, 0
	v_mov_b64_e32 v[84:85], v[0:1]
	v_mov_b64_e32 v[88:89], v[0:1]
	v_mov_b64_e32 v[92:93], v[0:1]
	v_mov_b64_e32 v[96:97], v[0:1]
	v_mov_b64_e32 v[112:113], v[0:1]
	v_mov_b64_e32 v[108:109], v[0:1]
	v_mov_b64_e32 v[104:105], v[0:1]
	v_mov_b64_e32 v[100:101], v[0:1]
	v_mov_b32_e32 v166, 0xf149f2ca
	v_mov_b32_e32 v140, 0
	v_mov_b64_e32 v[20:21], v[0:1]
	v_mov_b64_e32 v[24:25], v[0:1]
	v_mov_b64_e32 v[32:33], v[0:1]
	v_mov_b64_e32 v[44:45], v[0:1]
	v_mov_b32_e32 v161, 0xf149f2ca
	v_mov_b32_e32 v137, 0
	v_mov_b64_e32 v[28:29], v[0:1]
	v_mov_b64_e32 v[36:37], v[0:1]
	v_mov_b64_e32 v[40:41], v[0:1]
	v_mov_b64_e32 v[48:49], v[0:1]
	v_mov_b32_e32 v160, 0xf149f2ca
	v_mov_b32_e32 v136, 0
	v_mov_b32_e32 v0, 0
	v_mov_b32_e32 v177, 0xf149f2ca
	v_mov_b32_e32 v2, 0
	v_mov_b32_e32 v178, 0xf149f2ca
	v_mov_b32_e32 v3, 0
	v_mov_b32_e32 v179, 0xf149f2ca
	v_mov_b32_e32 v176, 0
	v_mov_b32_e32 v180, 0xf149f2ca
	s_branch .LBB0_249
.LBB0_247:
	s_or_b64 exec, exec, s[0:1]
	v_max3_f32 v70, v136, v181, v72
	v_max3_f32 v71, v182, v68, v69
	v_max3_f32 v75, v74, v73, v71
	v_max_f32_e32 v70, v70, v75
	v_mov_b32_e32 v71, v70
	s_nop 1
	v_permlane16_swap_b32_e32 v70, v71
	v_max_f32_e32 v70, v70, v71
	v_mov_b32_e32 v71, v70
	s_nop 1
	v_permlane32_swap_b32_e32 v70, v71
	v_max3_f32 v160, v177, v70, v71
	v_sub_f32_e32 v71, v181, v160
	v_exp_f32_e32 v71, v71
	v_sub_f32_e32 v136, v136, v160
	v_sub_f32_e32 v70, v177, v160
	v_exp_f32_e32 v177, v136
	v_sub_f32_e32 v136, v182, v160
	v_exp_f32_e32 v181, v136
	v_sub_f32_e32 v72, v72, v160
	v_exp_f32_e32 v72, v72
	v_sub_f32_e32 v74, v74, v160
	v_add_f32_e32 v75, 0, v71
	v_exp_f32_e32 v74, v74
	v_sub_f32_e32 v73, v73, v160
	v_add_f32_e32 v75, v177, v75
	v_exp_f32_e32 v73, v73
	v_sub_f32_e32 v69, v69, v160
	v_add_f32_e32 v75, v181, v75
	v_exp_f32_e32 v183, v69
	v_add_f32_e32 v75, v72, v75
	v_add_f32_e32 v75, v74, v75
	v_add_f32_e32 v75, v73, v75
	v_sub_f32_e32 v68, v68, v160
	v_add_f32_e32 v69, v183, v75
	v_exp_f32_e32 v75, v68
	v_exp_f32_e32 v182, v70
	v_cvt_pk_bf16_f32 v68, v71, v177
	v_cvt_pk_bf16_f32 v70, v74, v73
	v_add_f32_e32 v136, v75, v69
	v_fmac_f32_e32 v136, v0, v182
	v_cvt_pk_bf16_f32 v69, v181, v72
	v_cvt_pk_bf16_f32 v71, v183, v75
	v_pk_mul_f32 v[30:31], v[30:31], v[182:183] op_sel_hi:[1,0]
	v_pk_mul_f32 v[28:29], v[28:29], v[182:183] op_sel_hi:[1,0]
	v_pk_mul_f32 v[38:39], v[38:39], v[182:183] op_sel_hi:[1,0]
	v_pk_mul_f32 v[36:37], v[36:37], v[182:183] op_sel_hi:[1,0]
	s_waitcnt lgkmcnt(0)
	v_mfma_f32_16x16x32_bf16 v[28:31], v[226:229], v[68:71], v[28:31]
	v_pk_mul_f32 v[42:43], v[42:43], v[182:183] op_sel_hi:[1,0]
	v_pk_mul_f32 v[40:41], v[40:41], v[182:183] op_sel_hi:[1,0]
	v_mfma_f32_16x16x32_bf16 v[36:39], v[230:233], v[68:71], v[36:39]
	v_pk_mul_f32 v[50:51], v[50:51], v[182:183] op_sel_hi:[1,0]
	v_pk_mul_f32 v[48:49], v[48:49], v[182:183] op_sel_hi:[1,0]
	v_mfma_f32_16x16x32_bf16 v[40:43], v[234:237], v[68:71], v[40:43]
	v_mov_b32_e32 v177, v160
	v_mov_b32_e32 v0, v136
	v_mfma_f32_16x16x32_bf16 v[48:51], v[242:245], v[68:71], v[48:51]

.LBB0_249:
	s_add_i32 s0, s79, 4
	s_min_i32 s12, s0, s2
	v_mov_b32_e32 v68, 0x5c000
	v_mad_i64_i32 v[68:69], s[0:1], s12, v68, v[76:77]
	s_add_i32 s0, s78, 0xc000
	s_and_b32 s0, s0, 0xc000
	s_add_i32 s0, s0, 0
	s_add_i32 s13, s0, s3
	s_lshl_b32 s0, s12, 6
	s_waitcnt vmcnt(4)
	s_barrier
	s_add_i32 m0, s13, 0x10000
	s_ashr_i32 s1, s0, 31
	global_load_lds_dwordx4 v[68:69], off
	v_lshl_add_u64 v[68:69], s[0:1], 1, v[78:79]
	s_add_i32 m0, s13, 0x12000
	s_add_i32 s79, s79, 1
	global_load_lds_dwordx4 v[68:69], off
	s_and_b32 s12, s78, 0xc000
	v_cmp_ge_u32_e32 vcc, s79, v120
	s_add_i32 s80, s12, 0
	v_cmp_lt_u32_e64 s[0:1], s79, v121
	s_and_b64 s[82:83], s[16:17], vcc
	s_add_i32 s80, s80, 0x10000
	s_and_b64 s[0:1], s[82:83], s[0:1]
	v_add_u32_e32 v68, s80, v80
	v_add_u32_e32 v69, s80, v83
	s_andn2_b64 vcc, exec, s[0:1]
	v_add_u32_e32 v183, v68, v81
	v_add_u32_e32 v184, v68, v82
	v_add_u32_e32 v181, v69, v116
	v_add_u32_e32 v182, v69, v117
	s_cbranch_vccnz .LBB0_267
	ds_read_b128 v[68:71], v183
	ds_read_b128 v[72:75], v184
	ds_read_b128 v[198:201], v181
	ds_read_b128 v[186:189], v182
	v_add_u32_e32 v190, s77, v175
	ds_read_b32 v190, v190
	v_add_u32_e32 v191, s77, v174
	ds_read_b32 v191, v191
	v_add_u32_e32 v192, s77, v173
	ds_read_b32 v192, v192
	v_add_u32_e32 v193, s77, v172
	ds_read_b32 v193, v193
	v_add_u32_e32 v194, s77, v171
	ds_read_b32 v194, v194
	v_add_u32_e32 v195, s77, v170
	ds_read_b32 v195, v195
	v_add_u32_e32 v196, s77, v169
	ds_read_b32 v196, v196
	v_add_u32_e32 v197, s77, v168
	ds_read_b32 v197, v197
	v_add3_u32 v246, s80, v118, v119
	v_mov_b32_e32 v141, 0xf149f2ca
	v_mov_b32_e32 v185, 0xf149f2ca
	s_waitcnt lgkmcnt(10)
	v_mfma_f32_16x16x32_bf16 v[68:71], v[68:71], v[52:55], 0
	s_waitcnt lgkmcnt(8)
	v_mfma_f32_16x16x32_bf16 v[198:201], v[198:201], v[52:55], 0
	v_mfma_f32_16x16x32_bf16 v[72:75], v[72:75], v[56:59], v[68:71]
	v_mfma_f32_16x16x32_bf16 v[198:201], v[186:189], v[56:59], v[198:201]
	ds_read_b128 v[226:229], v246 offset:8192
	ds_read_b128 v[230:233], v246 offset:10240
	ds_read_b128 v[234:237], v246 offset:12288
	ds_read_b128 v[242:245], v246 offset:14336
	s_waitcnt lgkmcnt(4)
	s_nop 1
	v_add_f32_e32 v190, v72, v190
	v_cndmask_b32_e64 v185, v185, v190, s[22:23]
	v_add_f32_e32 v191, v73, v191
	v_cndmask_b32_e64 v141, v141, v191, s[38:39]
	v_mov_b32_e32 v72, 0xf149f2ca
	v_mov_b32_e32 v186, 0xf149f2ca
	v_add_f32_e32 v192, v74, v192
	v_cndmask_b32_e64 v186, v186, v192, s[48:49]
	v_add_f32_e32 v193, v75, v193
	v_cndmask_b32_e64 v72, v72, v193, s[58:59]
	v_mov_b32_e32 v73, 0xf149f2ca
	v_mov_b32_e32 v74, 0xf149f2ca
	v_add_f32_e32 v194, v198, v194
	v_cndmask_b32_e64 v74, v74, v194, s[96:97]
	v_add_f32_e32 v195, v199, v195
	v_cndmask_b32_e64 v73, v73, v195, s[42:43]
	v_mov_b32_e32 v68, 0xf149f2ca
	v_mov_b32_e32 v69, 0xf149f2ca
	v_add_f32_e32 v196, v200, v196
	v_cndmask_b32_e64 v69, v69, v196, s[44:45]
	v_add_f32_e32 v197, v201, v197
	v_cndmask_b32_e64 v68, v68, v197, s[46:47]
	v_max3_f32 v70, v141, v185, v72
	v_max3_f32 v71, v186, v68, v69
	v_max3_f32 v75, v74, v73, v71
	v_max_f32_e32 v70, v70, v75
	v_mov_b32_e32 v71, v70
	s_nop 1
	v_permlane16_swap_b32_e32 v70, v71
	v_max_f32_e32 v70, v70, v71
	v_mov_b32_e32 v71, v70
	s_nop 1
	v_permlane32_swap_b32_e32 v70, v71
	v_max3_f32 v165, v180, v70, v71
	v_sub_f32_e32 v71, v185, v165
	v_exp_f32_e32 v71, v71
	v_sub_f32_e32 v141, v141, v165
	v_exp_f32_e32 v185, v141
	v_sub_f32_e32 v141, v186, v165
	v_exp_f32_e32 v186, v141
	v_sub_f32_e32 v72, v72, v165
	v_exp_f32_e32 v72, v72
	v_sub_f32_e32 v74, v74, v165
	v_add_f32_e32 v75, 0, v71
	v_exp_f32_e32 v74, v74
	v_sub_f32_e32 v73, v73, v165
	v_add_f32_e32 v75, v185, v75
	v_exp_f32_e32 v73, v73
	v_sub_f32_e32 v69, v69, v165
	v_add_f32_e32 v75, v186, v75
	v_exp_f32_e32 v187, v69
	v_add_f32_e32 v75, v72, v75
	v_add_f32_e32 v75, v74, v75
	v_add_f32_e32 v75, v73, v75
	v_sub_f32_e32 v68, v68, v165
	v_sub_f32_e32 v70, v180, v165
	v_add_f32_e32 v69, v187, v75
	v_exp_f32_e32 v75, v68
	v_exp_f32_e32 v180, v70
	v_cvt_pk_bf16_f32 v68, v71, v185
	v_cvt_pk_bf16_f32 v70, v74, v73
	v_add_f32_e32 v141, v75, v69
	v_fmac_f32_e32 v141, v176, v180
	v_cvt_pk_bf16_f32 v69, v186, v72
	v_cvt_pk_bf16_f32 v71, v187, v75
	v_pk_mul_f32 v[102:103], v[102:103], v[180:181] op_sel_hi:[1,0]
	v_pk_mul_f32 v[100:101], v[100:101], v[180:181] op_sel_hi:[1,0]
	v_pk_mul_f32 v[106:107], v[106:107], v[180:181] op_sel_hi:[1,0]
	v_pk_mul_f32 v[104:105], v[104:105], v[180:181] op_sel_hi:[1,0]
	s_waitcnt lgkmcnt(0)
	v_mfma_f32_16x16x32_bf16 v[100:103], v[226:229], v[68:71], v[100:103]
	v_pk_mul_f32 v[110:111], v[110:111], v[180:181] op_sel_hi:[1,0]
	v_pk_mul_f32 v[108:109], v[108:109], v[180:181] op_sel_hi:[1,0]
	v_mfma_f32_16x16x32_bf16 v[104:107], v[230:233], v[68:71], v[104:107]
	v_pk_mul_f32 v[114:115], v[114:115], v[180:181] op_sel_hi:[1,0]
	v_pk_mul_f32 v[112:113], v[112:113], v[180:181] op_sel_hi:[1,0]
	v_mfma_f32_16x16x32_bf16 v[108:111], v[234:237], v[68:71], v[108:111]
	v_mov_b32_e32 v180, v165
	v_mov_b32_e32 v176, v141
	v_mfma_f32_16x16x32_bf16 v[112:115], v[242:245], v[68:71], v[112:115]
.LBB0_267:
	v_cmp_ge_u32_e32 vcc, s79, v122
	v_cmp_lt_u32_e64 s[0:1], s79, v123
	s_and_b64 s[82:83], s[18:19], vcc
	s_and_b64 s[0:1], s[82:83], s[0:1]
	s_andn2_b64 vcc, exec, s[0:1]
	s_cbranch_vccnz .LBB0_285
	ds_read_b128 v[68:71], v183
	ds_read_b128 v[72:75], v184
	ds_read_b128 v[198:201], v181
	ds_read_b128 v[186:189], v182
	v_add_u32_e32 v190, s77, v167
	ds_read_b32 v190, v190
	v_add_u32_e32 v191, s77, v162
	ds_read_b32 v191, v191
	v_add_u32_e32 v192, s77, v155
	ds_read_b32 v192, v192
	v_add_u32_e32 v193, s77, v154
	ds_read_b32 v193, v193
	v_add_u32_e32 v194, s77, v153
	ds_read_b32 v194, v194
	v_add_u32_e32 v195, s77, v152
	ds_read_b32 v195, v195
	v_add_u32_e32 v196, s77, v151
	ds_read_b32 v196, v196
	v_add_u32_e32 v197, s77, v150
	ds_read_b32 v197, v197
	v_add3_u32 v246, s80, v118, v119
	v_mov_b32_e32 v140, 0xf149f2ca
	v_mov_b32_e32 v185, 0xf149f2ca
	s_waitcnt lgkmcnt(10)
	v_mfma_f32_16x16x32_bf16 v[68:71], v[68:71], v[60:63], 0
	s_waitcnt lgkmcnt(8)
	v_mfma_f32_16x16x32_bf16 v[198:201], v[198:201], v[60:63], 0
	v_mfma_f32_16x16x32_bf16 v[72:75], v[72:75], v[64:67], v[68:71]
	v_mfma_f32_16x16x32_bf16 v[198:201], v[186:189], v[64:67], v[198:201]
	ds_read_b128 v[226:229], v246 offset:8192
	ds_read_b128 v[230:233], v246 offset:10240
	ds_read_b128 v[234:237], v246 offset:12288
	ds_read_b128 v[242:245], v246 offset:14336
	s_waitcnt lgkmcnt(4)
	s_nop 1
	v_add_f32_e32 v190, v72, v190
	v_cndmask_b32_e64 v185, v185, v190, s[22:23]
	v_add_f32_e32 v191, v73, v191
	v_cndmask_b32_e64 v140, v140, v191, s[38:39]
	v_mov_b32_e32 v72, 0xf149f2ca
	v_mov_b32_e32 v186, 0xf149f2ca
	v_add_f32_e32 v192, v74, v192
	v_cndmask_b32_e64 v186, v186, v192, s[48:49]
	v_add_f32_e32 v193, v75, v193
	v_cndmask_b32_e64 v72, v72, v193, s[58:59]
	v_mov_b32_e32 v73, 0xf149f2ca
	v_mov_b32_e32 v74, 0xf149f2ca
	v_add_f32_e32 v194, v198, v194
	v_cndmask_b32_e64 v74, v74, v194, s[96:97]
	v_add_f32_e32 v195, v199, v195
	v_cndmask_b32_e64 v73, v73, v195, s[42:43]
	v_mov_b32_e32 v68, 0xf149f2ca
	v_mov_b32_e32 v69, 0xf149f2ca
	v_add_f32_e32 v196, v200, v196
	v_cndmask_b32_e64 v69, v69, v196, s[44:45]
	v_add_f32_e32 v197, v201, v197
	v_cndmask_b32_e64 v68, v68, v197, s[46:47]
	v_max3_f32 v70, v140, v185, v72
	v_max3_f32 v71, v186, v68, v69
	v_max3_f32 v75, v74, v73, v71
	v_max_f32_e32 v70, v70, v75
	v_mov_b32_e32 v71, v70
	s_nop 1
	v_permlane16_swap_b32_e32 v70, v71
	v_max_f32_e32 v70, v70, v71
	v_mov_b32_e32 v71, v70
	s_nop 1
	v_permlane32_swap_b32_e32 v70, v71
	v_max3_f32 v166, v179, v70, v71
	v_sub_f32_e32 v71, v185, v166
	v_exp_f32_e32 v71, v71
	v_sub_f32_e32 v140, v140, v166
	v_sub_f32_e32 v70, v179, v166
	v_exp_f32_e32 v179, v140
	v_sub_f32_e32 v140, v186, v166
	v_exp_f32_e32 v185, v140
	v_sub_f32_e32 v72, v72, v166
	v_exp_f32_e32 v72, v72
	v_sub_f32_e32 v74, v74, v166
	v_add_f32_e32 v75, 0, v71
	v_exp_f32_e32 v74, v74
	v_sub_f32_e32 v73, v73, v166
	v_add_f32_e32 v75, v179, v75
	v_exp_f32_e32 v73, v73
	v_sub_f32_e32 v69, v69, v166
	v_add_f32_e32 v75, v185, v75
	v_exp_f32_e32 v187, v69
	v_add_f32_e32 v75, v72, v75
	v_add_f32_e32 v75, v74, v75
	v_add_f32_e32 v75, v73, v75
	v_sub_f32_e32 v68, v68, v166
	v_add_f32_e32 v69, v187, v75
	v_exp_f32_e32 v75, v68
	v_exp_f32_e32 v186, v70
	v_cvt_pk_bf16_f32 v68, v71, v179
	v_cvt_pk_bf16_f32 v70, v74, v73
	v_add_f32_e32 v140, v75, v69
	v_fmac_f32_e32 v140, v3, v186
	v_cvt_pk_bf16_f32 v69, v185, v72
	v_cvt_pk_bf16_f32 v71, v187, v75
	v_pk_mul_f32 v[94:95], v[94:95], v[186:187] op_sel_hi:[1,0]
	v_pk_mul_f32 v[92:93], v[92:93], v[186:187] op_sel_hi:[1,0]
	v_pk_mul_f32 v[90:91], v[90:91], v[186:187] op_sel_hi:[1,0]
	v_pk_mul_f32 v[88:89], v[88:89], v[186:187] op_sel_hi:[1,0]
	s_waitcnt lgkmcnt(0)
	v_mfma_f32_16x16x32_bf16 v[92:95], v[226:229], v[68:71], v[92:95]
	v_pk_mul_f32 v[86:87], v[86:87], v[186:187] op_sel_hi:[1,0]
	v_pk_mul_f32 v[84:85], v[84:85], v[186:187] op_sel_hi:[1,0]
	v_mfma_f32_16x16x32_bf16 v[88:91], v[230:233], v[68:71], v[88:91]
	v_pk_mul_f32 v[98:99], v[98:99], v[186:187] op_sel_hi:[1,0]
	v_pk_mul_f32 v[96:97], v[96:97], v[186:187] op_sel_hi:[1,0]
	v_mfma_f32_16x16x32_bf16 v[84:87], v[234:237], v[68:71], v[84:87]
	v_mov_b32_e32 v179, v166
	v_mov_b32_e32 v3, v140
	v_mfma_f32_16x16x32_bf16 v[96:99], v[242:245], v[68:71], v[96:99]
.LBB0_285:
	v_cmp_ge_u32_e32 vcc, s79, v124
	v_cmp_lt_u32_e64 s[0:1], s79, v125
	s_and_b64 s[82:83], s[40:41], vcc
	s_and_b64 s[0:1], s[82:83], s[0:1]
	s_andn2_b64 vcc, exec, s[0:1]
	s_cbranch_vccnz .LBB0_303
	ds_read_b128 v[68:71], v183
	ds_read_b128 v[72:75], v184
	ds_read_b128 v[198:201], v181
	ds_read_b128 v[186:189], v182
	v_add_u32_e32 v190, s77, v149
	ds_read_b32 v190, v190
	v_add_u32_e32 v191, s77, v148
	ds_read_b32 v191, v191
	v_add_u32_e32 v192, s77, v147
	ds_read_b32 v192, v192
	v_add_u32_e32 v193, s77, v146
	ds_read_b32 v193, v193
	v_add_u32_e32 v194, s77, v145
	ds_read_b32 v194, v194
	v_add_u32_e32 v195, s77, v144
	ds_read_b32 v195, v195
	v_add_u32_e32 v196, s77, v143
	ds_read_b32 v196, v196
	v_add_u32_e32 v197, s77, v142
	ds_read_b32 v197, v197
	v_add3_u32 v246, s80, v118, v119
	v_mov_b32_e32 v137, 0xf149f2ca
	v_mov_b32_e32 v185, 0xf149f2ca
	s_waitcnt lgkmcnt(10)
	v_mfma_f32_16x16x32_bf16 v[68:71], v[68:71], v[4:7], 0
	s_waitcnt lgkmcnt(8)
	v_mfma_f32_16x16x32_bf16 v[198:201], v[198:201], v[4:7], 0
	v_mfma_f32_16x16x32_bf16 v[72:75], v[72:75], v[8:11], v[68:71]
	v_mfma_f32_16x16x32_bf16 v[198:201], v[186:189], v[8:11], v[198:201]
	ds_read_b128 v[226:229], v246 offset:8192
	ds_read_b128 v[230:233], v246 offset:10240
	ds_read_b128 v[234:237], v246 offset:12288
	ds_read_b128 v[242:245], v246 offset:14336
	s_waitcnt lgkmcnt(4)
	s_nop 1
	v_add_f32_e32 v190, v72, v190
	v_cndmask_b32_e64 v185, v185, v190, s[22:23]
	v_add_f32_e32 v191, v73, v191
	v_cndmask_b32_e64 v137, v137, v191, s[38:39]
	v_mov_b32_e32 v72, 0xf149f2ca
	v_mov_b32_e32 v186, 0xf149f2ca
	v_add_f32_e32 v192, v74, v192
	v_cndmask_b32_e64 v186, v186, v192, s[48:49]
	v_add_f32_e32 v193, v75, v193
	v_cndmask_b32_e64 v72, v72, v193, s[58:59]
	v_mov_b32_e32 v73, 0xf149f2ca
	v_mov_b32_e32 v74, 0xf149f2ca
	v_add_f32_e32 v194, v198, v194
	v_cndmask_b32_e64 v74, v74, v194, s[96:97]
	v_add_f32_e32 v195, v199, v195
	v_cndmask_b32_e64 v73, v73, v195, s[42:43]
	v_mov_b32_e32 v68, 0xf149f2ca
	v_mov_b32_e32 v69, 0xf149f2ca
	v_add_f32_e32 v196, v200, v196
	v_cndmask_b32_e64 v69, v69, v196, s[44:45]
	v_add_f32_e32 v197, v201, v197
	v_cndmask_b32_e64 v68, v68, v197, s[46:47]
	v_max3_f32 v70, v137, v185, v72
	v_max3_f32 v71, v186, v68, v69
	v_max3_f32 v75, v74, v73, v71
	v_max_f32_e32 v70, v70, v75
	v_mov_b32_e32 v71, v70
	s_nop 1
	v_permlane16_swap_b32_e32 v70, v71
	v_max_f32_e32 v70, v70, v71
	v_mov_b32_e32 v71, v70
	s_nop 1
	v_permlane32_swap_b32_e32 v70, v71
	v_max3_f32 v161, v178, v70, v71
	v_sub_f32_e32 v71, v185, v161
	v_exp_f32_e32 v71, v71
	v_sub_f32_e32 v137, v137, v161
	v_exp_f32_e32 v185, v137
	v_sub_f32_e32 v137, v186, v161
	v_exp_f32_e32 v186, v137
	v_sub_f32_e32 v72, v72, v161
	v_exp_f32_e32 v72, v72
	v_sub_f32_e32 v74, v74, v161
	v_add_f32_e32 v75, 0, v71
	v_exp_f32_e32 v74, v74
	v_sub_f32_e32 v73, v73, v161
	v_add_f32_e32 v75, v185, v75
	v_exp_f32_e32 v73, v73
	v_sub_f32_e32 v69, v69, v161
	v_add_f32_e32 v75, v186, v75
	v_exp_f32_e32 v187, v69
	v_add_f32_e32 v75, v72, v75
	v_add_f32_e32 v75, v74, v75
	v_add_f32_e32 v75, v73, v75
	v_sub_f32_e32 v68, v68, v161
	v_sub_f32_e32 v70, v178, v161
	v_add_f32_e32 v69, v187, v75
	v_exp_f32_e32 v75, v68
	v_exp_f32_e32 v178, v70
	v_cvt_pk_bf16_f32 v68, v71, v185
	v_cvt_pk_bf16_f32 v70, v74, v73
	v_add_f32_e32 v137, v75, v69
	v_fmac_f32_e32 v137, v2, v178
	v_cvt_pk_bf16_f32 v69, v186, v72
	v_cvt_pk_bf16_f32 v71, v187, v75
	v_pk_mul_f32 v[22:23], v[22:23], v[178:179] op_sel_hi:[1,0]
	v_pk_mul_f32 v[20:21], v[20:21], v[178:179] op_sel_hi:[1,0]
	v_pk_mul_f32 v[26:27], v[26:27], v[178:179] op_sel_hi:[1,0]
	v_pk_mul_f32 v[24:25], v[24:25], v[178:179] op_sel_hi:[1,0]
	s_waitcnt lgkmcnt(0)
	v_mfma_f32_16x16x32_bf16 v[20:23], v[226:229], v[68:71], v[20:23]
	v_pk_mul_f32 v[34:35], v[34:35], v[178:179] op_sel_hi:[1,0]
	v_pk_mul_f32 v[32:33], v[32:33], v[178:179] op_sel_hi:[1,0]
	v_mfma_f32_16x16x32_bf16 v[24:27], v[230:233], v[68:71], v[24:27]
	v_pk_mul_f32 v[46:47], v[46:47], v[178:179] op_sel_hi:[1,0]
	v_pk_mul_f32 v[44:45], v[44:45], v[178:179] op_sel_hi:[1,0]
	v_mfma_f32_16x16x32_bf16 v[32:35], v[234:237], v[68:71], v[32:35]
	v_mov_b32_e32 v178, v161
	v_mov_b32_e32 v2, v137
	v_mfma_f32_16x16x32_bf16 v[44:47], v[242:245], v[68:71], v[44:47]

.LBB0_354:
	s_and_b64 vcc, exec, s[0:1]
	s_cbranch_vccnz .LBB0_482
	v_ashrrev_i32_e32 v0, 31, v10
	v_lshrrev_b32_e32 v0, 26, v0
	v_add_u32_e32 v0, v10, v0
	v_ashrrev_i32_e32 v11, 6, v0
	v_bfe_i32 v0, v10, 27, 1
	v_lshlrev_b32_e32 v2, 4, v10
	v_lshrrev_b32_e32 v0, 22, v0
	v_add_u32_e32 v0, v2, v0
	v_and_b32_e32 v0, 0xfffffc00, v0
	v_sub_u32_e32 v0, v2, v0
	v_lshrrev_b32_e32 v3, 4, v0
	v_bitop3_b32 v3, v3, v0, 32 bitop3:0x6c
	v_ashrrev_i32_e32 v0, 31, v0
	v_lshrrev_b32_e32 v0, 26, v0
	v_add_u32_e32 v0, v3, v0
	v_ashrrev_i32_e32 v12, 6, v0
	v_mul_i32_i24_e32 v5, 64, v12
	v_sub_u32_e32 v3, v3, v5
	v_lshlrev_b32_e32 v4, 3, v11
	v_lshlrev_b32_e32 v0, 5, v11
	v_ashrrev_i16_sdwa v3, v206, sext(v3) dst_sel:DWORD dst_unused:UNUSED_PAD src0_sel:DWORD src1_sel:BYTE_0
	v_and_b32_e32 v4, 0x1ffff0, v4
	v_and_b32_e32 v0, 32, v0
	v_bfe_i32 v13, v3, 0, 16
	v_add_u32_e32 v0, v0, v13
	v_add_lshl_u32 v3, v12, v4, 11
	v_add_u32_e32 v2, 0x2000, v2
	v_lshl_add_u32 v0, v0, 1, v3
	v_ashrrev_i32_e32 v3, 31, v2
	v_lshrrev_b32_e32 v3, 22, v3
	s_mul_i32 s1, s62, 0x1880000
	v_add_u32_e32 v3, v2, v3
	s_mul_hi_i32 s0, s62, 0x1880000
	s_add_u32 s23, s46, s1
	v_ashrrev_i32_e32 v14, 10, v3
	s_addc_u32 s34, s47, s0
	s_ashr_i32 s2, s22, 6
	v_mul_i32_i24_e32 v3, 0x400, v14
	s_lshl_b32 s0, s42, 8
	v_sub_u32_e32 v2, v2, v3
	s_ashr_i32 s3, s22, 8
	s_lshl_b32 s35, s2, 10
	s_or_b32 s0, s0, 1
	v_lshrrev_b32_e32 v3, 4, v2
	s_cmp_lt_i32 s42, 64
	v_bitop3_b32 v2, v3, v2, 32 bitop3:0x6c
	s_cselect_b32 s0, s0, 0x4003
	v_ashrrev_i32_e32 v4, 31, v2
	s_ashr_i32 s1, s0, 31
	v_lshrrev_b32_e32 v4, 26, v4
	s_lshl_b64 s[0:1], s[0:1], 11
	v_readlane_b32 s12, v252, 20
	v_add_u32_e32 v4, v2, v4
	v_readlane_b32 s13, v252, 21
	s_add_u32 s0, s12, s0
	v_ashrrev_i32_e32 v15, 6, v4
	v_and_b32_e32 v4, 0xc0, v4
	s_addc_u32 s1, s13, s1
	s_ashr_i32 s15, s14, 31
	v_sub_u32_e32 v2, v2, v4
	s_lshl_b64 s[16:17], s[14:15], 19
	v_lshlrev_b32_e32 v3, 3, v14
	v_lshlrev_b32_e32 v5, 5, v14
	v_ashrrev_i16_sdwa v2, v206, sext(v2) dst_sel:DWORD dst_unused:UNUSED_PAD src0_sel:DWORD src1_sel:BYTE_0
	s_add_u32 s16, s23, s16
	v_and_b32_e32 v3, 0x1ffff0, v3
	v_and_b32_e32 v5, 32, v5
	v_bfe_i32 v16, v2, 0, 16
	s_addc_u32 s17, s34, s17
	s_add_i32 s54, s35, 0
	v_add_u32_e32 v2, v5, v16
	v_add_lshl_u32 v3, v15, v3, 11
	s_add_i32 m0, s54, 0x10000
	v_lshl_add_u32 v154, v2, 1, v3
	v_lshrrev_b32_e32 v5, 7, v202
	v_and_b32_e32 v4, 60, v202
	v_bfe_u32 v6, v202, 2, 4
	v_or_b32_e32 v4, v4, v5
	v_lshl_or_b32 v5, v5, 4, v6
	v_sub_u32_e32 v4, v4, v5
	v_lshlrev_b32_e32 v4, 11, v4
	v_add_u32_e32 v250, v0, v4
	v_add_u32_e32 v251, v154, v4
	global_load_lds_dwordx4 v0, s[16:17]
	s_add_i32 m0, s54, 0x12000
	s_add_i32 s55, s54, 0x2000
	global_load_lds_dwordx4 v154, s[16:17]
	s_mov_b32 m0, s54
	s_add_u32 s18, s16, 0x40000
	global_load_lds_dwordx4 v250, s[0:1]
	s_mov_b32 m0, s55
	s_addc_u32 s19, s17, 0
	global_load_lds_dwordx4 v251, s[0:1]
	s_add_i32 m0, s54, 0x14000
	v_writelane_b32 v255, s50, 17
	global_load_lds_dwordx4 v0, s[18:19]
	s_add_i32 m0, s54, 0x16000
	v_mov_b32_e32 v155, v1
	global_load_lds_dwordx4 v154, s[18:19]
	s_add_u32 s18, s0, 0x40000
	s_addc_u32 s19, s1, 0
	s_add_i32 s58, s54, 0x4000
	s_mov_b32 m0, s58
	s_add_i32 s59, s54, 0x6000
	global_load_lds_dwordx4 v250, s[18:19]
	s_mov_b32 m0, s59
	v_writelane_b32 v255, s51, 18
	global_load_lds_dwordx4 v251, s[18:19]
	v_lshl_add_u64 v[8:9], s[16:17], 0, v[0:1]
	v_lshl_add_u64 v[6:7], s[16:17], 0, v[154:155]
	v_lshl_add_u64 v[4:5], s[0:1], 0, v[0:1]
	s_cmp_lg_u32 s3, 1
	v_lshl_add_u64 v[2:3], s[0:1], 0, v[154:155]
	s_cbranch_scc1 .LBB0_357
	s_setprio 1
	s_barrier

.LBB0_366:
	s_add_u32 s2, s0, 0xfffc0080
	s_addc_u32 s3, s1, -1
	s_add_i32 s12, 0, 0x10000
	v_add_u32_e32 v142, s12, v227
	ds_read_b128 v[130:133], v142
	ds_read_b128 v[134:137], v142 offset:1024
	ds_read_b128 v[138:141], v142 offset:2048
	ds_read_b128 v[142:145], v142 offset:3072
	s_cmp_eq_u32 s47, 12
	s_cselect_b32 s17, s15, s3
	s_cselect_b32 s16, s19, s2
	s_cselect_b32 s3, s43, s46
	s_cselect_b32 s2, s44, s45
	v_lshl_add_u64 v[190:191], s[0:1], 0, v[162:163]
	s_add_i32 m0, s54, 0xc000
	ds_read_b128 v[146:149], v233
	ds_read_b128 v[150:153], v233 offset:1024
	ds_read_b128 v[166:169], v233 offset:2048
	ds_read_b128 v[170:173], v233 offset:3072
	ds_read_b128 v[174:177], v233 offset:4096
	ds_read_b128 v[178:181], v233 offset:5120
	ds_read_b128 v[182:185], v233 offset:6144
	ds_read_b128 v[186:189], v233 offset:7168
	global_load_lds_dwordx4 v[190:191], off
	v_lshl_add_u64 v[190:191], s[0:1], 0, v[164:165]
	s_add_i32 m0, s54, 0xe000
	s_nop 0
	global_load_lds_dwordx4 v[190:191], off
	s_waitcnt lgkmcnt(8)
	s_barrier
	s_waitcnt lgkmcnt(0)
	s_waitcnt lgkmcnt(0)
	v_mfma_f32_16x16x32_bf16 v[126:129], v[130:133], v[146:149], v[126:129]
	v_mfma_f32_16x16x32_bf16 v[122:125], v[138:141], v[146:149], v[122:125]
	v_mfma_f32_16x16x32_bf16 v[118:121], v[130:133], v[166:169], v[118:121]
	v_mfma_f32_16x16x32_bf16 v[114:117], v[138:141], v[166:169], v[114:117]
	v_mfma_f32_16x16x32_bf16 v[110:113], v[130:133], v[174:177], v[110:113]
	v_mfma_f32_16x16x32_bf16 v[106:109], v[138:141], v[174:177], v[106:109]
	v_mfma_f32_16x16x32_bf16 v[102:105], v[130:133], v[182:185], v[102:105]
	v_mfma_f32_16x16x32_bf16 v[98:101], v[138:141], v[182:185], v[98:101]
	v_mfma_f32_16x16x32_bf16 v[126:129], v[134:137], v[150:153], v[126:129]
	v_mfma_f32_16x16x32_bf16 v[122:125], v[142:145], v[150:153], v[122:125]
	v_mfma_f32_16x16x32_bf16 v[118:121], v[134:137], v[170:173], v[118:121]
	v_mfma_f32_16x16x32_bf16 v[114:117], v[142:145], v[170:173], v[114:117]
	v_mfma_f32_16x16x32_bf16 v[110:113], v[134:137], v[178:181], v[110:113]
	v_mfma_f32_16x16x32_bf16 v[106:109], v[142:145], v[178:181], v[106:109]
	v_mfma_f32_16x16x32_bf16 v[102:105], v[134:137], v[186:189], v[102:105]
	v_mfma_f32_16x16x32_bf16 v[98:101], v[142:145], v[186:189], v[98:101]
	s_barrier
	s_add_i32 s13, 0, 0x14000
	s_add_i32 s12, s12, s35
	v_add_u32_e32 v234, s13, v227
	v_lshl_add_u64 v[242:243], s[2:3], 0, v[0:1]
	s_mov_b32 m0, s12
	ds_read_b128 v[190:193], v234
	ds_read_b128 v[194:197], v234 offset:1024
	ds_read_b128 v[198:201], v234 offset:2048
	ds_read_b128 v[234:237], v234 offset:3072
	global_load_lds_dwordx4 v[242:243], off
	v_lshl_add_u64 v[244:245], s[2:3], 0, v[154:155]
	s_add_i32 m0, s12, 0x2000
	s_nop 0
	global_load_lds_dwordx4 v[244:245], off
	s_barrier
	s_waitcnt lgkmcnt(0)
	s_waitcnt lgkmcnt(0)
	v_mfma_f32_16x16x32_bf16 v[62:65], v[190:193], v[146:149], v[62:65]
	v_mfma_f32_16x16x32_bf16 v[58:61], v[198:201], v[146:149], v[58:61]
	v_mfma_f32_16x16x32_bf16 v[54:57], v[190:193], v[166:169], v[54:57]
	v_mfma_f32_16x16x32_bf16 v[50:53], v[198:201], v[166:169], v[50:53]
	v_mfma_f32_16x16x32_bf16 v[46:49], v[190:193], v[174:177], v[46:49]
	v_mfma_f32_16x16x32_bf16 v[42:45], v[198:201], v[174:177], v[42:45]
	v_mfma_f32_16x16x32_bf16 v[38:41], v[190:193], v[182:185], v[38:41]
	v_mfma_f32_16x16x32_bf16 v[34:37], v[198:201], v[182:185], v[34:37]
	v_mfma_f32_16x16x32_bf16 v[62:65], v[194:197], v[150:153], v[62:65]
	v_mfma_f32_16x16x32_bf16 v[58:61], v[234:237], v[150:153], v[58:61]
	v_mfma_f32_16x16x32_bf16 v[54:57], v[194:197], v[170:173], v[54:57]
	v_mfma_f32_16x16x32_bf16 v[50:53], v[234:237], v[170:173], v[50:53]
	v_mfma_f32_16x16x32_bf16 v[46:49], v[194:197], v[178:181], v[46:49]
	v_mfma_f32_16x16x32_bf16 v[42:45], v[234:237], v[178:181], v[42:45]
	v_mfma_f32_16x16x32_bf16 v[38:41], v[194:197], v[186:189], v[38:41]
	v_mfma_f32_16x16x32_bf16 v[34:37], v[234:237], v[186:189], v[34:37]
	s_mov_b32 m0, s54
	s_nop 0
	s_barrier
	ds_read_b128 v[146:149], v233 offset:16384
	ds_read_b128 v[150:153], v233 offset:17408
	ds_read_b128 v[166:169], v233 offset:18432
	ds_read_b128 v[170:173], v233 offset:19456
	ds_read_b128 v[174:177], v233 offset:20480
	ds_read_b128 v[178:181], v233 offset:21504
	ds_read_b128 v[182:185], v233 offset:22528
	ds_read_b128 v[186:189], v233 offset:23552
	global_load_lds_dwordx4 v250, s[16:17]
	s_nop 0
	s_mov_b32 m0, s55
	s_nop 0
	global_load_lds_dwordx4 v251, s[16:17]
	s_barrier
	s_waitcnt lgkmcnt(0)
	s_waitcnt lgkmcnt(0)
	v_mfma_f32_16x16x32_bf16 v[94:97], v[130:133], v[146:149], v[94:97]
	v_mfma_f32_16x16x32_bf16 v[90:93], v[138:141], v[146:149], v[90:93]
	v_mfma_f32_16x16x32_bf16 v[86:89], v[130:133], v[166:169], v[86:89]
	v_mfma_f32_16x16x32_bf16 v[82:85], v[138:141], v[166:169], v[82:85]
	v_mfma_f32_16x16x32_bf16 v[78:81], v[130:133], v[174:177], v[78:81]
	v_mfma_f32_16x16x32_bf16 v[74:77], v[138:141], v[174:177], v[74:77]
	v_mfma_f32_16x16x32_bf16 v[70:73], v[130:133], v[182:185], v[70:73]
	v_mfma_f32_16x16x32_bf16 v[66:69], v[138:141], v[182:185], v[66:69]
	v_mfma_f32_16x16x32_bf16 v[94:97], v[134:137], v[150:153], v[94:97]
	v_mfma_f32_16x16x32_bf16 v[90:93], v[142:145], v[150:153], v[90:93]
	v_mfma_f32_16x16x32_bf16 v[86:89], v[134:137], v[170:173], v[86:89]
	v_mfma_f32_16x16x32_bf16 v[82:85], v[142:145], v[170:173], v[82:85]
	v_mfma_f32_16x16x32_bf16 v[78:81], v[134:137], v[178:181], v[78:81]
	v_mfma_f32_16x16x32_bf16 v[74:77], v[142:145], v[178:181], v[74:77]
	v_mfma_f32_16x16x32_bf16 v[70:73], v[134:137], v[186:189], v[70:73]
	v_mfma_f32_16x16x32_bf16 v[66:69], v[142:145], v[186:189], v[66:69]
	s_barrier
	s_add_u32 s78, s2, 0x40000
	s_addc_u32 s79, s3, 0
	s_add_i32 s12, s13, s35
	v_lshl_add_u64 v[130:131], s[78:79], 0, v[0:1]
	s_mov_b32 m0, s12
	s_nop 0
	global_load_lds_dwordx4 v[130:131], off
	v_lshl_add_u64 v[130:131], s[78:79], 0, v[154:155]
	s_add_i32 m0, s12, 0x2000
	s_nop 0
	global_load_lds_dwordx4 v[130:131], off
	s_waitcnt vmcnt(6)
	s_barrier
	v_mfma_f32_16x16x32_bf16 v[30:33], v[190:193], v[146:149], v[30:33]
	v_mfma_f32_16x16x32_bf16 v[26:29], v[198:201], v[146:149], v[26:29]
	v_mfma_f32_16x16x32_bf16 v[22:25], v[190:193], v[166:169], v[22:25]
	v_mfma_f32_16x16x32_bf16 v[18:21], v[198:201], v[166:169], v[18:21]
	v_mfma_f32_16x16x32_bf16 v[14:17], v[190:193], v[174:177], v[14:17]
	v_mfma_f32_16x16x32_bf16 v[10:13], v[198:201], v[174:177], v[10:13]
	v_mfma_f32_16x16x32_bf16 v[6:9], v[190:193], v[182:185], v[6:9]
	v_mfma_f32_16x16x32_bf16 v[2:5], v[198:201], v[182:185], v[2:5]
	v_mfma_f32_16x16x32_bf16 v[30:33], v[194:197], v[150:153], v[30:33]
	v_mfma_f32_16x16x32_bf16 v[26:29], v[234:237], v[150:153], v[26:29]
	v_mfma_f32_16x16x32_bf16 v[22:25], v[194:197], v[170:173], v[22:25]
	v_mfma_f32_16x16x32_bf16 v[18:21], v[234:237], v[170:173], v[18:21]
	v_mfma_f32_16x16x32_bf16 v[14:17], v[194:197], v[178:181], v[14:17]
	v_mfma_f32_16x16x32_bf16 v[10:13], v[234:237], v[178:181], v[10:13]
	v_mfma_f32_16x16x32_bf16 v[6:9], v[194:197], v[186:189], v[6:9]
	v_mfma_f32_16x16x32_bf16 v[2:5], v[234:237], v[186:189], v[2:5]
	s_add_i32 s12, 0, 0x18000
	v_add_u32_e32 v142, s12, v227
	s_barrier
	ds_read_b128 v[130:133], v142
	ds_read_b128 v[134:137], v142 offset:1024
	ds_read_b128 v[138:141], v142 offset:2048
	ds_read_b128 v[142:145], v142 offset:3072
	s_add_u32 s16, s16, 0x40000
	s_addc_u32 s17, s17, 0
	s_mov_b32 m0, s58
	s_nop 0
	ds_read_b128 v[146:149], v233 offset:32768
	ds_read_b128 v[150:153], v233 offset:33792
	ds_read_b128 v[166:169], v233 offset:34816
	ds_read_b128 v[170:173], v233 offset:35840
	ds_read_b128 v[174:177], v233 offset:36864
	ds_read_b128 v[178:181], v233 offset:37888
	ds_read_b128 v[182:185], v233 offset:38912
	ds_read_b128 v[186:189], v233 offset:39936
	global_load_lds_dwordx4 v250, s[16:17]
	s_nop 0
	s_mov_b32 m0, s59
	s_nop 0
	global_load_lds_dwordx4 v251, s[16:17]
	s_waitcnt lgkmcnt(8)
	s_barrier
	s_waitcnt lgkmcnt(0)
	s_waitcnt lgkmcnt(0)
	v_mfma_f32_16x16x32_bf16 v[126:129], v[130:133], v[146:149], v[126:129]
	v_mfma_f32_16x16x32_bf16 v[122:125], v[138:141], v[146:149], v[122:125]
	v_mfma_f32_16x16x32_bf16 v[118:121], v[130:133], v[166:169], v[118:121]
	v_mfma_f32_16x16x32_bf16 v[114:117], v[138:141], v[166:169], v[114:117]
	v_mfma_f32_16x16x32_bf16 v[110:113], v[130:133], v[174:177], v[110:113]
	v_mfma_f32_16x16x32_bf16 v[106:109], v[138:141], v[174:177], v[106:109]
	v_mfma_f32_16x16x32_bf16 v[102:105], v[130:133], v[182:185], v[102:105]
	v_mfma_f32_16x16x32_bf16 v[98:101], v[138:141], v[182:185], v[98:101]
	v_mfma_f32_16x16x32_bf16 v[126:129], v[134:137], v[150:153], v[126:129]
	v_mfma_f32_16x16x32_bf16 v[122:125], v[142:145], v[150:153], v[122:125]
	v_mfma_f32_16x16x32_bf16 v[118:121], v[134:137], v[170:173], v[118:121]
	v_mfma_f32_16x16x32_bf16 v[114:117], v[142:145], v[170:173], v[114:117]
	v_mfma_f32_16x16x32_bf16 v[110:113], v[134:137], v[178:181], v[110:113]
	v_mfma_f32_16x16x32_bf16 v[106:109], v[142:145], v[178:181], v[106:109]
	v_mfma_f32_16x16x32_bf16 v[102:105], v[134:137], v[186:189], v[102:105]
	v_mfma_f32_16x16x32_bf16 v[98:101], v[142:145], v[186:189], v[98:101]
	s_barrier
	s_add_i32 s13, 0, 0x1c000
	s_add_i32 s12, s12, s35
	v_add_u32_e32 v234, s13, v227
	v_lshl_add_u64 v[242:243], v[242:243], 0, s[20:21]
	s_mov_b32 m0, s12
	ds_read_b128 v[190:193], v234
	ds_read_b128 v[194:197], v234 offset:1024
	ds_read_b128 v[198:201], v234 offset:2048
	ds_read_b128 v[234:237], v234 offset:3072
	global_load_lds_dwordx4 v[242:243], off
	v_lshl_add_u64 v[242:243], v[244:245], 0, s[20:21]
	s_add_i32 m0, s12, 0x2000
	s_nop 0
	global_load_lds_dwordx4 v[242:243], off
	s_barrier
	s_waitcnt lgkmcnt(0)
	s_waitcnt lgkmcnt(0)
	v_mfma_f32_16x16x32_bf16 v[62:65], v[190:193], v[146:149], v[62:65]
	v_mfma_f32_16x16x32_bf16 v[58:61], v[198:201], v[146:149], v[58:61]
	v_mfma_f32_16x16x32_bf16 v[54:57], v[190:193], v[166:169], v[54:57]
	v_mfma_f32_16x16x32_bf16 v[50:53], v[198:201], v[166:169], v[50:53]
	v_mfma_f32_16x16x32_bf16 v[46:49], v[190:193], v[174:177], v[46:49]
	v_mfma_f32_16x16x32_bf16 v[42:45], v[198:201], v[174:177], v[42:45]
	v_mfma_f32_16x16x32_bf16 v[38:41], v[190:193], v[182:185], v[38:41]
	v_mfma_f32_16x16x32_bf16 v[34:37], v[198:201], v[182:185], v[34:37]
	v_mfma_f32_16x16x32_bf16 v[62:65], v[194:197], v[150:153], v[62:65]
	v_mfma_f32_16x16x32_bf16 v[58:61], v[234:237], v[150:153], v[58:61]
	v_mfma_f32_16x16x32_bf16 v[54:57], v[194:197], v[170:173], v[54:57]
	v_mfma_f32_16x16x32_bf16 v[50:53], v[234:237], v[170:173], v[50:53]
	v_mfma_f32_16x16x32_bf16 v[46:49], v[194:197], v[178:181], v[46:49]
	v_mfma_f32_16x16x32_bf16 v[42:45], v[234:237], v[178:181], v[42:45]
	v_mfma_f32_16x16x32_bf16 v[38:41], v[194:197], v[186:189], v[38:41]
	v_mfma_f32_16x16x32_bf16 v[34:37], v[234:237], v[186:189], v[34:37]
	s_mov_b32 m0, s96
	s_add_u32 s78, s16, 0xfffc0080
	s_addc_u32 s79, s17, -1
	s_barrier
	ds_read_b128 v[146:149], v233 offset:49152
	ds_read_b128 v[150:153], v233 offset:50176
	ds_read_b128 v[166:169], v233 offset:51200
	ds_read_b128 v[170:173], v233 offset:52224
	ds_read_b128 v[174:177], v233 offset:53248
	ds_read_b128 v[178:181], v233 offset:54272
	ds_read_b128 v[182:185], v233 offset:55296
	ds_read_b128 v[186:189], v233 offset:56320
	global_load_lds_dwordx4 v250, s[78:79]
	s_nop 0
	s_mov_b32 m0, s97
	s_nop 0
	global_load_lds_dwordx4 v251, s[78:79]
	s_barrier
	s_waitcnt lgkmcnt(0)
	s_waitcnt lgkmcnt(0)
	v_mfma_f32_16x16x32_bf16 v[94:97], v[130:133], v[146:149], v[94:97]
	v_mfma_f32_16x16x32_bf16 v[90:93], v[138:141], v[146:149], v[90:93]
	v_mfma_f32_16x16x32_bf16 v[86:89], v[130:133], v[166:169], v[86:89]
	v_mfma_f32_16x16x32_bf16 v[82:85], v[138:141], v[166:169], v[82:85]
	v_mfma_f32_16x16x32_bf16 v[78:81], v[130:133], v[174:177], v[78:81]
	v_mfma_f32_16x16x32_bf16 v[74:77], v[138:141], v[174:177], v[74:77]
	v_mfma_f32_16x16x32_bf16 v[70:73], v[130:133], v[182:185], v[70:73]
	v_mfma_f32_16x16x32_bf16 v[66:69], v[138:141], v[182:185], v[66:69]
	v_mfma_f32_16x16x32_bf16 v[94:97], v[134:137], v[150:153], v[94:97]
	v_mfma_f32_16x16x32_bf16 v[90:93], v[142:145], v[150:153], v[90:93]
	v_mfma_f32_16x16x32_bf16 v[86:89], v[134:137], v[170:173], v[86:89]
	v_mfma_f32_16x16x32_bf16 v[82:85], v[142:145], v[170:173], v[82:85]
	v_mfma_f32_16x16x32_bf16 v[78:81], v[134:137], v[178:181], v[78:81]
	v_mfma_f32_16x16x32_bf16 v[74:77], v[142:145], v[178:181], v[74:77]
	v_mfma_f32_16x16x32_bf16 v[70:73], v[134:137], v[186:189], v[70:73]
	v_mfma_f32_16x16x32_bf16 v[66:69], v[142:145], v[186:189], v[66:69]
	s_barrier
	s_add_u32 s2, s2, 0x40080
	s_addc_u32 s3, s3, 0
	s_add_i32 s12, s13, s35
	v_lshl_add_u64 v[130:131], s[2:3], 0, v[0:1]
	s_mov_b32 m0, s12
	s_nop 0
	global_load_lds_dwordx4 v[130:131], off
	v_lshl_add_u64 v[130:131], s[2:3], 0, v[154:155]
	s_add_i32 m0, s12, 0x2000
	s_nop 0
	global_load_lds_dwordx4 v[130:131], off
	s_waitcnt vmcnt(6)
	s_barrier
	v_mfma_f32_16x16x32_bf16 v[30:33], v[190:193], v[146:149], v[30:33]
	v_mfma_f32_16x16x32_bf16 v[26:29], v[198:201], v[146:149], v[26:29]
	v_mfma_f32_16x16x32_bf16 v[22:25], v[190:193], v[166:169], v[22:25]
	v_mfma_f32_16x16x32_bf16 v[18:21], v[198:201], v[166:169], v[18:21]
	v_mfma_f32_16x16x32_bf16 v[14:17], v[190:193], v[174:177], v[14:17]
	v_mfma_f32_16x16x32_bf16 v[10:13], v[198:201], v[174:177], v[10:13]
	v_mfma_f32_16x16x32_bf16 v[6:9], v[190:193], v[182:185], v[6:9]
	v_mfma_f32_16x16x32_bf16 v[2:5], v[198:201], v[182:185], v[2:5]
	v_mfma_f32_16x16x32_bf16 v[30:33], v[194:197], v[150:153], v[30:33]
	v_mfma_f32_16x16x32_bf16 v[26:29], v[234:237], v[150:153], v[26:29]
	v_mfma_f32_16x16x32_bf16 v[22:25], v[194:197], v[170:173], v[22:25]
	v_mfma_f32_16x16x32_bf16 v[18:21], v[234:237], v[170:173], v[18:21]
	v_mfma_f32_16x16x32_bf16 v[14:17], v[194:197], v[178:181], v[14:17]
	v_mfma_f32_16x16x32_bf16 v[10:13], v[234:237], v[178:181], v[10:13]
	v_mfma_f32_16x16x32_bf16 v[6:9], v[194:197], v[186:189], v[6:9]
	v_mfma_f32_16x16x32_bf16 v[2:5], v[234:237], v[186:189], v[2:5]
	s_add_i32 s47, s47, 2
	s_add_u32 s0, s0, 0x100
	s_addc_u32 s1, s1, 0
	s_add_u32 s45, s45, 0x100
	s_addc_u32 s46, s46, 0
	s_cmp_gt_u32 s47, 13
	s_barrier
	s_cbranch_scc0 .LBB0_366
	s_lshl_b32 s2, s42, 8
	s_add_i32 s2, s2, s92
	s_lshl_b32 s3, s14, 8
	s_or_b32 s3, s3, s93
	v_readlane_b32 s44, v255, 8
	v_readlane_b32 s45, v255, 9
	s_add_u32 s60, s8, 0xc404000
	s_addc_u32 s61, s9, 0
	v_lshl_add_u32 v166, v226, 2, s2
	s_cmp_lt_i32 s42, 64
	s_cselect_b32 s47, 1, 0
	v_mul_lo_u32 v167, v166, s57
	s_nop 0
	v_lshl_add_u32 v167, v228, 1, v167
	s_cmpk_gt_i32 s3, 0xb7f
	s_cbranch_scc1 .Lip0_end
	s_lshl_b32 s12, s3, 1
	v_add_u32_e32 v169, s12, v167
	s_add_i32 s0, s3, 0xfffffc00
	s_add_i32 s1, s3, 0xfffff780
	s_min_u32 s12, s0, s1
	s_cmpk_lt_u32 s12, 0x180
	s_cbranch_scc1 .Lip0_V
	s_add_i32 s12, s3, 0xfffffa80
	s_cmpk_lt_u32 s12, 0x300
	s_cbranch_scc1 .Lip0_R
	s_add_i32 s12, s3, 0xffffff00
	s_cmpk_lt_u32 s12, 0x180
	s_cbranch_scc0 .Lip0_nonq
	v_mul_f32_e32 v126, 0x3e38aa3b, v126
	v_mul_f32_e32 v127, 0x3e38aa3b, v127
	v_mul_f32_e32 v128, 0x3e38aa3b, v128
	v_mul_f32_e32 v129, 0x3e38aa3b, v129
	v_mul_f32_e32 v122, 0x3e38aa3b, v122
	v_mul_f32_e32 v123, 0x3e38aa3b, v123
	v_mul_f32_e32 v124, 0x3e38aa3b, v124
	v_mul_f32_e32 v125, 0x3e38aa3b, v125
	v_mul_f32_e32 v118, 0x3e38aa3b, v118
	v_mul_f32_e32 v119, 0x3e38aa3b, v119
	v_mul_f32_e32 v120, 0x3e38aa3b, v120
	v_mul_f32_e32 v121, 0x3e38aa3b, v121
	v_mul_f32_e32 v114, 0x3e38aa3b, v114
	v_mul_f32_e32 v115, 0x3e38aa3b, v115
	v_mul_f32_e32 v116, 0x3e38aa3b, v116
	v_mul_f32_e32 v117, 0x3e38aa3b, v117
	v_mul_f32_e32 v110, 0x3e38aa3b, v110
	v_mul_f32_e32 v111, 0x3e38aa3b, v111
	v_mul_f32_e32 v112, 0x3e38aa3b, v112
	v_mul_f32_e32 v113, 0x3e38aa3b, v113
	v_mul_f32_e32 v106, 0x3e38aa3b, v106
	v_mul_f32_e32 v107, 0x3e38aa3b, v107
	v_mul_f32_e32 v108, 0x3e38aa3b, v108
	v_mul_f32_e32 v109, 0x3e38aa3b, v109
	v_mul_f32_e32 v102, 0x3e38aa3b, v102
	v_mul_f32_e32 v103, 0x3e38aa3b, v103
	v_mul_f32_e32 v104, 0x3e38aa3b, v104
	v_mul_f32_e32 v105, 0x3e38aa3b, v105
	v_mul_f32_e32 v98, 0x3e38aa3b, v98
	v_mul_f32_e32 v99, 0x3e38aa3b, v99
	v_mul_f32_e32 v100, 0x3e38aa3b, v100
	v_mul_f32_e32 v101, 0x3e38aa3b, v101
	v_mul_f32_e32 v94, 0x3e38aa3b, v94
	v_mul_f32_e32 v95, 0x3e38aa3b, v95
	v_mul_f32_e32 v96, 0x3e38aa3b, v96
	v_mul_f32_e32 v97, 0x3e38aa3b, v97
	v_mul_f32_e32 v90, 0x3e38aa3b, v90
	v_mul_f32_e32 v91, 0x3e38aa3b, v91
	v_mul_f32_e32 v92, 0x3e38aa3b, v92
	v_mul_f32_e32 v93, 0x3e38aa3b, v93
	v_mul_f32_e32 v86, 0x3e38aa3b, v86
	v_mul_f32_e32 v87, 0x3e38aa3b, v87
	v_mul_f32_e32 v88, 0x3e38aa3b, v88
	v_mul_f32_e32 v89, 0x3e38aa3b, v89
	v_mul_f32_e32 v82, 0x3e38aa3b, v82
	v_mul_f32_e32 v83, 0x3e38aa3b, v83
	v_mul_f32_e32 v84, 0x3e38aa3b, v84
	v_mul_f32_e32 v85, 0x3e38aa3b, v85
	v_mul_f32_e32 v78, 0x3e38aa3b, v78
	v_mul_f32_e32 v79, 0x3e38aa3b, v79
	v_mul_f32_e32 v80, 0x3e38aa3b, v80
	v_mul_f32_e32 v81, 0x3e38aa3b, v81
	v_mul_f32_e32 v74, 0x3e38aa3b, v74
	v_mul_f32_e32 v75, 0x3e38aa3b, v75
	v_mul_f32_e32 v76, 0x3e38aa3b, v76
	v_mul_f32_e32 v77, 0x3e38aa3b, v77
	v_mul_f32_e32 v70, 0x3e38aa3b, v70
	v_mul_f32_e32 v71, 0x3e38aa3b, v71
	v_mul_f32_e32 v72, 0x3e38aa3b, v72
	v_mul_f32_e32 v73, 0x3e38aa3b, v73
	v_mul_f32_e32 v66, 0x3e38aa3b, v66
	v_mul_f32_e32 v67, 0x3e38aa3b, v67
	v_mul_f32_e32 v68, 0x3e38aa3b, v68
	v_mul_f32_e32 v69, 0x3e38aa3b, v69

.LBB0_479:
	s_setprio 0
	s_waitcnt vmcnt(0)
	v_readlane_b32 s84, v254, 59
	v_readlane_b32 s50, v255, 17
	s_cmpk_gt_u32 s22, 0xff
	v_readlane_b32 s85, v254, 60
	v_readlane_b32 s86, v254, 61
	v_readlane_b32 s87, v254, 62
	v_readlane_b32 s88, v254, 63
	v_readlane_b32 s89, v255, 0
	v_readlane_b32 s90, v255, 1
	v_readlane_b32 s91, v255, 2
	s_mov_b32 s77, 0x5c000
	v_readlane_b32 s51, v255, 18
	v_readlane_b32 s97, v255, 14
	s_cbranch_scc1 .LBB0_481
	s_barrier
